# norm phases: next chunk's small vector loads issued before the previous chunk's bf16 store (store operands copied), vmcnt recounted
# speedup vs baseline: 1.0092x; 1.0020x over previous
; __device__ __forceinline__ u16 f2bf(float x) { unsigned u = __float_as_uint(x); u += 0x7fffu + ((u >> 16) & 1u); return (u16)(u >> 16); }
; __device__ __forceinline__ size_t a_off(int row, int col, int nks) { return ((size_t)((row >> 8) * nks + (col >> 5)) << 13) + ((row & 255) << 5) + swzc(row, col & 31); }
; template <int MODE>
; __device__ __forceinline__ void norm_phase(const Params& p, const float* src, const float* w, const float* modl, int sh_off, int sc_off,
;                            char* smem, int bid, int nblk) {
;     ...
;   auto process = [&](int row, f32x4 (&v)[4]) {
;     float ss = 0.f;
; #pragma unroll
;     for (int i = 0; i < 4; ++i) ss += v[i][0] * v[i][0] + v[i][1] * v[i][1] + v[i][2] * v[i][2] + v[i][3] * v[i][3];
; #pragma unroll
;     for (int o = 32; o >= 1; o >>= 1) ss += __shfl_xor(ss, o);
;     const float rstd = rsqrtf(ss * (1.f / 1024.f) + 1e-6f);
;     const int b = row >> 13;
;     float dots[8];
;     if (MODE == 1) { for (int j = 0; j < 8; ++j) dots[j] = 0.f; }
; #pragma unroll
;     for (int i = 0; i < 4; ++i) {
;       const int c0 = i * 256 + lane * 4;
;       f32x4 ww = *(const f32x4*)(w + c0);
;       f32x4 y;
;       if (MODE == 2) {
; #pragma unroll
;         for (int e = 0; e < 4; ++e) y[e] = v[i][e] * rstd * ww[e];
;         *(f32x4*)(p.out + (size_t)row * 1024 + c0) = y;
;       } else {
;         f32x4 sc = *(const f32x4*)(modl + (size_t)b * 6144 + sc_off + c0);
;         f32x4 sh = *(const f32x4*)(modl + (size_t)b * 6144 + sh_off + c0);
; #pragma unroll
;         for (int e = 0; e < 4; ++e) y[e] = v[i][e] * rstd * ww[e] * (1.f + sc[e]) + sh[e];
;         uint2 pk; pk.x = (unsigned)f2bf(y[0]) | ((unsigned)f2bf(y[1]) << 16); pk.y = (unsigned)f2bf(y[2]) | ((unsigned)f2bf(y[3]) << 16);
;         *(uint2*)(hn + a_off(row, c0, 32)) = pk;
;         if (MODE == 1) {
; #pragma unroll
;           for (int e = 0; e < 4; ++e) {
;             f32x4 w0 = *(const f32x4*)(wba + (c0 + e) * 8), w1 = *(const f32x4*)(wba + (c0 + e) * 8 + 4);
; #pragma unroll
;             for (int j = 0; j < 4; ++j) { dots[j] += y[e] * w0[j]; dots[4 + j] += y[e] * w1[j]; }
;           }
;         }
.LBB0_107:
	s_or_b64 exec, exec, s[0:1]
	v_ashrrev_i32_e32 v160, 13, v156
	v_mul_i32_i24_e32 v182, 0x1800, v160
	v_readlane_b32 s0, v244, 23
	v_ashrrev_i32_e32 v183, 31, v182
	v_readlane_b32 s1, v244, 24
	v_lshlrev_b32_e32 v160, 2, v158
	global_load_dwordx4 v[210:213], v[164:165], off
	v_lshl_add_u64 v[182:183], v[182:183], 2, s[0:1]
	v_lshl_add_u64 v[184:185], v[182:183], 0, s[30:31]
	v_lshl_add_u64 v[214:215], v[184:185], 0, v[160:161]
	global_load_dwordx4 v[214:217], v[214:215], off
	v_lshl_add_u64 v[182:183], v[182:183], 0, v[160:161]
	global_load_dwordx4 v[218:221], v[182:183], off
	s_waitcnt vmcnt(6)
	v_pk_mul_f32 v[222:223], v[152:153], v[152:153]
	s_waitcnt vmcnt(5)
	v_pk_mul_f32 v[224:225], v[148:149], v[148:149]
	v_pk_mul_f32 v[186:187], v[154:155], v[154:155]
	v_pk_mul_f32 v[188:189], v[150:151], v[150:151]
	v_mov_b32_e32 v226, v222
	v_mov_b32_e32 v227, v224
	v_mov_b32_e32 v224, v223
	v_pk_add_f32 v[222:223], v[226:227], v[224:225]
	v_mov_b32_e32 v224, v186
	v_mov_b32_e32 v225, v188
	v_pk_add_f32 v[222:223], v[224:225], v[222:223]
	v_mov_b32_e32 v188, v187
	v_pk_add_f32 v[186:187], v[188:189], v[222:223]
	s_waitcnt vmcnt(3)
	v_mov_b32_e32 v222, v141
	v_mov_b32_e32 v223, v145
	v_mov_b32_e32 v188, v140
	v_mov_b32_e32 v189, v144
	v_pk_mul_f32 v[222:223], v[222:223], v[222:223]
	v_add_f32_e32 v171, v186, v187
	v_pk_fma_f32 v[188:189], v[188:189], v[188:189], v[222:223]
	v_mov_b32_e32 v222, v142
	v_mov_b32_e32 v223, v146
	v_pk_fma_f32 v[188:189], v[222:223], v[222:223], v[188:189]
	v_mov_b32_e32 v222, v143
	v_mov_b32_e32 v223, v147
	v_pk_fma_f32 v[188:189], v[222:223], v[222:223], v[188:189]
	v_mov_b32_e32 v223, v154
	v_add_f32_e32 v171, v189, v171
	v_add_f32_e32 v171, v188, v171
	ds_bpermute_b32 v173, v159, v171
	v_mov_b32_e32 v154, v153
	v_ashrrev_i32_e32 v175, 3, v156
	v_and_b32_e32 v209, 0xffffffe0, v175
	v_and_b32_e32 v188, 24, v202
	s_waitcnt lgkmcnt(0)
	v_add_f32_e32 v171, v171, v173
	ds_bpermute_b32 v173, v191, v171
	v_mov_b32_e32 v222, v152
	v_or_b32_e32 v152, v209, v196
	v_and_b32_e32 v186, 0x1fe0, v203
	v_mov_b32_e32 v187, v161
	s_waitcnt lgkmcnt(0)
	v_add_f32_e32 v171, v171, v173
	ds_bpermute_b32 v173, v192, v171
	v_lshlrev_b32_e32 v186, 1, v186
	v_mov_b32_e32 v189, v161
	s_waitcnt lgkmcnt(0)
	v_add_f32_e32 v171, v171, v173
	ds_bpermute_b32 v173, v193, v171
	s_waitcnt lgkmcnt(0)
	v_add_f32_e32 v153, v171, v173
	ds_bpermute_b32 v171, v194, v153
	v_sub_u32_e32 v173, 0, v188
	v_xor_b32_e32 v173, v158, v173
	v_and_or_b32 v173, v173, 24, v197
	v_lshlrev_b32_e32 v188, 1, v173
	s_waitcnt lgkmcnt(0)
	v_add_f32_e32 v171, v153, v171
	ds_bpermute_b32 v175, v195, v171
	v_ashrrev_i32_e32 v153, 31, v152
	v_lshlrev_b64 v[152:153], 14, v[152:153]
	v_lshl_add_u64 v[152:153], s[62:63], 0, v[152:153]
	v_lshl_add_u64 v[152:153], v[152:153], 0, v[186:187]
	s_waitcnt lgkmcnt(0)
	v_add_f32_e32 v171, v171, v175
	v_fmamk_f32 v171, v171, 0x3a800000, v157
	v_mul_f32_e32 v173, 0x4b800000, v171
	v_cmp_gt_f32_e64 s[0:1], s67, v171
	v_lshl_add_u64 v[224:225], v[152:153], 0, v[188:189]
	s_waitcnt vmcnt(0)
	v_mov_b32_e32 v227, v220
	v_cndmask_b32_e64 v171, v171, v173, s[0:1]
	v_rsq_f32_e32 v171, v171
	v_mov_b32_e32 v220, v219
	v_mov_b32_e32 v226, v218
	v_mul_f32_e32 v152, 0x45800000, v171
	v_cndmask_b32_e64 v190, v171, v152, s[0:1]
	v_pk_mul_f32 v[152:153], v[222:223], v[190:191] op_sel_hi:[1,0]
	v_mov_b32_e32 v222, v210
	v_mov_b32_e32 v223, v212
	v_pk_mul_f32 v[154:155], v[154:155], v[190:191] op_sel_hi:[1,0]
	v_pk_mul_f32 v[152:153], v[222:223], v[152:153]
	v_mov_b32_e32 v223, v216
	v_mov_b32_e32 v212, v211
	v_mov_b32_e32 v216, v215
	v_mov_b32_e32 v222, v214
	v_pk_mul_f32 v[154:155], v[212:213], v[154:155]
	v_pk_add_f32 v[210:211], v[216:217], 1.0 op_sel_hi:[1,0]
	v_pk_add_f32 v[222:223], v[222:223], 1.0 op_sel_hi:[1,0]
	v_pk_fma_f32 v[154:155], v[210:211], v[154:155], v[220:221]
	v_pk_fma_f32 v[152:153], v[222:223], v[152:153], v[226:227]
	v_and_b32_sdwa v175, v155, v205 dst_sel:DWORD dst_unused:UNUSED_PAD src0_sel:WORD_1 src1_sel:DWORD
	v_and_b32_sdwa v210, v154, v205 dst_sel:DWORD dst_unused:UNUSED_PAD src0_sel:WORD_1 src1_sel:DWORD
	v_and_b32_sdwa v171, v153, v205 dst_sel:DWORD dst_unused:UNUSED_PAD src0_sel:WORD_1 src1_sel:DWORD
	v_and_b32_sdwa v173, v152, v205 dst_sel:DWORD dst_unused:UNUSED_PAD src0_sel:WORD_1 src1_sel:DWORD
	v_add3_u32 v175, v155, v175, s80
	v_add3_u32 v210, v154, v210, s80
	v_add3_u32 v173, v152, v173, s80
	v_add3_u32 v171, v153, v171, s80
	v_and_b32_e32 v175, 0xffff0000, v175
	v_and_b32_e32 v210, 0xffff0000, v210
	v_or_b32_sdwa v211, v175, v171 dst_sel:DWORD dst_unused:UNUSED_PAD src0_sel:DWORD src1_sel:WORD_1
	v_or_b32_sdwa v210, v210, v173 dst_sel:DWORD dst_unused:UNUSED_PAD src0_sel:DWORD src1_sel:WORD_1
	v_mov_b32_e32 v250, v224
	v_mov_b32_e32 v251, v225
	v_mov_b32_e32 v252, v210
	v_mov_b32_e32 v253, v211
	v_mov_b32_e32 v171, v161
	global_load_dwordx4 v[210:213], v[164:165], off offset:1024
	v_lshl_add_u64 v[214:215], v[184:185], 0, v[170:171]
	global_load_dwordx4 v[214:217], v[214:215], off
	s_nop 0
	global_load_dwordx4 v[218:221], v[182:183], off offset:1024
	global_store_dwordx2 v[250:251], v[252:253], off
	v_mov_b32_e32 v222, v148
	v_or_b32_e32 v148, v209, v199
	v_mov_b32_e32 v223, v150
	v_mov_b32_e32 v150, v149
	v_ashrrev_i32_e32 v149, 31, v148
	v_lshlrev_b64 v[148:149], 14, v[148:149]
	v_lshl_add_u64 v[148:149], s[62:63], 0, v[148:149]
	v_lshl_add_u64 v[148:149], v[148:149], 0, v[186:187]
	v_lshl_add_u64 v[224:225], v[148:149], 0, v[188:189]
	v_pk_mul_f32 v[148:149], v[222:223], v[190:191] op_sel_hi:[1,0]
	v_pk_mul_f32 v[150:151], v[150:151], v[190:191] op_sel_hi:[1,0]
	v_mov_b32_e32 v173, v161
	v_fma_f32 v230, v7, v152, 0
	v_fmac_f32_e32 v230, v15, v154
	v_fmac_f32_e32 v230, v23, v153
	v_fmac_f32_e32 v230, v155, v31
	s_waitcnt vmcnt(3)
; __device__ __forceinline__ u16 f2bf(float x) { unsigned u = __float_as_uint(x); u += 0x7fffu + ((u >> 16) & 1u); return (u16)(u >> 16); }
; __device__ __forceinline__ size_t a_off(int row, int col, int nks) { return ((size_t)((row >> 8) * nks + (col >> 5)) << 13) + ((row & 255) << 5) + swzc(row, col & 31); }
; template <int MODE>
; __device__ __forceinline__ void norm_phase(const Params& p, const float* src, const float* w, const float* modl, int sh_off, int sc_off,
;                            char* smem, int bid, int nblk) {
;     ...
; #pragma unroll
;     for (int i = 0; i < 4; ++i) {
;       const int c0 = i * 256 + lane * 4;
;       f32x4 ww = *(const f32x4*)(w + c0);
;       f32x4 y;
;       if (MODE == 2) {
; #pragma unroll
;         for (int e = 0; e < 4; ++e) y[e] = v[i][e] * rstd * ww[e];
;         *(f32x4*)(p.out + (size_t)row * 1024 + c0) = y;
;       } else {
;         f32x4 sc = *(const f32x4*)(modl + (size_t)b * 6144 + sc_off + c0);
;         f32x4 sh = *(const f32x4*)(modl + (size_t)b * 6144 + sh_off + c0);
; #pragma unroll
;         for (int e = 0; e < 4; ++e) y[e] = v[i][e] * rstd * ww[e] * (1.f + sc[e]) + sh[e];
;         uint2 pk; pk.x = (unsigned)f2bf(y[0]) | ((unsigned)f2bf(y[1]) << 16); pk.y = (unsigned)f2bf(y[2]) | ((unsigned)f2bf(y[3]) << 16);
;         *(uint2*)(hn + a_off(row, c0, 32)) = pk;
;         if (MODE == 1) {
; #pragma unroll
;           for (int e = 0; e < 4; ++e) {
;             f32x4 w0 = *(const f32x4*)(wba + (c0 + e) * 8), w1 = *(const f32x4*)(wba + (c0 + e) * 8 + 4);
; #pragma unroll
;             for (int j = 0; j < 4; ++j) { dots[j] += y[e] * w0[j]; dots[4 + j] += y[e] * w1[j]; }
;           }
;         }
	v_mov_b32_e32 v222, v210
	v_mov_b32_e32 v223, v212
	s_waitcnt vmcnt(2)
	v_mov_b32_e32 v226, v214
	v_mov_b32_e32 v227, v216
	v_mov_b32_e32 v212, v211
	v_mov_b32_e32 v216, v215
	s_waitcnt vmcnt(1)
	v_mov_b32_e32 v228, v218
	v_mov_b32_e32 v229, v220
	v_mov_b32_e32 v220, v219
	v_pk_mul_f32 v[148:149], v[148:149], v[222:223]
	v_pk_add_f32 v[210:211], v[226:227], 1.0 op_sel_hi:[1,0]
	v_pk_mul_f32 v[212:213], v[150:151], v[212:213]
	v_pk_add_f32 v[214:215], v[216:217], 1.0 op_sel_hi:[1,0]
	v_pk_fma_f32 v[150:151], v[148:149], v[210:211], v[228:229]
	v_pk_fma_f32 v[148:149], v[212:213], v[214:215], v[220:221]
	v_and_b32_sdwa v171, v151, v205 dst_sel:DWORD dst_unused:UNUSED_PAD src0_sel:WORD_1 src1_sel:DWORD
	v_and_b32_sdwa v210, v149, v205 dst_sel:DWORD dst_unused:UNUSED_PAD src0_sel:WORD_1 src1_sel:DWORD
	v_and_b32_sdwa v211, v148, v205 dst_sel:DWORD dst_unused:UNUSED_PAD src0_sel:WORD_1 src1_sel:DWORD
	v_and_b32_sdwa v175, v150, v205 dst_sel:DWORD dst_unused:UNUSED_PAD src0_sel:WORD_1 src1_sel:DWORD
	v_add3_u32 v210, v149, v210, s80
	v_add3_u32 v211, v148, v211, s80
	v_add3_u32 v175, v150, v175, s80
	v_add3_u32 v171, v151, v171, s80
	v_and_b32_e32 v210, 0xffff0000, v210
	v_and_b32_e32 v212, 0xffff0000, v211
	v_or_b32_sdwa v211, v210, v171 dst_sel:DWORD dst_unused:UNUSED_PAD src0_sel:DWORD src1_sel:WORD_1
	v_or_b32_sdwa v210, v212, v175 dst_sel:DWORD dst_unused:UNUSED_PAD src0_sel:DWORD src1_sel:WORD_1
	v_mov_b32_e32 v250, v224
	v_mov_b32_e32 v251, v225
	v_mov_b32_e32 v252, v210
	v_mov_b32_e32 v253, v211
	global_load_dwordx4 v[210:213], v[164:165], off offset:2048
	v_lshl_add_u64 v[214:215], v[184:185], 0, v[172:173]
	global_load_dwordx4 v[214:217], v[214:215], off
	s_nop 0
	global_load_dwordx4 v[218:221], v[182:183], off offset:2048
	global_store_dwordx2 v[250:251], v[252:253], off
	v_mov_b32_e32 v222, v144
	v_mov_b32_e32 v144, v140
	v_or_b32_e32 v140, v209, v200
	v_or_b32_e32 v224, v209, v201
	v_mov_b32_e32 v223, v146
	v_mov_b32_e32 v146, v145
	v_mov_b32_e32 v145, v142
	v_mov_b32_e32 v142, v141
	v_ashrrev_i32_e32 v141, 31, v140
	v_ashrrev_i32_e32 v225, 31, v224
	v_lshlrev_b64 v[140:141], 14, v[140:141]
	v_lshlrev_b64 v[224:225], 14, v[224:225]
	v_lshl_add_u64 v[140:141], s[62:63], 0, v[140:141]
	v_lshl_add_u64 v[224:225], s[62:63], 0, v[224:225]
	v_lshl_add_u64 v[140:141], v[140:141], 0, v[186:187]
	v_lshl_add_u64 v[186:187], v[224:225], 0, v[186:187]
	v_lshl_add_u64 v[224:225], v[140:141], 0, v[188:189]
	v_lshl_add_u64 v[140:141], v[186:187], 0, v[188:189]
	v_pk_mul_f32 v[186:187], v[222:223], v[190:191] op_sel_hi:[1,0]
	v_pk_mul_f32 v[146:147], v[146:147], v[190:191] op_sel_hi:[1,0]
	v_pk_mul_f32 v[188:189], v[144:145], v[190:191] op_sel_hi:[1,0]
	v_pk_mul_f32 v[222:223], v[142:143], v[190:191] op_sel_hi:[1,0]
	v_mov_b32_e32 v175, v161
	v_lshl_add_u64 v[184:185], v[184:185], 0, v[174:175]
	v_fma_f32 v171, v0, v152, 0
	v_fma_f32 v173, v4, v152, 0
	v_fma_f32 v175, v1, v152, 0
	v_fma_f32 v190, v5, v152, 0
	v_fma_f32 v209, v2, v152, 0
	v_fma_f32 v228, v6, v152, 0
	v_fma_f32 v229, v3, v152, 0
	v_fmac_f32_e32 v171, v8, v154
	v_fmac_f32_e32 v173, v12, v154
	v_fmac_f32_e32 v175, v9, v154
	v_fmac_f32_e32 v190, v13, v154
	v_fmac_f32_e32 v209, v10, v154
	v_fmac_f32_e32 v228, v14, v154
	v_fmac_f32_e32 v229, v11, v154
	v_fmac_f32_e32 v171, v16, v153
	v_fmac_f32_e32 v173, v20, v153
	v_fmac_f32_e32 v175, v17, v153
	v_fmac_f32_e32 v190, v21, v153
	v_fmac_f32_e32 v209, v18, v153
	v_fmac_f32_e32 v228, v22, v153
	v_fmac_f32_e32 v229, v19, v153
	v_fmac_f32_e32 v171, v155, v24
	v_fmac_f32_e32 v173, v155, v28
	v_fmac_f32_e32 v175, v155, v25
	v_fmac_f32_e32 v190, v155, v29
	v_fmac_f32_e32 v209, v155, v26
	v_fmac_f32_e32 v228, v155, v30
	v_fmac_f32_e32 v229, v155, v27
	v_fmac_f32_e32 v171, v150, v32
	v_fmac_f32_e32 v173, v150, v36
	v_fmac_f32_e32 v175, v150, v33
	v_fmac_f32_e32 v190, v150, v37
	v_fmac_f32_e32 v209, v150, v34
	v_fmac_f32_e32 v228, v150, v38
	v_fmac_f32_e32 v229, v150, v35
	v_fmac_f32_e32 v230, v150, v39
	v_fmac_f32_e32 v171, v148, v40
	v_fmac_f32_e32 v173, v148, v44
	v_fmac_f32_e32 v175, v148, v41
	v_fmac_f32_e32 v190, v148, v45
	v_fmac_f32_e32 v209, v148, v42
	v_fmac_f32_e32 v228, v148, v46
	v_fmac_f32_e32 v229, v148, v43
	v_fmac_f32_e32 v230, v148, v47
	v_fmac_f32_e32 v171, v151, v48
	v_fmac_f32_e32 v173, v151, v52
	v_fmac_f32_e32 v175, v151, v49
	v_fmac_f32_e32 v190, v151, v53
	v_fmac_f32_e32 v209, v151, v50
	v_fmac_f32_e32 v228, v151, v54
	v_fmac_f32_e32 v229, v151, v51
	v_fmac_f32_e32 v230, v151, v55
	v_fmac_f32_e32 v171, v149, v56
	s_waitcnt vmcnt(3)
	v_mov_b32_e32 v142, v210
	v_mov_b32_e32 v143, v212
	s_waitcnt vmcnt(2)
	v_mov_b32_e32 v144, v214
	v_mov_b32_e32 v145, v216
	v_mov_b32_e32 v212, v211
	v_mov_b32_e32 v216, v215
	s_waitcnt vmcnt(1)
; __device__ __forceinline__ u16 f2bf(float x) { unsigned u = __float_as_uint(x); u += 0x7fffu + ((u >> 16) & 1u); return (u16)(u >> 16); }
; __device__ __forceinline__ size_t a_off(int row, int col, int nks) { return ((size_t)((row >> 8) * nks + (col >> 5)) << 13) + ((row & 255) << 5) + swzc(row, col & 31); }
; template <int MODE>
; __device__ __forceinline__ void norm_phase(const Params& p, const float* src, const float* w, const float* modl, int sh_off, int sc_off,
;                            char* smem, int bid, int nblk) {
;     ...
; #pragma unroll
;     for (int i = 0; i < 4; ++i) {
;       const int c0 = i * 256 + lane * 4;
;       f32x4 ww = *(const f32x4*)(w + c0);
;       f32x4 y;
;       if (MODE == 2) {
; #pragma unroll
;         for (int e = 0; e < 4; ++e) y[e] = v[i][e] * rstd * ww[e];
;         *(f32x4*)(p.out + (size_t)row * 1024 + c0) = y;
;       } else {
;         f32x4 sc = *(const f32x4*)(modl + (size_t)b * 6144 + sc_off + c0);
;         f32x4 sh = *(const f32x4*)(modl + (size_t)b * 6144 + sh_off + c0);
; #pragma unroll
;         for (int e = 0; e < 4; ++e) y[e] = v[i][e] * rstd * ww[e] * (1.f + sc[e]) + sh[e];
;         uint2 pk; pk.x = (unsigned)f2bf(y[0]) | ((unsigned)f2bf(y[1]) << 16); pk.y = (unsigned)f2bf(y[2]) | ((unsigned)f2bf(y[3]) << 16);
;         *(uint2*)(hn + a_off(row, c0, 32)) = pk;
;         if (MODE == 1) {
; #pragma unroll
;           for (int e = 0; e < 4; ++e) {
;             f32x4 w0 = *(const f32x4*)(wba + (c0 + e) * 8), w1 = *(const f32x4*)(wba + (c0 + e) * 8 + 4);
; #pragma unroll
;             for (int j = 0; j < 4; ++j) { dots[j] += y[e] * w0[j]; dots[4 + j] += y[e] * w1[j]; }
;           }
;         }
;       }
;     }
;     if (MODE == 1) {
; #pragma unroll
;       for (int j = 0; j < 8; ++j) {
; #pragma unroll
;         for (int o = 32; o >= 1; o >>= 1) dots[j] += __shfl_xor(dots[j], o);
	v_mov_b32_e32 v226, v218
	v_mov_b32_e32 v227, v220
	v_mov_b32_e32 v220, v219
	v_pk_mul_f32 v[142:143], v[186:187], v[142:143]
	v_pk_add_f32 v[144:145], v[144:145], 1.0 op_sel_hi:[1,0]
	v_pk_mul_f32 v[146:147], v[146:147], v[212:213]
	v_pk_add_f32 v[186:187], v[216:217], 1.0 op_sel_hi:[1,0]
	v_pk_fma_f32 v[214:215], v[142:143], v[144:145], v[226:227]
	v_pk_fma_f32 v[146:147], v[146:147], v[186:187], v[220:221]
	v_and_b32_sdwa v143, v214, v205 dst_sel:DWORD dst_unused:UNUSED_PAD src0_sel:WORD_1 src1_sel:DWORD
	v_and_b32_sdwa v144, v147, v205 dst_sel:DWORD dst_unused:UNUSED_PAD src0_sel:WORD_1 src1_sel:DWORD
	v_and_b32_sdwa v145, v146, v205 dst_sel:DWORD dst_unused:UNUSED_PAD src0_sel:WORD_1 src1_sel:DWORD
	v_and_b32_sdwa v142, v215, v205 dst_sel:DWORD dst_unused:UNUSED_PAD src0_sel:WORD_1 src1_sel:DWORD
	v_add3_u32 v152, v214, v143, s80
	v_add3_u32 v143, v147, v144, s80
	v_add3_u32 v144, v146, v145, s80
	v_add3_u32 v142, v215, v142, s80
	v_and_b32_e32 v143, 0xffff0000, v143
	v_and_b32_e32 v144, 0xffff0000, v144
	v_or_b32_sdwa v143, v143, v142 dst_sel:DWORD dst_unused:UNUSED_PAD src0_sel:DWORD src1_sel:WORD_1
	v_or_b32_sdwa v142, v144, v152 dst_sel:DWORD dst_unused:UNUSED_PAD src0_sel:DWORD src1_sel:WORD_1
	v_mov_b32_e32 v250, v224
	v_mov_b32_e32 v251, v225
	v_mov_b32_e32 v252, v142
	v_mov_b32_e32 v253, v143
	global_load_dwordx4 v[142:145], v[164:165], off offset:3072
	v_fmac_f32_e32 v173, v149, v60
	global_load_dwordx4 v[184:187], v[184:185], off
	v_fmac_f32_e32 v175, v149, v57
	global_load_dwordx4 v[210:213], v[182:183], off offset:3072
	global_store_dwordx2 v[250:251], v[252:253], off
	v_fmac_f32_e32 v190, v149, v61
	v_fmac_f32_e32 v209, v149, v58
	v_fmac_f32_e32 v228, v149, v62
	v_fmac_f32_e32 v229, v149, v59
	v_fmac_f32_e32 v230, v149, v63
	v_fmac_f32_e32 v171, v214, v88
	v_fmac_f32_e32 v173, v214, v96
	v_fmac_f32_e32 v175, v214, v89
	v_fmac_f32_e32 v190, v214, v97
	v_fmac_f32_e32 v209, v214, v90
	v_fmac_f32_e32 v228, v214, v98
	v_fmac_f32_e32 v229, v214, v91
	v_fmac_f32_e32 v230, v214, v99
	v_fmac_f32_e32 v171, v146, v64
	v_fmac_f32_e32 v173, v146, v68
	v_fmac_f32_e32 v175, v146, v65
	v_fmac_f32_e32 v190, v146, v69
	v_fmac_f32_e32 v209, v146, v66
	v_fmac_f32_e32 v228, v146, v70
	v_fmac_f32_e32 v229, v146, v67
	v_fmac_f32_e32 v230, v146, v71
	v_fmac_f32_e32 v171, v215, v72
	v_fmac_f32_e32 v173, v215, v76
	v_fmac_f32_e32 v175, v215, v73
	v_fmac_f32_e32 v190, v215, v77
	v_fmac_f32_e32 v209, v215, v74
	v_fmac_f32_e32 v228, v215, v78
	v_fmac_f32_e32 v229, v215, v75
	v_fmac_f32_e32 v230, v215, v79
	v_fmac_f32_e32 v171, v147, v80
	v_fmac_f32_e32 v173, v147, v84
	v_fmac_f32_e32 v175, v147, v81
	v_fmac_f32_e32 v190, v147, v85
	v_fmac_f32_e32 v209, v147, v82
	v_fmac_f32_e32 v228, v147, v86
	v_fmac_f32_e32 v229, v147, v83
	v_fmac_f32_e32 v230, v147, v87
	s_waitcnt vmcnt(3)
	v_mov_b32_e32 v146, v142
	v_mov_b32_e32 v147, v144
	s_waitcnt vmcnt(2)
	v_mov_b32_e32 v148, v184
	v_mov_b32_e32 v149, v186
	s_waitcnt vmcnt(1)
	v_mov_b32_e32 v150, v210
	v_mov_b32_e32 v151, v212
	v_mov_b32_e32 v144, v143
	v_mov_b32_e32 v186, v185
	v_pk_mul_f32 v[142:143], v[188:189], v[146:147]
	v_pk_add_f32 v[146:147], v[148:149], 1.0 op_sel_hi:[1,0]
	v_mov_b32_e32 v212, v211
	v_pk_mul_f32 v[144:145], v[222:223], v[144:145]
	v_pk_add_f32 v[148:149], v[186:187], 1.0 op_sel_hi:[1,0]
	v_pk_fma_f32 v[142:143], v[142:143], v[146:147], v[150:151]
	v_pk_fma_f32 v[144:145], v[144:145], v[148:149], v[212:213]
	v_fmac_f32_e32 v171, v142, v92
	v_fmac_f32_e32 v171, v144, v104
	v_and_b32_sdwa v147, v142, v205 dst_sel:DWORD dst_unused:UNUSED_PAD src0_sel:WORD_1 src1_sel:DWORD
	v_and_b32_sdwa v148, v145, v205 dst_sel:DWORD dst_unused:UNUSED_PAD src0_sel:WORD_1 src1_sel:DWORD
	v_fmac_f32_e32 v171, v143, v112
	v_fmac_f32_e32 v173, v142, v100
	v_fmac_f32_e32 v175, v142, v93
	v_fmac_f32_e32 v190, v142, v101
	v_fmac_f32_e32 v209, v142, v94
	v_fmac_f32_e32 v228, v142, v102
	v_fmac_f32_e32 v229, v142, v95
	v_fmac_f32_e32 v230, v142, v103
	v_add3_u32 v182, v142, v147, s80
	v_add3_u32 v142, v145, v148, s80
	v_fmac_f32_e32 v171, v145, v120
	v_and_b32_e32 v185, 0xffff0000, v142
	ds_bpermute_b32 v142, v159, v171
	v_and_b32_sdwa v149, v144, v205 dst_sel:DWORD dst_unused:UNUSED_PAD src0_sel:WORD_1 src1_sel:DWORD
	v_add3_u32 v184, v144, v149, s80
	v_fmac_f32_e32 v173, v144, v108
	v_fmac_f32_e32 v175, v144, v105
	s_waitcnt lgkmcnt(0)
	v_add_f32_e32 v142, v171, v142
	v_fmac_f32_e32 v190, v144, v109
	v_fmac_f32_e32 v209, v144, v106
	v_fmac_f32_e32 v228, v144, v110
	v_fmac_f32_e32 v229, v144, v107
	v_fmac_f32_e32 v230, v144, v111
	ds_bpermute_b32 v144, v191, v142
	v_fmac_f32_e32 v175, v143, v113
	v_and_b32_sdwa v146, v143, v205 dst_sel:DWORD dst_unused:UNUSED_PAD src0_sel:WORD_1 src1_sel:DWORD
	v_fmac_f32_e32 v175, v145, v121
	v_add3_u32 v183, v143, v146, s80
	v_fmac_f32_e32 v173, v143, v116
	v_fmac_f32_e32 v190, v143, v117
	v_fmac_f32_e32 v209, v143, v114
	v_fmac_f32_e32 v228, v143, v118
	v_fmac_f32_e32 v229, v143, v115
	v_fmac_f32_e32 v230, v143, v119
	ds_bpermute_b32 v143, v159, v175
	s_waitcnt lgkmcnt(1)
	v_add_f32_e32 v142, v142, v144
	ds_bpermute_b32 v144, v192, v142
	v_fmac_f32_e32 v209, v145, v122
	ds_bpermute_b32 v147, v159, v209
	s_waitcnt lgkmcnt(2)
	v_add_f32_e32 v143, v175, v143
	ds_bpermute_b32 v146, v191, v143
	s_waitcnt lgkmcnt(2)
	v_add_f32_e32 v142, v142, v144
	ds_bpermute_b32 v144, v193, v142
	s_waitcnt lgkmcnt(2)
	v_add_f32_e32 v147, v209, v147
	ds_bpermute_b32 v148, v191, v147
	s_waitcnt lgkmcnt(2)
	v_add_f32_e32 v143, v143, v146
	ds_bpermute_b32 v146, v192, v143
	s_waitcnt lgkmcnt(2)
	v_add_f32_e32 v142, v142, v144
	ds_bpermute_b32 v144, v194, v142
	v_fmac_f32_e32 v173, v145, v124
	s_waitcnt lgkmcnt(2)
; __device__ __forceinline__ float sigmoid_(float x) { return __builtin_amdgcn_rcpf(1.f + __expf(-x)); }
; __device__ __forceinline__ float softplus_(float x) { return fmaxf(x, 0.f) + log1pf(__expf(-fabsf(x))); }
; template <int MODE>
; __device__ __forceinline__ void norm_phase(const Params& p, const float* src, const float* w, const float* modl, int sh_off, int sc_off,
;                            char* smem, int bid, int nblk) {
;     ...
;     if (MODE == 1) {
; #pragma unroll
;       for (int j = 0; j < 8; ++j) {
; #pragma unroll
;         for (int o = 32; o >= 1; o >>= 1) dots[j] += __shfl_xor(dots[j], o);
;       }
;       if (lane == 0) {
;         float* beta = (float*)(p.ws + OFF_BETA); float* gg = (float*)(p.ws + OFF_G);
; #pragma unroll
;         for (int h = 0; h < 4; ++h) {
;           beta[(size_t)row * 4 + h] = sigmoid_(dots[h]);
;           gg[(size_t)row * 4 + h] = -__expf(p.hy_a_log[h]) * softplus_(dots[4 + h] + p.hy_dt_bias[h]);
;         }
	v_add_f32_e32 v147, v147, v148
	s_waitcnt lgkmcnt(1)
	v_add_f32_e32 v143, v143, v146
	ds_bpermute_b32 v146, v193, v143
	s_waitcnt lgkmcnt(1)
	v_add_f32_e32 v154, v142, v144
	ds_bpermute_b32 v144, v159, v173
	ds_bpermute_b32 v142, v192, v147
	v_fmac_f32_e32 v229, v145, v123
	s_waitcnt lgkmcnt(2)
	v_add_f32_e32 v143, v143, v146
	v_fmac_f32_e32 v190, v145, v125
	s_waitcnt lgkmcnt(1)
	v_add_f32_e32 v144, v173, v144
	v_fmac_f32_e32 v228, v145, v126
	v_fmac_f32_e32 v230, v145, v127
	ds_bpermute_b32 v145, v159, v229
	ds_bpermute_b32 v146, v194, v143
	s_waitcnt lgkmcnt(2)
	v_add_f32_e32 v142, v147, v142
	ds_bpermute_b32 v147, v191, v144
	ds_bpermute_b32 v149, v193, v142
	s_waitcnt lgkmcnt(3)
	v_add_f32_e32 v145, v229, v145
	s_waitcnt lgkmcnt(2)
	v_add_f32_e32 v171, v143, v146
	ds_bpermute_b32 v148, v191, v145
	s_waitcnt lgkmcnt(2)
	v_add_f32_e32 v143, v144, v147
	ds_bpermute_b32 v144, v192, v143
	s_waitcnt lgkmcnt(2)
	v_add_f32_e32 v142, v142, v149
	ds_bpermute_b32 v147, v194, v142
	s_waitcnt lgkmcnt(2)
	v_add_f32_e32 v145, v145, v148
	ds_bpermute_b32 v148, v192, v145
	s_waitcnt lgkmcnt(2)
	v_add_f32_e32 v143, v143, v144
	ds_bpermute_b32 v144, v193, v143
	s_waitcnt lgkmcnt(2)
	v_add_f32_e32 v150, v142, v147
	ds_bpermute_b32 v155, v195, v154
	s_waitcnt lgkmcnt(2)
	v_add_f32_e32 v145, v145, v148
	ds_bpermute_b32 v146, v193, v145
	s_waitcnt lgkmcnt(2)
	v_add_f32_e32 v142, v143, v144
	ds_bpermute_b32 v143, v194, v142
	ds_bpermute_b32 v144, v159, v190
	ds_bpermute_b32 v173, v195, v171
	s_waitcnt lgkmcnt(3)
	v_add_f32_e32 v145, v145, v146
	ds_bpermute_b32 v146, v194, v145
	s_waitcnt lgkmcnt(3)
	v_add_f32_e32 v152, v142, v143
	ds_bpermute_b32 v142, v159, v228
	ds_bpermute_b32 v143, v159, v230
	s_waitcnt lgkmcnt(4)
	v_add_f32_e32 v144, v190, v144
	s_waitcnt lgkmcnt(2)
	v_add_f32_e32 v146, v145, v146
	ds_bpermute_b32 v145, v191, v144
	s_waitcnt lgkmcnt(2)
	v_add_f32_e32 v142, v228, v142
	s_waitcnt lgkmcnt(1)
	v_add_f32_e32 v143, v230, v143
	ds_bpermute_b32 v148, v191, v142
	ds_bpermute_b32 v149, v191, v143
	s_waitcnt lgkmcnt(2)
	v_add_f32_e32 v144, v144, v145
	ds_bpermute_b32 v145, v192, v144
	ds_bpermute_b32 v151, v195, v150
	s_waitcnt lgkmcnt(3)
	v_add_f32_e32 v142, v142, v148
	s_waitcnt lgkmcnt(2)
	v_add_f32_e32 v143, v143, v149
	ds_bpermute_b32 v148, v192, v142
	ds_bpermute_b32 v149, v192, v143
	s_waitcnt lgkmcnt(3)
	v_add_f32_e32 v144, v144, v145
	ds_bpermute_b32 v145, v193, v144
	ds_bpermute_b32 v147, v195, v146
	s_waitcnt lgkmcnt(3)
	v_add_f32_e32 v142, v142, v148
	s_waitcnt lgkmcnt(2)
	v_add_f32_e32 v143, v143, v149
	ds_bpermute_b32 v148, v193, v142
	ds_bpermute_b32 v149, v193, v143
	s_waitcnt lgkmcnt(3)
	v_add_f32_e32 v144, v144, v145
	ds_bpermute_b32 v145, v194, v144
	ds_bpermute_b32 v153, v195, v152
	s_waitcnt lgkmcnt(3)
	v_add_f32_e32 v142, v142, v148
	s_waitcnt lgkmcnt(2)
	v_add_f32_e32 v143, v143, v149
	ds_bpermute_b32 v175, v194, v142
	ds_bpermute_b32 v186, v194, v143
	s_waitcnt lgkmcnt(3)
	v_add_f32_e32 v148, v144, v145
	ds_bpermute_b32 v149, v195, v148
	v_or_b32_sdwa v183, v185, v183 dst_sel:DWORD dst_unused:UNUSED_PAD src0_sel:DWORD src1_sel:WORD_1
	s_waitcnt lgkmcnt(2)
	v_add_f32_e32 v144, v142, v175
	s_waitcnt lgkmcnt(1)
	v_add_f32_e32 v142, v143, v186
	ds_bpermute_b32 v145, v195, v144
	ds_bpermute_b32 v143, v195, v142
	v_and_b32_e32 v175, 0xffff0000, v184
	v_or_b32_sdwa v182, v175, v182 dst_sel:DWORD dst_unused:UNUSED_PAD src0_sel:DWORD src1_sel:WORD_1
	global_store_dwordx2 v[140:141], v[182:183], off
	s_and_saveexec_b64 s[0:1], vcc
	s_xor_b64 s[64:65], exec, s[0:1]
	s_cbranch_execz .LBB0_109
	v_add_f32_e32 v140, v154, v155
	v_mul_f32_e32 v140, 0xbfb8aa3b, v140
	v_exp_f32_e32 v140, v140
	v_add_f32_e32 v152, v152, v153
	v_add_f32_e32 v150, v150, v151
	v_mul_f32_e32 v150, 0xbfb8aa3b, v150
	v_add_f32_e32 v140, 1.0, v140
	v_rcp_f32_e32 v140, v140
	v_exp_f32_e32 v150, v150
	s_waitcnt lgkmcnt(2)
	v_add_f32_e32 v148, v148, v149
	v_add_f32_e32 v146, v146, v147
	global_store_dword v[166:167], v140, off
	global_load_dword v154, v161, s[58:59]
	global_load_dword v155, v161, s[56:57]
	v_add_f32_e32 v140, v171, v173
	v_mul_f32_e32 v140, 0xbfb8aa3b, v140
	v_exp_f32_e32 v140, v140
	v_add_f32_e32 v150, 1.0, v150
	v_rcp_f32_e32 v150, v150
	v_mul_f32_e32 v146, 0xbfb8aa3b, v146
	v_add_f32_e32 v140, 1.0, v140
	v_rcp_f32_e32 v153, v140
	v_add_co_u32_e64 v140, s[0:1], s86, v166
	v_exp_f32_e32 v146, v146
	global_store_dword v[166:167], v153, off offset:4
	v_addc_co_u32_e64 v141, s[0:1], 0, v167, s[0:1]
	v_add_f32_e32 v146, 1.0, v146
	v_rcp_f32_e32 v146, v146
	s_waitcnt lgkmcnt(1)
	v_add_f32_e32 v144, v144, v145
	s_waitcnt lgkmcnt(0)
	v_add_f32_e32 v142, v142, v143
	s_waitcnt vmcnt(2)
	v_add_f32_e32 v152, v152, v154
	v_mul_f32_e64 v153, |v152|, s81
	v_exp_f32_e32 v154, v153
	s_waitcnt vmcnt(1)
; __device__ __forceinline__ float sigmoid_(float x) { return __builtin_amdgcn_rcpf(1.f + __expf(-x)); }
; __device__ __forceinline__ float softplus_(float x) { return fmaxf(x, 0.f) + log1pf(__expf(-fabsf(x))); }
; template <int MODE>
; __device__ __forceinline__ void norm_phase(const Params& p, const float* src, const float* w, const float* modl, int sh_off, int sc_off,
;                            char* smem, int bid, int nblk) {
;     ...
;           beta[(size_t)row * 4 + h] = sigmoid_(dots[h]);
;           gg[(size_t)row * 4 + h] = -__expf(p.hy_a_log[h]) * softplus_(dots[4 + h] + p.hy_dt_bias[h]);
;         }
	v_mul_f32_e32 v153, 0x3fb8aa3b, v155
	v_exp_f32_e32 v155, v153
	v_max_f32_e32 v171, 0, v152
	v_add_f32_e32 v173, 1.0, v154
	v_add_f32_e32 v175, -1.0, v173
	v_frexp_mant_f32_e32 v182, v173
	v_cvt_f64_f32_e32 v[152:153], v173
	v_sub_f32_e32 v183, v175, v173
	v_frexp_exp_i32_f64_e32 v152, v[152:153]
	v_cmp_gt_f32_e64 s[0:1], s82, v182
	v_sub_f32_e32 v175, v154, v175
	v_add_f32_e32 v153, 1.0, v183
	v_subbrev_co_u32_e64 v152, s[0:1], 0, v152, s[0:1]
	v_add_f32_e32 v153, v175, v153
	v_sub_u32_e32 v175, 0, v152
	v_cvt_f32_i32_e32 v152, v152
	v_ldexp_f32 v173, v173, v175
	v_ldexp_f32 v153, v153, v175
	v_add_f32_e32 v175, -1.0, v173
	v_add_f32_e32 v182, 1.0, v173
	v_add_f32_e32 v183, 1.0, v175
	v_add_f32_e32 v184, -1.0, v182
	v_sub_f32_e32 v183, v173, v183
	v_sub_f32_e32 v173, v173, v184
	v_mul_f32_e32 v184, 0x3f317218, v152
	v_add_f32_e32 v183, v153, v183
	v_add_f32_e32 v153, v153, v173
	v_fma_f32 v173, v152, s83, -v184
	v_add_f32_e32 v185, v175, v183
	v_add_f32_e32 v186, v182, v153
	v_fmac_f32_e32 v173, 0xb102e308, v152
	v_sub_f32_e32 v152, v185, v175
	v_sub_f32_e32 v175, v186, v182
	v_rcp_f32_e32 v182, v186
	v_add_f32_e32 v187, v184, v173
	v_sub_f32_e32 v153, v153, v175
	v_sub_f32_e32 v175, v187, v184
	v_sub_f32_e32 v173, v173, v175
	v_mul_f32_e32 v175, v185, v182
	v_sub_f32_e32 v152, v183, v152
	v_mul_f32_e32 v183, v186, v175
	v_fma_f32 v184, v175, v186, -v183
	v_fmac_f32_e32 v184, v175, v153
	v_add_f32_e32 v188, v183, v184
	v_sub_f32_e32 v189, v185, v188
	v_sub_f32_e32 v183, v188, v183
	v_sub_f32_e32 v185, v185, v189
	v_sub_f32_e32 v183, v183, v184
	v_sub_f32_e32 v184, v185, v188
	v_add_f32_e32 v152, v152, v184
	v_add_f32_e32 v152, v183, v152
	v_add_f32_e32 v183, v189, v152
	v_mul_f32_e32 v184, v182, v183
	v_sub_f32_e32 v185, v189, v183
	v_mul_f32_e32 v188, v186, v184
	v_add_f32_e32 v152, v152, v185
	v_add_f32_e32 v185, v175, v184
	v_fma_f32 v186, v184, v186, -v188
	v_sub_f32_e32 v175, v185, v175
	v_fmac_f32_e32 v186, v184, v153
	v_sub_f32_e32 v153, v184, v175
	v_add_f32_e32 v175, v188, v186
	v_sub_f32_e32 v184, v175, v188
	v_sub_f32_e32 v188, v183, v175
	v_sub_f32_e32 v183, v183, v188
	v_sub_f32_e32 v175, v183, v175
	v_sub_f32_e32 v184, v184, v186
	v_add_f32_e32 v152, v152, v175
	v_add_f32_e32 v152, v184, v152
	v_add_f32_e32 v152, v188, v152
	v_mul_f32_e32 v152, v182, v152
	v_add_f32_e32 v152, v153, v152
	v_add_f32_e32 v153, v185, v152
	v_mul_f32_e32 v175, v153, v153
	v_fmamk_f32 v184, v175, 0x3e9b6dac, v204
	v_sub_f32_e32 v182, v153, v185
	v_ldexp_f32 v183, v153, 1
	v_mul_f32_e32 v153, v153, v175
	v_fmaak_f32 v175, v175, v184, 0x3f2aaada
	v_mul_f32_e32 v153, v153, v175
	v_add_f32_e32 v175, v183, v153
	v_sub_f32_e32 v152, v152, v182
	v_sub_f32_e32 v182, v175, v183
	v_ldexp_f32 v152, v152, 1
	v_sub_f32_e32 v153, v153, v182
	v_add_f32_e32 v152, v152, v153
	v_add_f32_e32 v153, v175, v152
	v_sub_f32_e32 v175, v153, v175
	v_add_f32_e32 v182, v187, v153
	v_sub_f32_e32 v152, v152, v175
	v_sub_f32_e32 v175, v182, v187
	v_sub_f32_e32 v183, v182, v175
	v_sub_f32_e32 v153, v153, v175
	v_add_f32_e32 v175, v173, v152
	v_sub_f32_e32 v183, v187, v183
	v_sub_f32_e32 v184, v175, v173
	v_add_f32_e32 v153, v153, v183
	v_sub_f32_e32 v183, v175, v184
	v_sub_f32_e32 v152, v152, v184
	v_sub_f32_e32 v173, v173, v183
	v_add_f32_e32 v153, v175, v153
	v_add_f32_e32 v152, v152, v173
	v_add_f32_e32 v173, v182, v153
	v_sub_f32_e32 v175, v173, v182
	v_sub_f32_e32 v153, v153, v175
	v_add_f32_e32 v152, v152, v153
	v_add_f32_e32 v152, v173, v152
	v_cmp_neq_f32_e64 s[0:1], s84, v154
	s_nop 1
	v_cndmask_b32_e64 v152, v206, v152, s[0:1]
	v_cmp_ngt_f32_e64 s[0:1], -1.0, v154
	s_nop 1
	v_cndmask_b32_e64 v152, v207, v152, s[0:1]
	v_cmp_neq_f32_e64 s[0:1], -1.0, v154
	s_nop 1
	v_cndmask_b32_e64 v152, v208, v152, s[0:1]
	v_cmp_lt_f32_e64 s[0:1], |v154|, s85
	s_nop 1
	v_cndmask_b32_e64 v152, v152, v154, s[0:1]
	v_add_f32_e32 v152, v171, v152
	v_mul_f32_e64 v152, v152, -v155
	global_store_dword v[140:141], v152, off
	global_load_dword v152, v161, s[58:59] offset:4
	s_nop 0
	global_load_dword v153, v161, s[56:57] offset:4
	s_waitcnt vmcnt(1)
	v_add_f32_e32 v148, v148, v152
	v_mul_f32_e64 v149, |v148|, s81
	global_store_dword v[166:167], v150, off offset:8
	v_exp_f32_e32 v150, v149
	s_waitcnt vmcnt(1)
; __device__ __forceinline__ float sigmoid_(float x) { return __builtin_amdgcn_rcpf(1.f + __expf(-x)); }
; __device__ __forceinline__ float softplus_(float x) { return fmaxf(x, 0.f) + log1pf(__expf(-fabsf(x))); }
; template <int MODE>
; __device__ __forceinline__ void norm_phase(const Params& p, const float* src, const float* w, const float* modl, int sh_off, int sc_off,
;                            char* smem, int bid, int nblk) {
;     ...
;           beta[(size_t)row * 4 + h] = sigmoid_(dots[h]);
;           gg[(size_t)row * 4 + h] = -__expf(p.hy_a_log[h]) * softplus_(dots[4 + h] + p.hy_dt_bias[h]);
;         }
	v_mul_f32_e32 v149, 0x3fb8aa3b, v153
	v_exp_f32_e32 v151, v149
	v_max_f32_e32 v152, 0, v148
	v_add_f32_e32 v153, 1.0, v150
	v_add_f32_e32 v154, -1.0, v153
	v_frexp_mant_f32_e32 v155, v153
	v_cvt_f64_f32_e32 v[148:149], v153
	v_sub_f32_e32 v171, v154, v153
	v_frexp_exp_i32_f64_e32 v148, v[148:149]
	v_cmp_gt_f32_e64 s[0:1], s82, v155
	v_sub_f32_e32 v154, v150, v154
	v_add_f32_e32 v149, 1.0, v171
	v_subbrev_co_u32_e64 v148, s[0:1], 0, v148, s[0:1]
	v_add_f32_e32 v149, v154, v149
	v_sub_u32_e32 v154, 0, v148
	v_cvt_f32_i32_e32 v148, v148
	v_ldexp_f32 v153, v153, v154
	v_ldexp_f32 v149, v149, v154
	v_add_f32_e32 v154, -1.0, v153
	v_add_f32_e32 v155, 1.0, v153
	v_add_f32_e32 v171, 1.0, v154
	v_add_f32_e32 v173, -1.0, v155
	v_sub_f32_e32 v171, v153, v171
	v_sub_f32_e32 v153, v153, v173
	v_mul_f32_e32 v173, 0x3f317218, v148
	v_add_f32_e32 v171, v149, v171
	v_add_f32_e32 v149, v149, v153
	v_fma_f32 v153, v148, s83, -v173
	v_add_f32_e32 v175, v154, v171
	v_add_f32_e32 v182, v155, v149
	v_fmac_f32_e32 v153, 0xb102e308, v148
	v_sub_f32_e32 v148, v175, v154
	v_sub_f32_e32 v154, v182, v155
	v_rcp_f32_e32 v155, v182
	v_add_f32_e32 v183, v173, v153
	v_sub_f32_e32 v149, v149, v154
	v_sub_f32_e32 v154, v183, v173
	v_sub_f32_e32 v153, v153, v154
	v_mul_f32_e32 v154, v175, v155
	v_sub_f32_e32 v148, v171, v148
	v_mul_f32_e32 v171, v182, v154
	v_fma_f32 v173, v154, v182, -v171
	v_fmac_f32_e32 v173, v154, v149
	v_add_f32_e32 v184, v171, v173
	v_sub_f32_e32 v185, v175, v184
	v_sub_f32_e32 v171, v184, v171
	v_sub_f32_e32 v175, v175, v185
	v_sub_f32_e32 v171, v171, v173
	v_sub_f32_e32 v173, v175, v184
	v_add_f32_e32 v148, v148, v173
	v_add_f32_e32 v148, v171, v148
	v_add_f32_e32 v171, v185, v148
	v_mul_f32_e32 v173, v155, v171
	v_sub_f32_e32 v175, v185, v171
	v_mul_f32_e32 v184, v182, v173
	v_add_f32_e32 v148, v148, v175
	v_add_f32_e32 v175, v154, v173
	v_fma_f32 v182, v173, v182, -v184
	v_sub_f32_e32 v154, v175, v154
	v_fmac_f32_e32 v182, v173, v149
	v_sub_f32_e32 v149, v173, v154
	v_add_f32_e32 v154, v184, v182
	v_sub_f32_e32 v173, v154, v184
	v_sub_f32_e32 v184, v171, v154
	v_sub_f32_e32 v171, v171, v184
	v_sub_f32_e32 v154, v171, v154
	v_sub_f32_e32 v173, v173, v182
	v_add_f32_e32 v148, v148, v154
	v_add_f32_e32 v148, v173, v148
	v_add_f32_e32 v148, v184, v148
	v_mul_f32_e32 v148, v155, v148
	v_add_f32_e32 v148, v149, v148
	v_add_f32_e32 v149, v175, v148
	v_mul_f32_e32 v154, v149, v149
	v_fmamk_f32 v173, v154, 0x3e9b6dac, v204
	v_sub_f32_e32 v155, v149, v175
	v_ldexp_f32 v171, v149, 1
	v_mul_f32_e32 v149, v149, v154
	v_fmaak_f32 v154, v154, v173, 0x3f2aaada
	v_mul_f32_e32 v149, v149, v154
	v_add_f32_e32 v154, v171, v149
	v_sub_f32_e32 v148, v148, v155
	v_sub_f32_e32 v155, v154, v171
	v_ldexp_f32 v148, v148, 1
	v_sub_f32_e32 v149, v149, v155
	v_add_f32_e32 v148, v148, v149
	v_add_f32_e32 v149, v154, v148
	v_sub_f32_e32 v154, v149, v154
	v_add_f32_e32 v155, v183, v149
	v_sub_f32_e32 v148, v148, v154
	v_sub_f32_e32 v154, v155, v183
	v_sub_f32_e32 v171, v155, v154
	v_sub_f32_e32 v149, v149, v154
	v_add_f32_e32 v154, v153, v148
	v_sub_f32_e32 v171, v183, v171
	v_sub_f32_e32 v173, v154, v153
	v_add_f32_e32 v149, v149, v171
	v_sub_f32_e32 v171, v154, v173
	v_sub_f32_e32 v148, v148, v173
	v_sub_f32_e32 v153, v153, v171
	v_add_f32_e32 v149, v154, v149
	v_add_f32_e32 v148, v148, v153
	v_add_f32_e32 v153, v155, v149
	v_sub_f32_e32 v154, v153, v155
	v_sub_f32_e32 v149, v149, v154
	v_add_f32_e32 v148, v148, v149
	v_add_f32_e32 v148, v153, v148
	v_cmp_neq_f32_e64 s[0:1], s84, v150
	s_nop 1
	v_cndmask_b32_e64 v148, v206, v148, s[0:1]
	v_cmp_ngt_f32_e64 s[0:1], -1.0, v150
	s_nop 1
	v_cndmask_b32_e64 v148, v207, v148, s[0:1]
	v_cmp_neq_f32_e64 s[0:1], -1.0, v150
	s_nop 1
	v_cndmask_b32_e64 v148, v208, v148, s[0:1]
	v_cmp_lt_f32_e64 s[0:1], |v150|, s85
	s_nop 1
	v_cndmask_b32_e64 v148, v148, v150, s[0:1]
	v_add_f32_e32 v148, v152, v148
	v_mul_f32_e64 v148, v148, -v151
	global_store_dword v[140:141], v148, off offset:4
	global_load_dword v148, v161, s[58:59] offset:8
	s_nop 0
	global_load_dword v149, v161, s[56:57] offset:8
	s_waitcnt vmcnt(1)
	v_add_f32_e32 v144, v144, v148
	v_mul_f32_e64 v145, |v144|, s81
	global_store_dword v[166:167], v146, off offset:12
	v_exp_f32_e32 v146, v145
	s_waitcnt vmcnt(1)
; __device__ __forceinline__ float sigmoid_(float x) { return __builtin_amdgcn_rcpf(1.f + __expf(-x)); }
; __device__ __forceinline__ float softplus_(float x) { return fmaxf(x, 0.f) + log1pf(__expf(-fabsf(x))); }
; template <int MODE>
; __device__ __forceinline__ void norm_phase(const Params& p, const float* src, const float* w, const float* modl, int sh_off, int sc_off,
;                            char* smem, int bid, int nblk) {
;     ...
;           beta[(size_t)row * 4 + h] = sigmoid_(dots[h]);
;           gg[(size_t)row * 4 + h] = -__expf(p.hy_a_log[h]) * softplus_(dots[4 + h] + p.hy_dt_bias[h]);
;         }
	v_mul_f32_e32 v145, 0x3fb8aa3b, v149
	v_exp_f32_e32 v147, v145
	v_max_f32_e32 v148, 0, v144
	v_add_f32_e32 v149, 1.0, v146
	v_add_f32_e32 v150, -1.0, v149
	v_frexp_mant_f32_e32 v151, v149
	v_cvt_f64_f32_e32 v[144:145], v149
	v_sub_f32_e32 v152, v150, v149
	v_frexp_exp_i32_f64_e32 v144, v[144:145]
	v_cmp_gt_f32_e64 s[0:1], s82, v151
	v_sub_f32_e32 v150, v146, v150
	v_add_f32_e32 v145, 1.0, v152
	v_subbrev_co_u32_e64 v144, s[0:1], 0, v144, s[0:1]
	v_add_f32_e32 v145, v150, v145
	v_sub_u32_e32 v150, 0, v144
	v_cvt_f32_i32_e32 v144, v144
	v_ldexp_f32 v149, v149, v150
	v_ldexp_f32 v145, v145, v150
	v_add_f32_e32 v150, -1.0, v149
	v_add_f32_e32 v151, 1.0, v149
	v_add_f32_e32 v152, 1.0, v150
	v_add_f32_e32 v153, -1.0, v151
	v_sub_f32_e32 v152, v149, v152
	v_sub_f32_e32 v149, v149, v153
	v_mul_f32_e32 v153, 0x3f317218, v144
	v_add_f32_e32 v152, v145, v152
	v_add_f32_e32 v145, v145, v149
	v_fma_f32 v149, v144, s83, -v153
	v_add_f32_e32 v154, v150, v152
	v_add_f32_e32 v155, v151, v145
	v_fmac_f32_e32 v149, 0xb102e308, v144
	v_sub_f32_e32 v144, v154, v150
	v_sub_f32_e32 v150, v155, v151
	v_rcp_f32_e32 v151, v155
	v_add_f32_e32 v171, v153, v149
	v_sub_f32_e32 v145, v145, v150
	v_sub_f32_e32 v150, v171, v153
	v_sub_f32_e32 v149, v149, v150
	v_mul_f32_e32 v150, v154, v151
	v_sub_f32_e32 v144, v152, v144
	v_mul_f32_e32 v152, v155, v150
	v_fma_f32 v153, v150, v155, -v152
	v_fmac_f32_e32 v153, v150, v145
	v_add_f32_e32 v173, v152, v153
	v_sub_f32_e32 v175, v154, v173
	v_sub_f32_e32 v152, v173, v152
	v_sub_f32_e32 v154, v154, v175
	v_sub_f32_e32 v152, v152, v153
	v_sub_f32_e32 v153, v154, v173
	v_add_f32_e32 v144, v144, v153
	v_add_f32_e32 v144, v152, v144
	v_add_f32_e32 v152, v175, v144
	v_mul_f32_e32 v153, v151, v152
	v_sub_f32_e32 v154, v175, v152
	v_mul_f32_e32 v173, v155, v153
	v_add_f32_e32 v144, v144, v154
	v_add_f32_e32 v154, v150, v153
	v_fma_f32 v155, v153, v155, -v173
	v_sub_f32_e32 v150, v154, v150
	v_fmac_f32_e32 v155, v153, v145
	v_sub_f32_e32 v145, v153, v150
	v_add_f32_e32 v150, v173, v155
	v_sub_f32_e32 v153, v150, v173
	v_sub_f32_e32 v173, v152, v150
	v_sub_f32_e32 v152, v152, v173
	v_sub_f32_e32 v150, v152, v150
	v_sub_f32_e32 v153, v153, v155
	v_add_f32_e32 v144, v144, v150
	v_add_f32_e32 v144, v153, v144
	v_add_f32_e32 v144, v173, v144
	v_mul_f32_e32 v144, v151, v144
	v_add_f32_e32 v144, v145, v144
	v_add_f32_e32 v145, v154, v144
	v_mul_f32_e32 v150, v145, v145
	v_fmamk_f32 v153, v150, 0x3e9b6dac, v204
	v_sub_f32_e32 v151, v145, v154
	v_ldexp_f32 v152, v145, 1
	v_mul_f32_e32 v145, v145, v150
	v_fmaak_f32 v150, v150, v153, 0x3f2aaada
	v_mul_f32_e32 v145, v145, v150
	v_add_f32_e32 v150, v152, v145
	v_sub_f32_e32 v144, v144, v151
	v_sub_f32_e32 v151, v150, v152
	v_ldexp_f32 v144, v144, 1
	v_sub_f32_e32 v145, v145, v151
	v_add_f32_e32 v144, v144, v145
	v_add_f32_e32 v145, v150, v144
	v_sub_f32_e32 v150, v145, v150
	v_add_f32_e32 v151, v171, v145
	v_sub_f32_e32 v144, v144, v150
	v_sub_f32_e32 v150, v151, v171
	v_sub_f32_e32 v152, v151, v150
	v_sub_f32_e32 v145, v145, v150
	v_add_f32_e32 v150, v149, v144
	v_sub_f32_e32 v152, v171, v152
	v_sub_f32_e32 v153, v150, v149
	v_add_f32_e32 v145, v145, v152
	v_sub_f32_e32 v152, v150, v153
	v_sub_f32_e32 v144, v144, v153
	v_sub_f32_e32 v149, v149, v152
	v_add_f32_e32 v145, v150, v145
	v_add_f32_e32 v144, v144, v149
	v_add_f32_e32 v149, v151, v145
	v_sub_f32_e32 v150, v149, v151
	v_sub_f32_e32 v145, v145, v150
	v_add_f32_e32 v144, v144, v145
	v_add_f32_e32 v144, v149, v144
	v_cmp_neq_f32_e64 s[0:1], s84, v146
	s_nop 1
	v_cndmask_b32_e64 v144, v206, v144, s[0:1]
	v_cmp_ngt_f32_e64 s[0:1], -1.0, v146
	s_nop 1
	v_cndmask_b32_e64 v144, v207, v144, s[0:1]
	v_cmp_neq_f32_e64 s[0:1], -1.0, v146
	s_nop 1
	v_cndmask_b32_e64 v144, v208, v144, s[0:1]
	v_cmp_lt_f32_e64 s[0:1], |v146|, s85
	s_nop 1
	v_cndmask_b32_e64 v144, v144, v146, s[0:1]
	v_add_f32_e32 v144, v148, v144
	v_mul_f32_e64 v144, v144, -v147
	global_store_dword v[140:141], v144, off offset:8
	global_load_dword v144, v161, s[58:59] offset:12
	s_nop 0
	global_load_dword v145, v161, s[56:57] offset:12
	s_waitcnt vmcnt(1)
	v_add_f32_e32 v142, v142, v144
	v_mul_f32_e64 v143, |v142|, s81
	v_exp_f32_e32 v144, v143
	s_waitcnt vmcnt(0)
	v_mul_f32_e32 v143, 0x3fb8aa3b, v145
	v_exp_f32_e32 v145, v143
	v_max_f32_e32 v146, 0, v142
	v_add_f32_e32 v147, 1.0, v144
	v_add_f32_e32 v148, -1.0, v147
	v_frexp_mant_f32_e32 v149, v147
	v_cvt_f64_f32_e32 v[142:143], v147
	v_sub_f32_e32 v150, v148, v147
	v_frexp_exp_i32_f64_e32 v142, v[142:143]
	v_cmp_gt_f32_e64 s[0:1], s82, v149
	v_sub_f32_e32 v148, v144, v148
	v_add_f32_e32 v143, 1.0, v150
	v_subbrev_co_u32_e64 v142, s[0:1], 0, v142, s[0:1]
	v_add_f32_e32 v143, v148, v143
	v_sub_u32_e32 v148, 0, v142
	v_cvt_f32_i32_e32 v142, v142
	v_ldexp_f32 v147, v147, v148
	v_ldexp_f32 v143, v143, v148
	v_add_f32_e32 v148, -1.0, v147
	v_add_f32_e32 v149, 1.0, v147
	v_add_f32_e32 v150, 1.0, v148
	v_add_f32_e32 v151, -1.0, v149
	v_sub_f32_e32 v150, v147, v150
	v_sub_f32_e32 v147, v147, v151
	v_mul_f32_e32 v151, 0x3f317218, v142
	v_add_f32_e32 v150, v143, v150
	v_add_f32_e32 v143, v143, v147
	v_fma_f32 v147, v142, s83, -v151
	v_add_f32_e32 v152, v148, v150
	v_add_f32_e32 v153, v149, v143
	v_fmac_f32_e32 v147, 0xb102e308, v142
	v_sub_f32_e32 v142, v152, v148
	v_sub_f32_e32 v148, v153, v149
	v_rcp_f32_e32 v149, v153
	v_add_f32_e32 v154, v151, v147
	v_sub_f32_e32 v143, v143, v148
	v_sub_f32_e32 v148, v154, v151
	v_sub_f32_e32 v147, v147, v148
	v_mul_f32_e32 v148, v152, v149
	v_sub_f32_e32 v142, v150, v142
	v_mul_f32_e32 v150, v153, v148
	v_fma_f32 v151, v148, v153, -v150
	v_fmac_f32_e32 v151, v148, v143
	v_add_f32_e32 v155, v150, v151
; __device__ __forceinline__ u16 f2bf(float x) { unsigned u = __float_as_uint(x); u += 0x7fffu + ((u >> 16) & 1u); return (u16)(u >> 16); }
; __device__ __forceinline__ size_t a_off(int row, int col, int nks) { return ((size_t)((row >> 8) * nks + (col >> 5)) << 13) + ((row & 255) << 5) + swzc(row, col & 31); }
; template <int MODE>
; __device__ __forceinline__ void norm_phase(const Params& p, const float* src, const float* w, const float* modl, int sh_off, int sc_off,
;                            char* smem, int bid, int nblk) {
;     ...
;   auto process = [&](int row, f32x4 (&v)[4]) {
;     float ss = 0.f;
; #pragma unroll
;     for (int i = 0; i < 4; ++i) ss += v[i][0] * v[i][0] + v[i][1] * v[i][1] + v[i][2] * v[i][2] + v[i][3] * v[i][3];
; #pragma unroll
;     for (int o = 32; o >= 1; o >>= 1) ss += __shfl_xor(ss, o);
;     const float rstd = rsqrtf(ss * (1.f / 1024.f) + 1e-6f);
;     const int b = row >> 13;
;     float dots[8];
;     if (MODE == 1) { for (int j = 0; j < 8; ++j) dots[j] = 0.f; }
; #pragma unroll
;     for (int i = 0; i < 4; ++i) {
;       const int c0 = i * 256 + lane * 4;
;       f32x4 ww = *(const f32x4*)(w + c0);
;       f32x4 y;
;       if (MODE == 2) {
; #pragma unroll
;         for (int e = 0; e < 4; ++e) y[e] = v[i][e] * rstd * ww[e];
;         *(f32x4*)(p.out + (size_t)row * 1024 + c0) = y;
;       } else {
;         f32x4 sc = *(const f32x4*)(modl + (size_t)b * 6144 + sc_off + c0);
;         f32x4 sh = *(const f32x4*)(modl + (size_t)b * 6144 + sh_off + c0);
; #pragma unroll
;         for (int e = 0; e < 4; ++e) y[e] = v[i][e] * rstd * ww[e] * (1.f + sc[e]) + sh[e];
;         uint2 pk; pk.x = (unsigned)f2bf(y[0]) | ((unsigned)f2bf(y[1]) << 16); pk.y = (unsigned)f2bf(y[2]) | ((unsigned)f2bf(y[3]) << 16);
;         *(uint2*)(hn + a_off(row, c0, 32)) = pk;
	v_sub_f32_e32 v171, v152, v155
	v_sub_f32_e32 v150, v155, v150
	v_sub_f32_e32 v152, v152, v171
	v_sub_f32_e32 v150, v150, v151
	v_sub_f32_e32 v151, v152, v155
	v_add_f32_e32 v142, v142, v151
	v_add_f32_e32 v142, v150, v142
	v_add_f32_e32 v150, v171, v142
	v_mul_f32_e32 v151, v149, v150
	v_sub_f32_e32 v152, v171, v150
	v_mul_f32_e32 v155, v153, v151
	v_add_f32_e32 v142, v142, v152
	v_add_f32_e32 v152, v148, v151
	v_fma_f32 v153, v151, v153, -v155
	v_sub_f32_e32 v148, v152, v148
	v_fmac_f32_e32 v153, v151, v143
	v_sub_f32_e32 v143, v151, v148
	v_add_f32_e32 v148, v155, v153
	v_sub_f32_e32 v151, v148, v155
	v_sub_f32_e32 v155, v150, v148
	v_sub_f32_e32 v150, v150, v155
	v_sub_f32_e32 v148, v150, v148
	v_sub_f32_e32 v151, v151, v153
	v_add_f32_e32 v142, v142, v148
	v_add_f32_e32 v142, v151, v142
	v_add_f32_e32 v142, v155, v142
	v_mul_f32_e32 v142, v149, v142
	v_add_f32_e32 v142, v143, v142
	v_add_f32_e32 v143, v152, v142
	v_mul_f32_e32 v148, v143, v143
	v_fmamk_f32 v151, v148, 0x3e9b6dac, v204
	v_sub_f32_e32 v149, v143, v152
	v_ldexp_f32 v150, v143, 1
	v_mul_f32_e32 v143, v143, v148
	v_fmaak_f32 v148, v148, v151, 0x3f2aaada
	v_mul_f32_e32 v143, v143, v148
	v_add_f32_e32 v148, v150, v143
	v_sub_f32_e32 v142, v142, v149
	v_sub_f32_e32 v149, v148, v150
	v_ldexp_f32 v142, v142, 1
	v_sub_f32_e32 v143, v143, v149
	v_add_f32_e32 v142, v142, v143
	v_add_f32_e32 v143, v148, v142
	v_sub_f32_e32 v148, v143, v148
	v_add_f32_e32 v149, v154, v143
	v_sub_f32_e32 v142, v142, v148
	v_sub_f32_e32 v148, v149, v154
	v_sub_f32_e32 v150, v149, v148
	v_sub_f32_e32 v143, v143, v148
	v_add_f32_e32 v148, v147, v142
	v_sub_f32_e32 v150, v154, v150
	v_sub_f32_e32 v151, v148, v147
	v_add_f32_e32 v143, v143, v150
	v_sub_f32_e32 v150, v148, v151
	v_sub_f32_e32 v142, v142, v151
	v_sub_f32_e32 v147, v147, v150
	v_add_f32_e32 v143, v148, v143
	v_add_f32_e32 v142, v142, v147
	v_add_f32_e32 v147, v149, v143
	v_sub_f32_e32 v148, v147, v149
	v_sub_f32_e32 v143, v143, v148
	v_add_f32_e32 v142, v142, v143
	v_add_f32_e32 v142, v147, v142
	v_cmp_neq_f32_e64 s[0:1], s84, v144
	s_nop 1
	v_cndmask_b32_e64 v142, v206, v142, s[0:1]
	v_cmp_ngt_f32_e64 s[0:1], -1.0, v144
	s_nop 1
	v_cndmask_b32_e64 v142, v207, v142, s[0:1]
	v_cmp_neq_f32_e64 s[0:1], -1.0, v144
	s_nop 1
	v_cndmask_b32_e64 v142, v208, v142, s[0:1]
	v_cmp_lt_f32_e64 s[0:1], |v144|, s85
	s_nop 1
	v_cndmask_b32_e64 v142, v142, v144, s[0:1]
	v_add_f32_e32 v142, v146, v142
	v_mul_f32_e64 v142, v142, -v145
	global_store_dword v[140:141], v142, off offset:12
.LBB0_109:
	s_or_b64 exec, exec, s[64:65]
	s_and_saveexec_b64 s[64:65], s[4:5]
	s_cbranch_execz .LBB0_98
	v_ashrrev_i32_e32 v140, 13, v176
	v_mul_i32_i24_e32 v140, 0x1800, v140
	v_readlane_b32 s0, v244, 23
	v_ashrrev_i32_e32 v141, 31, v140
	v_readlane_b32 s1, v244, 24
	s_waitcnt lgkmcnt(2)
	global_load_dwordx4 v[148:151], v[164:165], off
	v_pk_mul_f32 v[186:187], v[132:133], v[132:133]
	v_lshl_add_u64 v[140:141], v[140:141], 2, s[0:1]
	s_waitcnt lgkmcnt(0)
	v_lshl_add_u64 v[142:143], v[140:141], 0, s[30:31]
	v_lshl_add_u64 v[144:145], v[142:143], 0, v[160:161]
	global_load_dwordx4 v[152:155], v[144:145], off
	v_lshl_add_u64 v[140:141], v[140:141], 0, v[160:161]
	global_load_dwordx4 v[182:185], v[140:141], off
	v_pk_mul_f32 v[188:189], v[136:137], v[136:137]
	v_pk_mul_f32 v[144:145], v[138:139], v[138:139]
	v_pk_mul_f32 v[146:147], v[134:135], v[134:135]
	v_mov_b32_e32 v212, v188
	v_mov_b32_e32 v213, v186
	v_mov_b32_e32 v186, v189
	v_pk_mul_f32 v[210:211], v[180:181], v[180:181]
	v_mov_b32_e32 v188, v144
	v_mov_b32_e32 v189, v146
	v_pk_add_f32 v[186:187], v[212:213], v[186:187]
	v_mov_b32_e32 v146, v145
	v_pk_fma_f32 v[144:145], v[128:129], v[128:129], v[210:211]
	v_pk_add_f32 v[186:187], v[188:189], v[186:187]
	v_pk_fma_f32 v[144:145], v[130:131], v[130:131], v[144:145]
	v_pk_add_f32 v[146:147], v[146:147], v[186:187]
	v_pk_fma_f32 v[144:145], v[178:179], v[178:179], v[144:145]
	v_add_f32_e32 v146, v146, v147
	v_add_f32_e32 v144, v144, v146
	v_add_f32_e32 v144, v144, v145
	ds_bpermute_b32 v145, v159, v144
	v_mov_b32_e32 v186, v136
	v_ashrrev_i32_e32 v146, 3, v176
	v_add_u32_e32 v147, s9, v203
	v_and_b32_e32 v190, 0xffffffe0, v146
	s_waitcnt lgkmcnt(0)
	v_add_f32_e32 v144, v144, v145
	ds_bpermute_b32 v145, v191, v144
	v_and_b32_e32 v146, 0x1fe0, v147
	v_add_u32_e32 v171, s8, v202
	v_mov_b32_e32 v187, v138
	v_mov_b32_e32 v138, v137
	s_waitcnt lgkmcnt(0)
	v_add_f32_e32 v144, v144, v145
	ds_bpermute_b32 v160, v192, v144
	v_and_b32_e32 v137, 24, v171
	v_mov_b32_e32 v145, v161
	v_mov_b32_e32 v173, v161
	v_mov_b32_e32 v175, v161
	s_waitcnt lgkmcnt(0)
	v_add_f32_e32 v136, v144, v160
	ds_bpermute_b32 v144, v193, v136
	v_sub_u32_e32 v160, 0, v137
	v_xor_b32_e32 v160, v158, v160
	v_and_or_b32 v171, v160, 24, v197
	v_lshlrev_b32_e32 v160, 1, v146
	s_waitcnt lgkmcnt(0)
	v_add_f32_e32 v144, v136, v144
	ds_bpermute_b32 v147, v194, v144
	v_or_b32_e32 v136, v190, v196
	v_ashrrev_i32_e32 v137, 31, v136
	v_lshlrev_b64 v[136:137], 14, v[136:137]
	v_lshl_add_u64 v[136:137], s[62:63], 0, v[136:137]
	s_waitcnt lgkmcnt(0)
	v_add_f32_e32 v144, v144, v147
	ds_bpermute_b32 v147, v195, v144
	v_lshl_add_u64 v[136:137], v[136:137], 0, v[160:161]
	s_waitcnt lgkmcnt(0)
	v_add_f32_e32 v144, v144, v147
	v_fmamk_f32 v144, v144, 0x3a800000, v157
	v_mul_f32_e32 v146, 0x4b800000, v144
	v_cmp_gt_f32_e64 s[0:1], s67, v144
	s_nop 1
	v_cndmask_b32_e64 v144, v144, v146, s[0:1]
	v_rsq_f32_e32 v146, v144
	v_lshlrev_b32_e32 v144, 1, v171
	v_lshl_add_u64 v[188:189], v[136:137], 0, v[144:145]
	v_mov_b32_e32 v171, v161
	v_mul_f32_e32 v136, 0x45800000, v146
	v_cndmask_b32_e64 v146, v146, v136, s[0:1]
	v_pk_mul_f32 v[136:137], v[186:187], v[146:147] op_sel_hi:[1,0]
	v_pk_mul_f32 v[138:139], v[138:139], v[146:147] op_sel_hi:[1,0]
	s_waitcnt vmcnt(2)
; __device__ __forceinline__ u16 f2bf(float x) { unsigned u = __float_as_uint(x); u += 0x7fffu + ((u >> 16) & 1u); return (u16)(u >> 16); }
; __device__ __forceinline__ size_t a_off(int row, int col, int nks) { return ((size_t)((row >> 8) * nks + (col >> 5)) << 13) + ((row & 255) << 5) + swzc(row, col & 31); }
; template <int MODE>
; __device__ __forceinline__ void norm_phase(const Params& p, const float* src, const float* w, const float* modl, int sh_off, int sc_off,
;                            char* smem, int bid, int nblk) {
;     ...
; #pragma unroll
;     for (int i = 0; i < 4; ++i) {
;       const int c0 = i * 256 + lane * 4;
;       f32x4 ww = *(const f32x4*)(w + c0);
;       f32x4 y;
;       if (MODE == 2) {
; #pragma unroll
;         for (int e = 0; e < 4; ++e) y[e] = v[i][e] * rstd * ww[e];
;         *(f32x4*)(p.out + (size_t)row * 1024 + c0) = y;
;       } else {
;         f32x4 sc = *(const f32x4*)(modl + (size_t)b * 6144 + sc_off + c0);
;         f32x4 sh = *(const f32x4*)(modl + (size_t)b * 6144 + sh_off + c0);
; #pragma unroll
;         for (int e = 0; e < 4; ++e) y[e] = v[i][e] * rstd * ww[e] * (1.f + sc[e]) + sh[e];
;         uint2 pk; pk.x = (unsigned)f2bf(y[0]) | ((unsigned)f2bf(y[1]) << 16); pk.y = (unsigned)f2bf(y[2]) | ((unsigned)f2bf(y[3]) << 16);
;         *(uint2*)(hn + a_off(row, c0, 32)) = pk;
;         if (MODE == 1) {
; #pragma unroll
;           for (int e = 0; e < 4; ++e) {
;             f32x4 w0 = *(const f32x4*)(wba + (c0 + e) * 8), w1 = *(const f32x4*)(wba + (c0 + e) * 8 + 4);
; #pragma unroll
;             for (int j = 0; j < 4; ++j) { dots[j] += y[e] * w0[j]; dots[4 + j] += y[e] * w1[j]; }
;           }
;         }
	v_mov_b32_e32 v187, v150
	v_mov_b32_e32 v150, v149
	v_mov_b32_e32 v186, v148
	v_pk_mul_f32 v[148:149], v[150:151], v[138:139]
	v_pk_mul_f32 v[136:137], v[186:187], v[136:137]
	s_waitcnt vmcnt(1)
	v_mov_b32_e32 v138, v152
	v_mov_b32_e32 v139, v154
	v_mov_b32_e32 v154, v153
	s_waitcnt vmcnt(0)
	v_mov_b32_e32 v150, v182
	v_mov_b32_e32 v151, v184
	v_mov_b32_e32 v184, v183
	v_pk_add_f32 v[138:139], v[138:139], 1.0 op_sel_hi:[1,0]
	v_pk_add_f32 v[152:153], v[154:155], 1.0 op_sel_hi:[1,0]
	v_pk_fma_f32 v[138:139], v[138:139], v[136:137], v[150:151]
	v_pk_fma_f32 v[136:137], v[152:153], v[148:149], v[184:185]
	v_and_b32_sdwa v147, v139, v205 dst_sel:DWORD dst_unused:UNUSED_PAD src0_sel:WORD_1 src1_sel:DWORD
	v_and_b32_sdwa v149, v137, v205 dst_sel:DWORD dst_unused:UNUSED_PAD src0_sel:WORD_1 src1_sel:DWORD
	v_and_b32_sdwa v150, v136, v205 dst_sel:DWORD dst_unused:UNUSED_PAD src0_sel:WORD_1 src1_sel:DWORD
	v_and_b32_sdwa v148, v138, v205 dst_sel:DWORD dst_unused:UNUSED_PAD src0_sel:WORD_1 src1_sel:DWORD
	v_add3_u32 v149, v137, v149, s80
	v_add3_u32 v150, v136, v150, s80
	v_add3_u32 v148, v138, v148, s80
	v_add3_u32 v147, v139, v147, s80
	v_and_b32_e32 v149, 0xffff0000, v149
	v_and_b32_e32 v150, 0xffff0000, v150
	v_or_b32_sdwa v149, v149, v147 dst_sel:DWORD dst_unused:UNUSED_PAD src0_sel:DWORD src1_sel:WORD_1
	v_or_b32_sdwa v148, v150, v148 dst_sel:DWORD dst_unused:UNUSED_PAD src0_sel:DWORD src1_sel:WORD_1
	v_mov_b32_e32 v250, v188
	v_mov_b32_e32 v251, v189
	v_mov_b32_e32 v252, v148
	v_mov_b32_e32 v253, v149
	global_load_dwordx4 v[148:151], v[164:165], off offset:1024
	v_lshl_add_u64 v[152:153], v[142:143], 0, v[170:171]
	global_load_dwordx4 v[152:155], v[152:153], off
	s_nop 0
	global_load_dwordx4 v[182:185], v[140:141], off offset:1024
	global_store_dwordx2 v[250:251], v[252:253], off
	v_mov_b32_e32 v186, v132
	v_or_b32_e32 v132, v190, v199
	v_mov_b32_e32 v187, v134
	v_mov_b32_e32 v134, v133
	v_ashrrev_i32_e32 v133, 31, v132
	v_lshlrev_b64 v[132:133], 14, v[132:133]
	v_lshl_add_u64 v[132:133], s[62:63], 0, v[132:133]
	v_lshl_add_u64 v[132:133], v[132:133], 0, v[160:161]
	v_lshl_add_u64 v[188:189], v[132:133], 0, v[144:145]
	v_pk_mul_f32 v[132:133], v[186:187], v[146:147] op_sel_hi:[1,0]
	v_pk_mul_f32 v[134:135], v[134:135], v[146:147] op_sel_hi:[1,0]
	v_fma_f32 v171, v4, v138, 0
	v_fma_f32 v209, v6, v138, 0
	v_fmac_f32_e32 v171, v12, v136
	v_fmac_f32_e32 v209, v14, v136
	v_fmac_f32_e32 v171, v20, v139
	v_fmac_f32_e32 v209, v22, v139
	v_fmac_f32_e32 v171, v28, v137
	v_fmac_f32_e32 v209, v30, v137
	s_waitcnt vmcnt(3)
	v_mov_b32_e32 v186, v148
	v_mov_b32_e32 v187, v150
	s_waitcnt vmcnt(2)
	v_mov_b32_e32 v210, v152
	v_mov_b32_e32 v211, v154
	v_mov_b32_e32 v150, v149
	v_mov_b32_e32 v154, v153
	s_waitcnt vmcnt(1)
	v_mov_b32_e32 v212, v182
	v_mov_b32_e32 v213, v184
	v_mov_b32_e32 v184, v183
	v_pk_mul_f32 v[132:133], v[186:187], v[132:133]
	v_pk_add_f32 v[148:149], v[210:211], 1.0 op_sel_hi:[1,0]
	v_pk_mul_f32 v[150:151], v[150:151], v[134:135]
	v_pk_add_f32 v[152:153], v[154:155], 1.0 op_sel_hi:[1,0]
	v_pk_fma_f32 v[134:135], v[148:149], v[132:133], v[212:213]
	v_pk_fma_f32 v[132:133], v[152:153], v[150:151], v[184:185]
	v_and_b32_sdwa v147, v135, v205 dst_sel:DWORD dst_unused:UNUSED_PAD src0_sel:WORD_1 src1_sel:DWORD
	v_and_b32_sdwa v149, v133, v205 dst_sel:DWORD dst_unused:UNUSED_PAD src0_sel:WORD_1 src1_sel:DWORD
	v_and_b32_sdwa v150, v132, v205 dst_sel:DWORD dst_unused:UNUSED_PAD src0_sel:WORD_1 src1_sel:DWORD
	v_and_b32_sdwa v148, v134, v205 dst_sel:DWORD dst_unused:UNUSED_PAD src0_sel:WORD_1 src1_sel:DWORD
	v_add3_u32 v149, v133, v149, s80
	v_add3_u32 v150, v132, v150, s80
	v_add3_u32 v148, v134, v148, s80
	v_add3_u32 v147, v135, v147, s80
	v_and_b32_e32 v149, 0xffff0000, v149
	v_and_b32_e32 v150, 0xffff0000, v150
	v_or_b32_sdwa v149, v149, v147 dst_sel:DWORD dst_unused:UNUSED_PAD src0_sel:DWORD src1_sel:WORD_1
	v_or_b32_sdwa v148, v150, v148 dst_sel:DWORD dst_unused:UNUSED_PAD src0_sel:DWORD src1_sel:WORD_1
	v_mov_b32_e32 v250, v188
	v_mov_b32_e32 v251, v189
	v_mov_b32_e32 v252, v148
	v_mov_b32_e32 v253, v149
	global_load_dwordx4 v[148:151], v[164:165], off offset:2048
	v_lshl_add_u64 v[152:153], v[142:143], 0, v[172:173]
	global_load_dwordx4 v[152:155], v[152:153], off
	s_nop 0
	global_load_dwordx4 v[182:185], v[140:141], off offset:2048
	global_store_dwordx2 v[250:251], v[252:253], off
	v_mov_b32_e32 v186, v128
	v_or_b32_e32 v128, v190, v200
	v_or_b32_e32 v210, v190, v201
	v_mov_b32_e32 v187, v130
	v_mov_b32_e32 v130, v129
	v_ashrrev_i32_e32 v129, 31, v128
	v_ashrrev_i32_e32 v211, 31, v210
	v_mov_b32_e32 v188, v180
	v_mov_b32_e32 v189, v178
	v_mov_b32_e32 v178, v181
	v_lshlrev_b64 v[128:129], 14, v[128:129]
	v_lshlrev_b64 v[180:181], 14, v[210:211]
	v_lshl_add_u64 v[128:129], s[62:63], 0, v[128:129]
	v_lshl_add_u64 v[210:211], v[142:143], 0, v[174:175]
	v_lshl_add_u64 v[142:143], s[62:63], 0, v[180:181]
	v_lshl_add_u64 v[128:129], v[128:129], 0, v[160:161]
	v_lshl_add_u64 v[142:143], v[142:143], 0, v[160:161]
	v_lshl_add_u64 v[180:181], v[128:129], 0, v[144:145]
	v_lshl_add_u64 v[128:129], v[142:143], 0, v[144:145]
	v_pk_mul_f32 v[142:143], v[186:187], v[146:147] op_sel_hi:[1,0]
	v_pk_mul_f32 v[144:145], v[188:189], v[146:147] op_sel_hi:[1,0]
	v_pk_mul_f32 v[130:131], v[130:131], v[146:147] op_sel_hi:[1,0]
	v_pk_mul_f32 v[178:179], v[178:179], v[146:147] op_sel_hi:[1,0]
	v_fma_f32 v160, v0, v138, 0
	v_fma_f32 v173, v1, v138, 0
	v_fma_f32 v175, v5, v138, 0
	v_fma_f32 v190, v2, v138, 0
	v_fma_f32 v212, v3, v138, 0
	v_fma_f32 v213, v7, v138, 0
	v_fmac_f32_e32 v160, v8, v136
	v_fmac_f32_e32 v173, v9, v136
	v_fmac_f32_e32 v175, v13, v136
; __device__ __forceinline__ u16 f2bf(float x) { unsigned u = __float_as_uint(x); u += 0x7fffu + ((u >> 16) & 1u); return (u16)(u >> 16); }
; __device__ __forceinline__ size_t a_off(int row, int col, int nks) { return ((size_t)((row >> 8) * nks + (col >> 5)) << 13) + ((row & 255) << 5) + swzc(row, col & 31); }
; template <int MODE>
; __device__ __forceinline__ void norm_phase(const Params& p, const float* src, const float* w, const float* modl, int sh_off, int sc_off,
;                            char* smem, int bid, int nblk) {
;     ...
; #pragma unroll
;     for (int i = 0; i < 4; ++i) {
;       const int c0 = i * 256 + lane * 4;
;       f32x4 ww = *(const f32x4*)(w + c0);
;       f32x4 y;
;       if (MODE == 2) {
; #pragma unroll
;         for (int e = 0; e < 4; ++e) y[e] = v[i][e] * rstd * ww[e];
;         *(f32x4*)(p.out + (size_t)row * 1024 + c0) = y;
;       } else {
;         f32x4 sc = *(const f32x4*)(modl + (size_t)b * 6144 + sc_off + c0);
;         f32x4 sh = *(const f32x4*)(modl + (size_t)b * 6144 + sh_off + c0);
; #pragma unroll
;         for (int e = 0; e < 4; ++e) y[e] = v[i][e] * rstd * ww[e] * (1.f + sc[e]) + sh[e];
;         uint2 pk; pk.x = (unsigned)f2bf(y[0]) | ((unsigned)f2bf(y[1]) << 16); pk.y = (unsigned)f2bf(y[2]) | ((unsigned)f2bf(y[3]) << 16);
;         *(uint2*)(hn + a_off(row, c0, 32)) = pk;
;         if (MODE == 1) {
; #pragma unroll
;           for (int e = 0; e < 4; ++e) {
;             f32x4 w0 = *(const f32x4*)(wba + (c0 + e) * 8), w1 = *(const f32x4*)(wba + (c0 + e) * 8 + 4);
; #pragma unroll
;             for (int j = 0; j < 4; ++j) { dots[j] += y[e] * w0[j]; dots[4 + j] += y[e] * w1[j]; }
;           }
;         }
	v_fmac_f32_e32 v190, v10, v136
	v_fmac_f32_e32 v212, v11, v136
	v_fmac_f32_e32 v213, v15, v136
	v_fmac_f32_e32 v160, v16, v139
	v_fmac_f32_e32 v160, v24, v137
	v_fmac_f32_e32 v173, v17, v139
	v_fmac_f32_e32 v175, v21, v139
	v_fmac_f32_e32 v190, v18, v139
	v_fmac_f32_e32 v212, v19, v139
	v_fmac_f32_e32 v213, v23, v139
	v_fmac_f32_e32 v160, v32, v134
	v_fmac_f32_e32 v173, v25, v137
	v_fmac_f32_e32 v175, v29, v137
	v_fmac_f32_e32 v190, v26, v137
	v_fmac_f32_e32 v212, v27, v137
	v_fmac_f32_e32 v213, v31, v137
	v_fmac_f32_e32 v160, v40, v132
	v_fmac_f32_e32 v171, v36, v134
	v_fmac_f32_e32 v173, v33, v134
	v_fmac_f32_e32 v175, v37, v134
	v_fmac_f32_e32 v190, v34, v134
	v_fmac_f32_e32 v209, v38, v134
	v_fmac_f32_e32 v212, v35, v134
	v_fmac_f32_e32 v213, v39, v134
	v_fmac_f32_e32 v160, v48, v135
	v_fmac_f32_e32 v171, v44, v132
	v_fmac_f32_e32 v173, v41, v132
	v_fmac_f32_e32 v175, v45, v132
	v_fmac_f32_e32 v190, v42, v132
	v_fmac_f32_e32 v209, v46, v132
	v_fmac_f32_e32 v212, v43, v132
	v_fmac_f32_e32 v213, v47, v132
	v_fmac_f32_e32 v160, v56, v133
	v_fmac_f32_e32 v171, v52, v135
	v_fmac_f32_e32 v173, v49, v135
	v_fmac_f32_e32 v175, v53, v135
	v_fmac_f32_e32 v190, v50, v135
	v_fmac_f32_e32 v209, v54, v135
	v_fmac_f32_e32 v212, v51, v135
	v_fmac_f32_e32 v213, v55, v135
	v_fmac_f32_e32 v171, v60, v133
	v_fmac_f32_e32 v173, v57, v133
	v_fmac_f32_e32 v175, v61, v133
	v_fmac_f32_e32 v190, v58, v133
	v_fmac_f32_e32 v209, v62, v133
	s_waitcnt vmcnt(3)
	v_mov_b32_e32 v147, v150
	s_waitcnt vmcnt(2)
	v_mov_b32_e32 v187, v154
	v_mov_b32_e32 v150, v149
	v_mov_b32_e32 v154, v153
	v_mov_b32_e32 v146, v148
	v_mov_b32_e32 v186, v152
	s_waitcnt vmcnt(1)
	v_mov_b32_e32 v189, v184
	v_mov_b32_e32 v184, v183
	v_pk_mul_f32 v[144:145], v[144:145], v[150:151]
	v_pk_add_f32 v[148:149], v[154:155], 1.0 op_sel_hi:[1,0]
	v_mov_b32_e32 v188, v182
	v_pk_mul_f32 v[142:143], v[142:143], v[146:147]
	v_pk_add_f32 v[146:147], v[186:187], 1.0 op_sel_hi:[1,0]
	v_pk_fma_f32 v[182:183], v[144:145], v[148:149], v[184:185]
	v_pk_fma_f32 v[154:155], v[142:143], v[146:147], v[188:189]
	v_and_b32_sdwa v142, v183, v205 dst_sel:DWORD dst_unused:UNUSED_PAD src0_sel:WORD_1 src1_sel:DWORD
	v_and_b32_sdwa v143, v182, v205 dst_sel:DWORD dst_unused:UNUSED_PAD src0_sel:WORD_1 src1_sel:DWORD
	v_and_b32_sdwa v136, v155, v205 dst_sel:DWORD dst_unused:UNUSED_PAD src0_sel:WORD_1 src1_sel:DWORD
	v_and_b32_sdwa v138, v154, v205 dst_sel:DWORD dst_unused:UNUSED_PAD src0_sel:WORD_1 src1_sel:DWORD
	v_add3_u32 v142, v183, v142, s80
	v_add3_u32 v143, v182, v143, s80
	v_add3_u32 v138, v154, v138, s80
	v_add3_u32 v136, v155, v136, s80
	v_and_b32_e32 v142, 0xffff0000, v142
	v_and_b32_e32 v144, 0xffff0000, v143
	v_or_b32_sdwa v143, v142, v136 dst_sel:DWORD dst_unused:UNUSED_PAD src0_sel:DWORD src1_sel:WORD_1
	v_or_b32_sdwa v142, v144, v138 dst_sel:DWORD dst_unused:UNUSED_PAD src0_sel:DWORD src1_sel:WORD_1
	v_mov_b32_e32 v250, v180
	v_mov_b32_e32 v251, v181
	v_mov_b32_e32 v252, v142
	v_mov_b32_e32 v253, v143
	global_load_dwordx4 v[142:145], v[164:165], off offset:3072
	v_fmac_f32_e32 v160, v88, v154
	global_load_dwordx4 v[146:149], v[210:211], off
	global_load_dwordx4 v[150:153], v[140:141], off offset:3072
	global_store_dwordx2 v[250:251], v[252:253], off
	v_fmac_f32_e32 v212, v59, v133
	v_fmac_f32_e32 v213, v63, v133
	v_fmac_f32_e32 v160, v64, v182
	v_fmac_f32_e32 v160, v72, v155
	v_fmac_f32_e32 v171, v96, v154
	v_fmac_f32_e32 v173, v89, v154
	v_fmac_f32_e32 v175, v97, v154
	v_fmac_f32_e32 v190, v90, v154
	v_fmac_f32_e32 v209, v98, v154
	v_fmac_f32_e32 v212, v91, v154
	v_fmac_f32_e32 v213, v99, v154
	v_fmac_f32_e32 v160, v80, v183
	v_fmac_f32_e32 v171, v68, v182
	v_fmac_f32_e32 v173, v65, v182
	v_fmac_f32_e32 v175, v69, v182
	v_fmac_f32_e32 v190, v66, v182
	v_fmac_f32_e32 v209, v70, v182
	v_fmac_f32_e32 v212, v67, v182
	v_fmac_f32_e32 v213, v71, v182
	v_fmac_f32_e32 v171, v76, v155
	v_fmac_f32_e32 v173, v73, v155
	v_fmac_f32_e32 v175, v77, v155
	v_fmac_f32_e32 v190, v74, v155
	v_fmac_f32_e32 v209, v78, v155
	v_fmac_f32_e32 v212, v75, v155
	v_fmac_f32_e32 v213, v79, v155
	v_fmac_f32_e32 v171, v84, v183
	v_fmac_f32_e32 v173, v81, v183
	v_fmac_f32_e32 v175, v85, v183
	v_fmac_f32_e32 v190, v82, v183
	v_fmac_f32_e32 v209, v86, v183
	v_fmac_f32_e32 v212, v83, v183
	v_fmac_f32_e32 v213, v87, v183
	s_waitcnt vmcnt(3)
	v_mov_b32_e32 v132, v142
	v_mov_b32_e32 v133, v144
	s_waitcnt vmcnt(2)
	v_mov_b32_e32 v134, v146
	v_mov_b32_e32 v135, v148
	s_waitcnt vmcnt(1)
	v_mov_b32_e32 v136, v150
	v_mov_b32_e32 v137, v152
	v_mov_b32_e32 v144, v143
	v_mov_b32_e32 v148, v147
	v_pk_mul_f32 v[130:131], v[130:131], v[132:133]
	v_pk_add_f32 v[132:133], v[134:135], 1.0 op_sel_hi:[1,0]
	v_mov_b32_e32 v152, v151
	v_pk_mul_f32 v[134:135], v[178:179], v[144:145]
	v_pk_add_f32 v[138:139], v[148:149], 1.0 op_sel_hi:[1,0]
	v_pk_fma_f32 v[130:131], v[130:131], v[132:133], v[136:137]
	v_pk_fma_f32 v[132:133], v[134:135], v[138:139], v[152:153]
	v_fmac_f32_e32 v160, v92, v130
	v_fmac_f32_e32 v160, v104, v132
	v_and_b32_sdwa v135, v130, v205 dst_sel:DWORD dst_unused:UNUSED_PAD src0_sel:WORD_1 src1_sel:DWORD
	v_and_b32_sdwa v136, v133, v205 dst_sel:DWORD dst_unused:UNUSED_PAD src0_sel:WORD_1 src1_sel:DWORD
	v_fmac_f32_e32 v160, v112, v131
	v_fmac_f32_e32 v171, v100, v130
	v_fmac_f32_e32 v173, v93, v130
	v_fmac_f32_e32 v175, v101, v130
	v_fmac_f32_e32 v190, v94, v130
	v_fmac_f32_e32 v209, v102, v130
	v_fmac_f32_e32 v212, v95, v130
	v_fmac_f32_e32 v213, v103, v130
	v_add3_u32 v146, v130, v135, s80
	v_add3_u32 v130, v133, v136, s80
	v_fmac_f32_e32 v160, v120, v133
	v_and_b32_e32 v149, 0xffff0000, v130
	ds_bpermute_b32 v130, v159, v160
	v_fmac_f32_e32 v173, v105, v132
	v_fmac_f32_e32 v173, v113, v131
	v_and_b32_sdwa v134, v131, v205 dst_sel:DWORD dst_unused:UNUSED_PAD src0_sel:WORD_1 src1_sel:DWORD
	v_fmac_f32_e32 v171, v108, v132
	v_fmac_f32_e32 v175, v109, v132
	v_fmac_f32_e32 v190, v106, v132
	v_fmac_f32_e32 v209, v110, v132
	v_fmac_f32_e32 v212, v107, v132
	v_fmac_f32_e32 v213, v111, v132
	v_fmac_f32_e32 v173, v121, v133
	v_add3_u32 v147, v131, v134, s80
	v_fmac_f32_e32 v171, v116, v131
	v_fmac_f32_e32 v175, v117, v131
	v_fmac_f32_e32 v190, v114, v131
	v_fmac_f32_e32 v209, v118, v131
	v_fmac_f32_e32 v212, v115, v131
	v_fmac_f32_e32 v213, v119, v131
	ds_bpermute_b32 v131, v159, v173
	s_waitcnt lgkmcnt(1)
; template <int MODE>
; __device__ __forceinline__ void norm_phase(const Params& p, const float* src, const float* w, const float* modl, int sh_off, int sc_off,
;                            char* smem, int bid, int nblk) {
;     ...
;     if (MODE == 1) {
; #pragma unroll
;       for (int j = 0; j < 8; ++j) {
; #pragma unroll
;         for (int o = 32; o >= 1; o >>= 1) dots[j] += __shfl_xor(dots[j], o);
;       }
;       if (lane == 0) {
	v_add_f32_e32 v130, v160, v130
	ds_bpermute_b32 v135, v191, v130
	v_and_b32_sdwa v137, v132, v205 dst_sel:DWORD dst_unused:UNUSED_PAD src0_sel:WORD_1 src1_sel:DWORD
	v_fmac_f32_e32 v190, v122, v133
	s_waitcnt lgkmcnt(1)
	v_add_f32_e32 v131, v173, v131
	v_add3_u32 v148, v132, v137, s80
	ds_bpermute_b32 v132, v159, v190
	ds_bpermute_b32 v136, v191, v131
	s_waitcnt lgkmcnt(2)
	v_add_f32_e32 v130, v130, v135
	ds_bpermute_b32 v135, v192, v130
	v_fmac_f32_e32 v212, v123, v133
	s_waitcnt lgkmcnt(2)
	v_add_f32_e32 v132, v190, v132
	s_waitcnt lgkmcnt(1)
	v_add_f32_e32 v131, v131, v136
	v_fmac_f32_e32 v171, v124, v133
	v_fmac_f32_e32 v175, v125, v133
	v_fmac_f32_e32 v209, v126, v133
	v_fmac_f32_e32 v213, v127, v133
	ds_bpermute_b32 v133, v159, v212
	ds_bpermute_b32 v137, v191, v132
	ds_bpermute_b32 v136, v192, v131
	s_waitcnt lgkmcnt(3)
	v_add_f32_e32 v130, v130, v135
	ds_bpermute_b32 v135, v193, v130
	s_waitcnt lgkmcnt(3)
	v_add_f32_e32 v133, v212, v133
	s_waitcnt lgkmcnt(2)
	v_add_f32_e32 v132, v132, v137
	s_waitcnt lgkmcnt(1)
	v_add_f32_e32 v131, v131, v136
	ds_bpermute_b32 v134, v159, v171
	ds_bpermute_b32 v138, v191, v133
	ds_bpermute_b32 v137, v192, v132
	ds_bpermute_b32 v136, v193, v131
	s_waitcnt lgkmcnt(4)
	v_add_f32_e32 v130, v130, v135
	ds_bpermute_b32 v135, v194, v130
	s_waitcnt lgkmcnt(4)
	v_add_f32_e32 v134, v171, v134
	s_waitcnt lgkmcnt(2)
	v_add_f32_e32 v132, v132, v137
	s_waitcnt lgkmcnt(1)
	v_add_f32_e32 v131, v131, v136
	v_add_f32_e32 v133, v133, v138
	ds_bpermute_b32 v139, v191, v134
	ds_bpermute_b32 v136, v194, v131
	s_waitcnt lgkmcnt(2)
	v_add_f32_e32 v143, v130, v135
	ds_bpermute_b32 v130, v193, v132
	ds_bpermute_b32 v135, v192, v133
	ds_bpermute_b32 v144, v195, v143
	s_waitcnt lgkmcnt(3)
	v_add_f32_e32 v142, v131, v136
	v_add_f32_e32 v131, v134, v139
	s_waitcnt lgkmcnt(2)
	v_add_f32_e32 v130, v132, v130
	s_waitcnt lgkmcnt(1)
	v_add_f32_e32 v132, v133, v135
	ds_bpermute_b32 v134, v192, v131
	ds_bpermute_b32 v133, v193, v132
	ds_bpermute_b32 v135, v194, v130
	ds_bpermute_b32 v145, v195, v142
	v_and_b32_e32 v148, 0xffff0000, v148
	s_waitcnt lgkmcnt(3)
	v_add_f32_e32 v131, v131, v134
	s_waitcnt lgkmcnt(2)
	v_add_f32_e32 v132, v132, v133
	ds_bpermute_b32 v134, v193, v131
	ds_bpermute_b32 v133, v194, v132
	s_waitcnt lgkmcnt(3)
	v_add_f32_e32 v140, v130, v135
	ds_bpermute_b32 v141, v195, v140
	v_or_b32_sdwa v147, v149, v147 dst_sel:DWORD dst_unused:UNUSED_PAD src0_sel:DWORD src1_sel:WORD_1
	s_waitcnt lgkmcnt(2)
	v_add_f32_e32 v130, v131, v134
	s_waitcnt lgkmcnt(1)
	v_add_f32_e32 v138, v132, v133
	ds_bpermute_b32 v132, v159, v175
	ds_bpermute_b32 v133, v159, v209
	ds_bpermute_b32 v134, v159, v213
	ds_bpermute_b32 v131, v194, v130
	ds_bpermute_b32 v139, v195, v138
	s_waitcnt lgkmcnt(4)
	v_add_f32_e32 v132, v175, v132
	s_waitcnt lgkmcnt(3)
	v_add_f32_e32 v133, v209, v133
	s_waitcnt lgkmcnt(2)
	v_add_f32_e32 v134, v213, v134
	ds_bpermute_b32 v135, v191, v132
	ds_bpermute_b32 v136, v191, v133
	ds_bpermute_b32 v137, v191, v134
	s_waitcnt lgkmcnt(4)
	v_add_f32_e32 v130, v130, v131
	ds_bpermute_b32 v131, v195, v130
	s_waitcnt lgkmcnt(3)
	v_add_f32_e32 v132, v132, v135
	s_waitcnt lgkmcnt(2)
	v_add_f32_e32 v133, v133, v136
	s_waitcnt lgkmcnt(1)
	v_add_f32_e32 v134, v134, v137
	ds_bpermute_b32 v135, v192, v132
	ds_bpermute_b32 v136, v192, v133
	ds_bpermute_b32 v137, v192, v134
	v_or_b32_sdwa v146, v148, v146 dst_sel:DWORD dst_unused:UNUSED_PAD src0_sel:DWORD src1_sel:WORD_1
	global_store_dwordx2 v[128:129], v[146:147], off
	s_waitcnt lgkmcnt(2)
	v_add_f32_e32 v132, v132, v135
	s_waitcnt lgkmcnt(1)
	v_add_f32_e32 v133, v133, v136
	s_waitcnt lgkmcnt(0)
	v_add_f32_e32 v134, v134, v137
	ds_bpermute_b32 v135, v193, v132
	ds_bpermute_b32 v136, v193, v133
	ds_bpermute_b32 v137, v193, v134
	s_waitcnt lgkmcnt(2)
	v_add_f32_e32 v132, v132, v135
	s_waitcnt lgkmcnt(1)
	v_add_f32_e32 v136, v133, v136
	s_waitcnt lgkmcnt(0)
	v_add_f32_e32 v134, v134, v137
	ds_bpermute_b32 v135, v194, v132
	ds_bpermute_b32 v150, v194, v136
	ds_bpermute_b32 v151, v194, v134
	s_waitcnt lgkmcnt(2)
	v_add_f32_e32 v132, v132, v135
	s_waitcnt lgkmcnt(1)
	v_add_f32_e32 v136, v136, v150
	s_waitcnt lgkmcnt(0)
	v_add_f32_e32 v134, v134, v151
	ds_bpermute_b32 v133, v195, v132
	ds_bpermute_b32 v137, v195, v136
	ds_bpermute_b32 v135, v195, v134
	s_and_b64 exec, exec, vcc
	s_cbranch_execz .LBB0_98
; __device__ __forceinline__ float sigmoid_(float x) { return __builtin_amdgcn_rcpf(1.f + __expf(-x)); }
; __device__ __forceinline__ float softplus_(float x) { return fmaxf(x, 0.f) + log1pf(__expf(-fabsf(x))); }
; template <int MODE>
; __device__ __forceinline__ void norm_phase(const Params& p, const float* src, const float* w, const float* modl, int sh_off, int sc_off,
;                            char* smem, int bid, int nblk) {
;     ...
;         float* beta = (float*)(p.ws + OFF_BETA); float* gg = (float*)(p.ws + OFF_G);
; #pragma unroll
;         for (int h = 0; h < 4; ++h) {
;           beta[(size_t)row * 4 + h] = sigmoid_(dots[h]);
;           gg[(size_t)row * 4 + h] = -__expf(p.hy_a_log[h]) * softplus_(dots[4 + h] + p.hy_dt_bias[h]);
;         }
	v_add_f32_e32 v128, v143, v144
	v_mul_f32_e32 v128, 0xbfb8aa3b, v128
	v_exp_f32_e32 v128, v128
	v_add_f32_e32 v142, v142, v145
	v_mul_f32_e32 v142, 0xbfb8aa3b, v142
	v_exp_f32_e32 v144, v142
	v_add_f32_e32 v128, 1.0, v128
	v_rcp_f32_e32 v143, v128
	v_lshlrev_b64 v[128:129], 4, v[176:177]
	v_lshl_add_u64 v[146:147], s[10:11], 0, v[128:129]
	v_add_f32_e32 v148, v130, v131
	global_store_dword v[146:147], v143, off
	global_load_dword v146, v161, s[58:59]
	s_nop 0
	global_load_dword v147, v161, s[56:57]
	v_add_f32_e32 v130, 1.0, v144
	v_rcp_f32_e32 v149, v130
	v_or_b32_e32 v130, 4, v128
	v_mov_b32_e32 v131, v129
	v_lshl_add_u64 v[144:145], s[10:11], 0, v[130:131]
	global_store_dword v[144:145], v149, off
	v_lshl_add_u64 v[142:143], s[12:13], 0, v[128:129]
	v_add_f32_e32 v140, v140, v141
	v_mul_f32_e32 v140, 0xbfb8aa3b, v140
	v_exp_f32_e32 v140, v140
	v_lshl_add_u64 v[130:131], s[12:13], 0, v[130:131]
	s_waitcnt lgkmcnt(1)
	v_add_f32_e32 v136, v136, v137
	s_waitcnt vmcnt(2)
	v_add_f32_e32 v144, v148, v146
	v_mul_f32_e64 v145, |v144|, s81
	v_exp_f32_e32 v146, v145
	s_waitcnt vmcnt(1)
	v_mul_f32_e32 v145, 0x3fb8aa3b, v147
	v_exp_f32_e32 v147, v145
	v_max_f32_e32 v148, 0, v144
	v_add_f32_e32 v149, 1.0, v146
	v_add_f32_e32 v150, -1.0, v149
	v_frexp_mant_f32_e32 v151, v149
	v_cvt_f64_f32_e32 v[144:145], v149
	v_sub_f32_e32 v152, v150, v149
	v_frexp_exp_i32_f64_e32 v144, v[144:145]
	v_cmp_gt_f32_e64 s[0:1], s82, v151
	v_sub_f32_e32 v150, v146, v150
	v_add_f32_e32 v145, 1.0, v152
	v_subbrev_co_u32_e64 v144, s[0:1], 0, v144, s[0:1]
	v_add_f32_e32 v145, v150, v145
	v_sub_u32_e32 v150, 0, v144
	v_cvt_f32_i32_e32 v144, v144
	v_ldexp_f32 v149, v149, v150
	v_ldexp_f32 v145, v145, v150
	v_add_f32_e32 v150, -1.0, v149
	v_add_f32_e32 v151, 1.0, v149
	v_add_f32_e32 v152, 1.0, v150
	v_add_f32_e32 v153, -1.0, v151
	v_sub_f32_e32 v152, v149, v152
	v_sub_f32_e32 v149, v149, v153
	v_mul_f32_e32 v153, 0x3f317218, v144
	v_add_f32_e32 v152, v145, v152
	v_add_f32_e32 v145, v145, v149
	v_fma_f32 v149, v144, s83, -v153
	v_add_f32_e32 v154, v150, v152
	v_add_f32_e32 v155, v151, v145
	v_fmac_f32_e32 v149, 0xb102e308, v144
	v_sub_f32_e32 v144, v154, v150
	v_sub_f32_e32 v150, v155, v151
	v_rcp_f32_e32 v151, v155
	v_add_f32_e32 v160, v153, v149
	v_sub_f32_e32 v145, v145, v150
	v_sub_f32_e32 v150, v160, v153
	v_sub_f32_e32 v149, v149, v150
	v_mul_f32_e32 v150, v154, v151
	v_sub_f32_e32 v144, v152, v144
	v_mul_f32_e32 v152, v155, v150
	v_fma_f32 v153, v150, v155, -v152
	v_fmac_f32_e32 v153, v150, v145
	v_add_f32_e32 v171, v152, v153
	v_sub_f32_e32 v173, v154, v171
	v_sub_f32_e32 v152, v171, v152
	v_sub_f32_e32 v154, v154, v173
	v_sub_f32_e32 v152, v152, v153
	v_sub_f32_e32 v153, v154, v171
	v_add_f32_e32 v144, v144, v153
	v_add_f32_e32 v144, v152, v144
	v_add_f32_e32 v152, v173, v144
	v_mul_f32_e32 v153, v151, v152
	v_sub_f32_e32 v154, v173, v152
	v_mul_f32_e32 v171, v155, v153
	v_add_f32_e32 v144, v144, v154
	v_add_f32_e32 v154, v150, v153
	v_fma_f32 v155, v153, v155, -v171
	v_sub_f32_e32 v150, v154, v150
	v_fmac_f32_e32 v155, v153, v145
	v_sub_f32_e32 v145, v153, v150
	v_add_f32_e32 v150, v171, v155
	v_sub_f32_e32 v153, v150, v171
	v_sub_f32_e32 v171, v152, v150
	v_sub_f32_e32 v152, v152, v171
	v_sub_f32_e32 v150, v152, v150
	v_sub_f32_e32 v153, v153, v155
	v_add_f32_e32 v144, v144, v150
	v_add_f32_e32 v144, v153, v144
	v_add_f32_e32 v144, v171, v144
	v_mul_f32_e32 v144, v151, v144
	v_add_f32_e32 v144, v145, v144
	v_add_f32_e32 v145, v154, v144
	v_mul_f32_e32 v150, v145, v145
	v_fmamk_f32 v153, v150, 0x3e9b6dac, v204
	v_sub_f32_e32 v151, v145, v154
	v_ldexp_f32 v152, v145, 1
	v_mul_f32_e32 v145, v145, v150
	v_fmaak_f32 v150, v150, v153, 0x3f2aaada
	v_mul_f32_e32 v145, v145, v150
	v_add_f32_e32 v150, v152, v145
	v_sub_f32_e32 v144, v144, v151
	v_sub_f32_e32 v151, v150, v152
	v_ldexp_f32 v144, v144, 1
	v_sub_f32_e32 v145, v145, v151
	v_add_f32_e32 v144, v144, v145
	v_add_f32_e32 v145, v150, v144
	v_sub_f32_e32 v150, v145, v150
	v_add_f32_e32 v151, v160, v145
	v_sub_f32_e32 v144, v144, v150
	v_sub_f32_e32 v150, v151, v160
	v_sub_f32_e32 v152, v151, v150
	v_sub_f32_e32 v145, v145, v150
	v_add_f32_e32 v150, v149, v144
	v_sub_f32_e32 v152, v160, v152
	v_sub_f32_e32 v153, v150, v149
	v_add_f32_e32 v145, v145, v152
	v_sub_f32_e32 v152, v150, v153
	v_sub_f32_e32 v144, v144, v153
	v_sub_f32_e32 v149, v149, v152
	v_add_f32_e32 v145, v150, v145
	v_add_f32_e32 v144, v144, v149
	v_add_f32_e32 v149, v151, v145
	v_sub_f32_e32 v150, v149, v151
	v_sub_f32_e32 v145, v145, v150
	v_add_f32_e32 v144, v144, v145
	v_add_f32_e32 v144, v149, v144
	v_cmp_neq_f32_e64 s[0:1], s84, v146
	s_nop 1
	v_cndmask_b32_e64 v144, v206, v144, s[0:1]
	v_cmp_ngt_f32_e64 s[0:1], -1.0, v146
	s_nop 1
	v_cndmask_b32_e64 v144, v207, v144, s[0:1]
	v_cmp_neq_f32_e64 s[0:1], -1.0, v146
	s_nop 1
	v_cndmask_b32_e64 v144, v208, v144, s[0:1]
	v_cmp_lt_f32_e64 s[0:1], |v146|, s85
	s_nop 1
	v_cndmask_b32_e64 v144, v144, v146, s[0:1]
	v_add_f32_e32 v144, v148, v144
	v_mul_f32_e64 v144, v144, -v147
	global_store_dword v[142:143], v144, off
	global_load_dword v142, v161, s[58:59] offset:4
	s_nop 0
	global_load_dword v143, v161, s[56:57] offset:4
	v_add_f32_e32 v144, v132, v133
	v_add_f32_e32 v133, 1.0, v140
	v_rcp_f32_e32 v145, v133
	v_or_b32_e32 v132, 8, v128
	v_mov_b32_e32 v133, v129
	v_lshl_add_u64 v[140:141], s[10:11], 0, v[132:133]
	global_store_dword v[140:141], v145, off
	v_or_b32_e32 v128, 12, v128
	s_waitcnt vmcnt(2)
	v_add_f32_e32 v140, v144, v142
	v_mul_f32_e64 v141, |v140|, s81
	v_exp_f32_e32 v142, v141
	s_waitcnt vmcnt(1)
; __device__ __forceinline__ float sigmoid_(float x) { return __builtin_amdgcn_rcpf(1.f + __expf(-x)); }
; __device__ __forceinline__ float softplus_(float x) { return fmaxf(x, 0.f) + log1pf(__expf(-fabsf(x))); }
; template <int MODE>
; __device__ __forceinline__ void norm_phase(const Params& p, const float* src, const float* w, const float* modl, int sh_off, int sc_off,
;                            char* smem, int bid, int nblk) {
;     ...
;           beta[(size_t)row * 4 + h] = sigmoid_(dots[h]);
;           gg[(size_t)row * 4 + h] = -__expf(p.hy_a_log[h]) * softplus_(dots[4 + h] + p.hy_dt_bias[h]);
;         }
	v_mul_f32_e32 v141, 0x3fb8aa3b, v143
	v_exp_f32_e32 v143, v141
	v_max_f32_e32 v144, 0, v140
	v_add_f32_e32 v145, 1.0, v142
	v_add_f32_e32 v146, -1.0, v145
	v_frexp_mant_f32_e32 v147, v145
	v_cvt_f64_f32_e32 v[140:141], v145
	v_sub_f32_e32 v148, v146, v145
	v_frexp_exp_i32_f64_e32 v140, v[140:141]
	v_cmp_gt_f32_e64 s[0:1], s82, v147
	v_sub_f32_e32 v146, v142, v146
	v_add_f32_e32 v141, 1.0, v148
	v_subbrev_co_u32_e64 v140, s[0:1], 0, v140, s[0:1]
	v_add_f32_e32 v141, v146, v141
	v_sub_u32_e32 v146, 0, v140
	v_cvt_f32_i32_e32 v140, v140
	v_ldexp_f32 v145, v145, v146
	v_ldexp_f32 v141, v141, v146
	v_add_f32_e32 v146, -1.0, v145
	v_add_f32_e32 v147, 1.0, v145
	v_add_f32_e32 v148, 1.0, v146
	v_add_f32_e32 v149, -1.0, v147
	v_sub_f32_e32 v148, v145, v148
	v_sub_f32_e32 v145, v145, v149
	v_mul_f32_e32 v149, 0x3f317218, v140
	v_add_f32_e32 v148, v141, v148
	v_add_f32_e32 v141, v141, v145
	v_fma_f32 v145, v140, s83, -v149
	v_add_f32_e32 v150, v146, v148
	v_add_f32_e32 v151, v147, v141
	v_fmac_f32_e32 v145, 0xb102e308, v140
	v_sub_f32_e32 v140, v150, v146
	v_sub_f32_e32 v146, v151, v147
	v_rcp_f32_e32 v147, v151
	v_add_f32_e32 v152, v149, v145
	v_sub_f32_e32 v141, v141, v146
	v_sub_f32_e32 v146, v152, v149
	v_sub_f32_e32 v145, v145, v146
	v_mul_f32_e32 v146, v150, v147
	v_sub_f32_e32 v140, v148, v140
	v_mul_f32_e32 v148, v151, v146
	v_fma_f32 v149, v146, v151, -v148
	v_fmac_f32_e32 v149, v146, v141
	v_add_f32_e32 v153, v148, v149
	v_sub_f32_e32 v154, v150, v153
	v_sub_f32_e32 v148, v153, v148
	v_sub_f32_e32 v150, v150, v154
	v_sub_f32_e32 v148, v148, v149
	v_sub_f32_e32 v149, v150, v153
	v_add_f32_e32 v140, v140, v149
	v_add_f32_e32 v140, v148, v140
	v_add_f32_e32 v148, v154, v140
	v_mul_f32_e32 v149, v147, v148
	v_sub_f32_e32 v150, v154, v148
	v_mul_f32_e32 v153, v151, v149
	v_add_f32_e32 v140, v140, v150
	v_add_f32_e32 v150, v146, v149
	v_fma_f32 v151, v149, v151, -v153
	v_sub_f32_e32 v146, v150, v146
	v_fmac_f32_e32 v151, v149, v141
	v_sub_f32_e32 v141, v149, v146
	v_add_f32_e32 v146, v153, v151
	v_sub_f32_e32 v149, v146, v153
	v_sub_f32_e32 v153, v148, v146
	v_sub_f32_e32 v148, v148, v153
	v_sub_f32_e32 v146, v148, v146
	v_sub_f32_e32 v149, v149, v151
	v_add_f32_e32 v140, v140, v146
	v_add_f32_e32 v140, v149, v140
	v_add_f32_e32 v140, v153, v140
	v_mul_f32_e32 v140, v147, v140
	v_add_f32_e32 v140, v141, v140
	v_add_f32_e32 v141, v150, v140
	v_mul_f32_e32 v146, v141, v141
	v_fmamk_f32 v149, v146, 0x3e9b6dac, v204
	v_sub_f32_e32 v147, v141, v150
	v_ldexp_f32 v148, v141, 1
	v_mul_f32_e32 v141, v141, v146
	v_fmaak_f32 v146, v146, v149, 0x3f2aaada
	v_mul_f32_e32 v141, v141, v146
	v_add_f32_e32 v146, v148, v141
	v_sub_f32_e32 v140, v140, v147
	v_sub_f32_e32 v147, v146, v148
	v_ldexp_f32 v140, v140, 1
	v_sub_f32_e32 v141, v141, v147
	v_add_f32_e32 v140, v140, v141
	v_add_f32_e32 v141, v146, v140
	v_sub_f32_e32 v146, v141, v146
	v_add_f32_e32 v147, v152, v141
	v_sub_f32_e32 v140, v140, v146
	v_sub_f32_e32 v146, v147, v152
	v_sub_f32_e32 v148, v147, v146
	v_sub_f32_e32 v141, v141, v146
	v_add_f32_e32 v146, v145, v140
	v_sub_f32_e32 v148, v152, v148
	v_sub_f32_e32 v149, v146, v145
	v_add_f32_e32 v141, v141, v148
	v_sub_f32_e32 v148, v146, v149
	v_sub_f32_e32 v140, v140, v149
	v_sub_f32_e32 v145, v145, v148
	v_add_f32_e32 v141, v146, v141
	v_add_f32_e32 v140, v140, v145
	v_add_f32_e32 v145, v147, v141
	v_sub_f32_e32 v146, v145, v147
	v_sub_f32_e32 v141, v141, v146
	v_add_f32_e32 v140, v140, v141
	v_add_f32_e32 v140, v145, v140
	v_cmp_neq_f32_e64 s[0:1], s84, v142
	s_nop 1
	v_cndmask_b32_e64 v140, v206, v140, s[0:1]
	v_cmp_ngt_f32_e64 s[0:1], -1.0, v142
	s_nop 1
	v_cndmask_b32_e64 v140, v207, v140, s[0:1]
	v_cmp_neq_f32_e64 s[0:1], -1.0, v142
	s_nop 1
	v_cndmask_b32_e64 v140, v208, v140, s[0:1]
	v_cmp_lt_f32_e64 s[0:1], |v142|, s85
	s_nop 1
	v_cndmask_b32_e64 v140, v140, v142, s[0:1]
	v_add_f32_e32 v140, v144, v140
	v_mul_f32_e64 v140, v140, -v143
	global_store_dword v[130:131], v140, off
	global_load_dword v140, v161, s[58:59] offset:8
	s_nop 0
	global_load_dword v141, v161, s[56:57] offset:8
	v_add_f32_e32 v130, v138, v139
	v_mul_f32_e32 v130, 0xbfb8aa3b, v130
	v_exp_f32_e32 v130, v130
	s_nop 0
	v_add_f32_e32 v130, 1.0, v130
	v_rcp_f32_e32 v137, v130
	v_lshl_add_u64 v[130:131], s[12:13], 0, v[132:133]
	v_lshl_add_u64 v[132:133], s[10:11], 0, v[128:129]
	v_lshl_add_u64 v[128:129], s[12:13], 0, v[128:129]
	global_store_dword v[132:133], v137, off
	s_waitcnt vmcnt(2)
	v_add_f32_e32 v132, v136, v140
	v_mul_f32_e64 v133, |v132|, s81
	v_exp_f32_e32 v136, v133
	s_waitcnt vmcnt(1)
; __device__ __forceinline__ float sigmoid_(float x) { return __builtin_amdgcn_rcpf(1.f + __expf(-x)); }
; __device__ __forceinline__ float softplus_(float x) { return fmaxf(x, 0.f) + log1pf(__expf(-fabsf(x))); }
; template <int MODE>
; __device__ __forceinline__ void norm_phase(const Params& p, const float* src, const float* w, const float* modl, int sh_off, int sc_off,
;                            char* smem, int bid, int nblk) {
;     ...
;         float* beta = (float*)(p.ws + OFF_BETA); float* gg = (float*)(p.ws + OFF_G);
; #pragma unroll
;         for (int h = 0; h < 4; ++h) {
;           beta[(size_t)row * 4 + h] = sigmoid_(dots[h]);
;           gg[(size_t)row * 4 + h] = -__expf(p.hy_a_log[h]) * softplus_(dots[4 + h] + p.hy_dt_bias[h]);
;         }
	v_mul_f32_e32 v133, 0x3fb8aa3b, v141
	v_exp_f32_e32 v137, v133
	v_max_f32_e32 v138, 0, v132
	v_add_f32_e32 v139, 1.0, v136
	v_add_f32_e32 v140, -1.0, v139
	v_frexp_mant_f32_e32 v141, v139
	v_cvt_f64_f32_e32 v[132:133], v139
	v_sub_f32_e32 v142, v140, v139
	v_frexp_exp_i32_f64_e32 v132, v[132:133]
	v_cmp_gt_f32_e64 s[0:1], s82, v141
	v_sub_f32_e32 v140, v136, v140
	v_add_f32_e32 v133, 1.0, v142
	v_subbrev_co_u32_e64 v132, s[0:1], 0, v132, s[0:1]
	v_add_f32_e32 v133, v140, v133
	v_sub_u32_e32 v140, 0, v132
	v_cvt_f32_i32_e32 v132, v132
	v_ldexp_f32 v139, v139, v140
	v_ldexp_f32 v133, v133, v140
	v_add_f32_e32 v140, -1.0, v139
	v_add_f32_e32 v141, 1.0, v139
	v_add_f32_e32 v142, 1.0, v140
	v_add_f32_e32 v143, -1.0, v141
	v_sub_f32_e32 v142, v139, v142
	v_sub_f32_e32 v139, v139, v143
	v_mul_f32_e32 v143, 0x3f317218, v132
	v_add_f32_e32 v142, v133, v142
	v_add_f32_e32 v133, v133, v139
	v_fma_f32 v139, v132, s83, -v143
	v_add_f32_e32 v144, v140, v142
	v_add_f32_e32 v145, v141, v133
	v_fmac_f32_e32 v139, 0xb102e308, v132
	v_sub_f32_e32 v132, v144, v140
	v_sub_f32_e32 v140, v145, v141
	v_rcp_f32_e32 v141, v145
	v_add_f32_e32 v146, v143, v139
	v_sub_f32_e32 v133, v133, v140
	v_sub_f32_e32 v140, v146, v143
	v_sub_f32_e32 v139, v139, v140
	v_mul_f32_e32 v140, v144, v141
	v_sub_f32_e32 v132, v142, v132
	v_mul_f32_e32 v142, v145, v140
	v_fma_f32 v143, v140, v145, -v142
	v_fmac_f32_e32 v143, v140, v133
	v_add_f32_e32 v147, v142, v143
	v_sub_f32_e32 v148, v144, v147
	v_sub_f32_e32 v142, v147, v142
	v_sub_f32_e32 v144, v144, v148
	v_sub_f32_e32 v142, v142, v143
	v_sub_f32_e32 v143, v144, v147
	v_add_f32_e32 v132, v132, v143
	v_add_f32_e32 v132, v142, v132
	v_add_f32_e32 v142, v148, v132
	v_mul_f32_e32 v143, v141, v142
	v_sub_f32_e32 v144, v148, v142
	v_mul_f32_e32 v147, v145, v143
	v_add_f32_e32 v132, v132, v144
	v_add_f32_e32 v144, v140, v143
	v_fma_f32 v145, v143, v145, -v147
	v_sub_f32_e32 v140, v144, v140
	v_fmac_f32_e32 v145, v143, v133
	v_sub_f32_e32 v133, v143, v140
	v_add_f32_e32 v140, v147, v145
	v_sub_f32_e32 v143, v140, v147
	v_sub_f32_e32 v147, v142, v140
	v_sub_f32_e32 v142, v142, v147
	v_sub_f32_e32 v140, v142, v140
	v_sub_f32_e32 v143, v143, v145
	v_add_f32_e32 v132, v132, v140
	v_add_f32_e32 v132, v143, v132
	v_add_f32_e32 v132, v147, v132
	v_mul_f32_e32 v132, v141, v132
	v_add_f32_e32 v132, v133, v132
	v_add_f32_e32 v133, v144, v132
	v_mul_f32_e32 v140, v133, v133
	v_fmamk_f32 v143, v140, 0x3e9b6dac, v204
	v_sub_f32_e32 v141, v133, v144
	v_ldexp_f32 v142, v133, 1
	v_mul_f32_e32 v133, v133, v140
	v_fmaak_f32 v140, v140, v143, 0x3f2aaada
	v_mul_f32_e32 v133, v133, v140
	v_add_f32_e32 v140, v142, v133
	v_sub_f32_e32 v132, v132, v141
	v_sub_f32_e32 v141, v140, v142
	v_ldexp_f32 v132, v132, 1
	v_sub_f32_e32 v133, v133, v141
	v_add_f32_e32 v132, v132, v133
	v_add_f32_e32 v133, v140, v132
	v_sub_f32_e32 v140, v133, v140
	v_add_f32_e32 v141, v146, v133
	v_sub_f32_e32 v132, v132, v140
	v_sub_f32_e32 v140, v141, v146
	v_sub_f32_e32 v142, v141, v140
	v_sub_f32_e32 v133, v133, v140
	v_add_f32_e32 v140, v139, v132
	v_sub_f32_e32 v142, v146, v142
	v_sub_f32_e32 v143, v140, v139
	v_add_f32_e32 v133, v133, v142
	v_sub_f32_e32 v142, v140, v143
	v_sub_f32_e32 v132, v132, v143
	v_sub_f32_e32 v139, v139, v142
	v_add_f32_e32 v133, v140, v133
	v_add_f32_e32 v132, v132, v139
	v_add_f32_e32 v139, v141, v133
	v_sub_f32_e32 v140, v139, v141
	v_sub_f32_e32 v133, v133, v140
	v_add_f32_e32 v132, v132, v133
	v_add_f32_e32 v132, v139, v132
	v_cmp_neq_f32_e64 s[0:1], s84, v136
	s_nop 1
	v_cndmask_b32_e64 v132, v206, v132, s[0:1]
	v_cmp_ngt_f32_e64 s[0:1], -1.0, v136
	s_nop 1
	v_cndmask_b32_e64 v132, v207, v132, s[0:1]
	v_cmp_neq_f32_e64 s[0:1], -1.0, v136
	s_nop 1
	v_cndmask_b32_e64 v132, v208, v132, s[0:1]
	v_cmp_lt_f32_e64 s[0:1], |v136|, s85
	s_nop 1
	v_cndmask_b32_e64 v132, v132, v136, s[0:1]
	v_add_f32_e32 v132, v138, v132
	v_mul_f32_e64 v132, v132, -v137
	global_store_dword v[130:131], v132, off
	global_load_dword v130, v161, s[58:59] offset:12
	s_nop 0
	global_load_dword v131, v161, s[56:57] offset:12
	s_waitcnt lgkmcnt(0)
; __device__ __forceinline__ float sigmoid_(float x) { return __builtin_amdgcn_rcpf(1.f + __expf(-x)); }
; __device__ __forceinline__ float softplus_(float x) { return fmaxf(x, 0.f) + log1pf(__expf(-fabsf(x))); }
; template <int MODE>
; __device__ __forceinline__ void norm_phase(const Params& p, const float* src, const float* w, const float* modl, int sh_off, int sc_off,
;                            char* smem, int bid, int nblk) {
;     ...
;         float* beta = (float*)(p.ws + OFF_BETA); float* gg = (float*)(p.ws + OFF_G);
; #pragma unroll
;         for (int h = 0; h < 4; ++h) {
;           beta[(size_t)row * 4 + h] = sigmoid_(dots[h]);
;           gg[(size_t)row * 4 + h] = -__expf(p.hy_a_log[h]) * softplus_(dots[4 + h] + p.hy_dt_bias[h]);
;         }
	v_add_f32_e32 v132, v134, v135
	s_waitcnt vmcnt(1)
	v_add_f32_e32 v130, v132, v130
	v_mul_f32_e64 v132, |v130|, s81
	v_exp_f32_e32 v132, v132
	s_waitcnt vmcnt(0)
	v_mul_f32_e32 v131, 0x3fb8aa3b, v131
	v_exp_f32_e32 v133, v131
	v_max_f32_e32 v134, 0, v130
	v_add_f32_e32 v135, 1.0, v132
	v_add_f32_e32 v136, -1.0, v135
	v_frexp_mant_f32_e32 v137, v135
	v_cvt_f64_f32_e32 v[130:131], v135
	v_sub_f32_e32 v138, v136, v135
	v_frexp_exp_i32_f64_e32 v130, v[130:131]
	v_cmp_gt_f32_e64 s[0:1], s82, v137
	v_sub_f32_e32 v136, v132, v136
	v_add_f32_e32 v131, 1.0, v138
	v_subbrev_co_u32_e64 v130, s[0:1], 0, v130, s[0:1]
	v_add_f32_e32 v131, v136, v131
	v_sub_u32_e32 v136, 0, v130
	v_cvt_f32_i32_e32 v130, v130
	v_ldexp_f32 v135, v135, v136
	v_ldexp_f32 v131, v131, v136
	v_add_f32_e32 v136, -1.0, v135
	v_add_f32_e32 v137, 1.0, v135
	v_add_f32_e32 v138, 1.0, v136
	v_add_f32_e32 v139, -1.0, v137
	v_sub_f32_e32 v138, v135, v138
	v_sub_f32_e32 v135, v135, v139
	v_mul_f32_e32 v139, 0x3f317218, v130
	v_add_f32_e32 v138, v131, v138
	v_add_f32_e32 v131, v131, v135
	v_fma_f32 v135, v130, s83, -v139
	v_add_f32_e32 v140, v136, v138
	v_add_f32_e32 v141, v137, v131
	v_fmac_f32_e32 v135, 0xb102e308, v130
	v_sub_f32_e32 v130, v140, v136
	v_sub_f32_e32 v136, v141, v137
	v_rcp_f32_e32 v137, v141
	v_add_f32_e32 v142, v139, v135
	v_sub_f32_e32 v131, v131, v136
	v_sub_f32_e32 v136, v142, v139
	v_sub_f32_e32 v135, v135, v136
	v_mul_f32_e32 v136, v140, v137
	v_sub_f32_e32 v130, v138, v130
	v_mul_f32_e32 v138, v141, v136
	v_fma_f32 v139, v136, v141, -v138
	v_fmac_f32_e32 v139, v136, v131
	v_add_f32_e32 v143, v138, v139
	v_sub_f32_e32 v144, v140, v143
	v_sub_f32_e32 v138, v143, v138
	v_sub_f32_e32 v140, v140, v144
	v_sub_f32_e32 v138, v138, v139
	v_sub_f32_e32 v139, v140, v143
	v_add_f32_e32 v130, v130, v139
	v_add_f32_e32 v130, v138, v130
	v_add_f32_e32 v138, v144, v130
	v_mul_f32_e32 v139, v137, v138
	v_sub_f32_e32 v140, v144, v138
	v_mul_f32_e32 v143, v141, v139
	v_add_f32_e32 v130, v130, v140
	v_add_f32_e32 v140, v136, v139
	v_fma_f32 v141, v139, v141, -v143
	v_sub_f32_e32 v136, v140, v136
	v_fmac_f32_e32 v141, v139, v131
	v_sub_f32_e32 v131, v139, v136
	v_add_f32_e32 v136, v143, v141
	v_sub_f32_e32 v139, v136, v143
	v_sub_f32_e32 v143, v138, v136
	v_sub_f32_e32 v138, v138, v143
	v_sub_f32_e32 v136, v138, v136
	v_sub_f32_e32 v139, v139, v141
	v_add_f32_e32 v130, v130, v136
	v_add_f32_e32 v130, v139, v130
	v_add_f32_e32 v130, v143, v130
	v_mul_f32_e32 v130, v137, v130
	v_add_f32_e32 v130, v131, v130
	v_add_f32_e32 v131, v140, v130
	v_mul_f32_e32 v136, v131, v131
	v_fmamk_f32 v139, v136, 0x3e9b6dac, v204
	v_sub_f32_e32 v137, v131, v140
	v_ldexp_f32 v138, v131, 1
	v_mul_f32_e32 v131, v131, v136
	v_fmaak_f32 v136, v136, v139, 0x3f2aaada
	v_mul_f32_e32 v131, v131, v136
	v_add_f32_e32 v136, v138, v131
	v_sub_f32_e32 v130, v130, v137
	v_sub_f32_e32 v137, v136, v138
	v_ldexp_f32 v130, v130, 1
	v_sub_f32_e32 v131, v131, v137
	v_add_f32_e32 v130, v130, v131
	v_add_f32_e32 v131, v136, v130
	v_sub_f32_e32 v136, v131, v136
	v_add_f32_e32 v137, v142, v131
	v_sub_f32_e32 v130, v130, v136
	v_sub_f32_e32 v136, v137, v142
	v_sub_f32_e32 v138, v137, v136
	v_sub_f32_e32 v131, v131, v136
	v_add_f32_e32 v136, v135, v130
	v_sub_f32_e32 v138, v142, v138
	v_sub_f32_e32 v139, v136, v135
	v_add_f32_e32 v131, v131, v138
	v_sub_f32_e32 v138, v136, v139
	v_sub_f32_e32 v130, v130, v139
	v_sub_f32_e32 v135, v135, v138
	v_add_f32_e32 v131, v136, v131
	v_add_f32_e32 v130, v130, v135
	v_add_f32_e32 v135, v137, v131
	v_sub_f32_e32 v136, v135, v137
	v_sub_f32_e32 v131, v131, v136
	v_add_f32_e32 v130, v130, v131
	v_add_f32_e32 v130, v135, v130
	v_cmp_neq_f32_e64 s[0:1], s84, v132
	s_nop 1
	v_cndmask_b32_e64 v130, v206, v130, s[0:1]
	v_cmp_ngt_f32_e64 s[0:1], -1.0, v132
	s_nop 1
	v_cndmask_b32_e64 v130, v207, v130, s[0:1]
	v_cmp_neq_f32_e64 s[0:1], -1.0, v132
	s_nop 1
	v_cndmask_b32_e64 v130, v208, v130, s[0:1]
	v_cmp_lt_f32_e64 s[0:1], |v132|, s85
	s_nop 1
	v_cndmask_b32_e64 v130, v130, v132, s[0:1]
	v_add_f32_e32 v130, v134, v130
	v_mul_f32_e64 v130, v130, -v133
	global_store_dword v[128:129], v130, off
	s_branch .LBB0_98

; __device__ __forceinline__ u16 f2bf(float x) { unsigned u = __float_as_uint(x); u += 0x7fffu + ((u >> 16) & 1u); return (u16)(u >> 16); }
; __device__ __forceinline__ size_t a_off(int row, int col, int nks) { return ((size_t)((row >> 8) * nks + (col >> 5)) << 13) + ((row & 255) << 5) + swzc(row, col & 31); }
; template <int MODE>
; __device__ __forceinline__ void norm_phase(const Params& p, const float* src, const float* w, const float* modl, int sh_off, int sc_off,
;                            char* smem, int bid, int nblk) {
;     ...
;     float ss = 0.f;
; #pragma unroll
;     for (int i = 0; i < 4; ++i) ss += v[i][0] * v[i][0] + v[i][1] * v[i][1] + v[i][2] * v[i][2] + v[i][3] * v[i][3];
; #pragma unroll
;     for (int o = 32; o >= 1; o >>= 1) ss += __shfl_xor(ss, o);
;     const float rstd = rsqrtf(ss * (1.f / 1024.f) + 1e-6f);
;     const int b = row >> 13;
;     float dots[8];
;     if (MODE == 1) { for (int j = 0; j < 8; ++j) dots[j] = 0.f; }
; #pragma unroll
;     for (int i = 0; i < 4; ++i) {
;       const int c0 = i * 256 + lane * 4;
;       f32x4 ww = *(const f32x4*)(w + c0);
;       f32x4 y;
;       if (MODE == 2) {
; #pragma unroll
;         for (int e = 0; e < 4; ++e) y[e] = v[i][e] * rstd * ww[e];
;         *(f32x4*)(p.out + (size_t)row * 1024 + c0) = y;
;       } else {
;         f32x4 sc = *(const f32x4*)(modl + (size_t)b * 6144 + sc_off + c0);
;         f32x4 sh = *(const f32x4*)(modl + (size_t)b * 6144 + sh_off + c0);
; #pragma unroll
;         for (int e = 0; e < 4; ++e) y[e] = v[i][e] * rstd * ww[e] * (1.f + sc[e]) + sh[e];
;         uint2 pk; pk.x = (unsigned)f2bf(y[0]) | ((unsigned)f2bf(y[1]) << 16); pk.y = (unsigned)f2bf(y[2]) | ((unsigned)f2bf(y[3]) << 16);
;         *(uint2*)(hn + a_off(row, c0, 32)) = pk;
.LBB0_1428:
	s_or_b64 exec, exec, s[0:1]
	v_ashrrev_i32_e32 v34, 13, v33
	v_mul_i32_i24_e32 v60, 0x1800, v34
	v_readlane_b32 s0, v244, 23
	v_ashrrev_i32_e32 v61, 31, v60
	v_readlane_b32 s1, v244, 24
	global_load_dwordx4 v[82:85], v[38:39], off
	s_waitcnt vmcnt(0)
	v_pk_mul_f32 v[96:97], v[28:29], v[28:29]
	v_lshl_add_u64 v[62:63], v[60:61], 2, s[0:1]
	v_lshl_add_u64 v[60:61], v[62:63], 0, s[12:13]
	v_lshl_add_u64 v[86:87], v[60:61], 0, v[44:45]
	v_lshl_add_u64 v[62:63], v[62:63], 0, s[14:15]
	global_load_dwordx4 v[86:89], v[86:87], off
	v_lshl_add_u64 v[90:91], v[62:63], 0, v[44:45]
	global_load_dwordx4 v[90:93], v[90:91], off
	v_pk_mul_f32 v[98:99], v[24:25], v[24:25]
	v_pk_mul_f32 v[64:65], v[30:31], v[30:31]
	v_pk_mul_f32 v[94:95], v[26:27], v[26:27]
	v_mov_b32_e32 v100, v96
	v_mov_b32_e32 v101, v98
	v_mov_b32_e32 v98, v97
	v_pk_add_f32 v[96:97], v[100:101], v[98:99]
	v_mov_b32_e32 v98, v64
	v_mov_b32_e32 v99, v94
	v_pk_add_f32 v[96:97], v[98:99], v[96:97]
	v_mov_b32_e32 v94, v65
	v_pk_add_f32 v[64:65], v[94:95], v[96:97]
	v_mov_b32_e32 v96, v17
	v_mov_b32_e32 v97, v21
	v_mov_b32_e32 v94, v16
	v_mov_b32_e32 v95, v20
	v_pk_mul_f32 v[96:97], v[96:97], v[96:97]
	v_add_f32_e32 v34, v64, v65
	v_pk_fma_f32 v[94:95], v[94:95], v[94:95], v[96:97]
	v_mov_b32_e32 v96, v18
	v_mov_b32_e32 v97, v22
	v_pk_fma_f32 v[94:95], v[96:97], v[96:97], v[94:95]
	v_mov_b32_e32 v96, v19
	v_mov_b32_e32 v97, v23
	v_pk_fma_f32 v[94:95], v[96:97], v[96:97], v[94:95]
	v_and_b32_e32 v55, 24, v77
	v_add_f32_e32 v34, v95, v34
	v_add_f32_e32 v34, v94, v34
	ds_bpermute_b32 v43, v66, v34
	v_mov_b32_e32 v95, v30
	v_mov_b32_e32 v30, v29
	v_and_b32_e32 v51, 0x1fe0, v78
	v_sub_u32_e32 v55, 0, v55
	s_waitcnt lgkmcnt(0)
	v_add_f32_e32 v34, v34, v43
	ds_bpermute_b32 v43, v67, v34
	v_mov_b32_e32 v94, v28
	v_ashrrev_i32_e32 v47, 3, v33
	v_and_b32_e32 v47, 0xffffffe0, v47
	v_or_b32_e32 v28, v47, v72
	s_waitcnt lgkmcnt(0)
	v_add_f32_e32 v34, v34, v43
	ds_bpermute_b32 v43, v68, v34
	v_mov_b32_e32 v65, v35
	s_waitcnt lgkmcnt(0)
	v_add_f32_e32 v34, v34, v43
	ds_bpermute_b32 v43, v69, v34
	s_waitcnt lgkmcnt(0)
	v_add_f32_e32 v29, v34, v43
	ds_bpermute_b32 v43, v70, v29
	v_lshlrev_b32_e32 v34, 1, v51
	v_xor_b32_e32 v51, v32, v55
	v_and_or_b32 v51, v51, 24, v73
	v_lshlrev_b32_e32 v64, 1, v51
	s_waitcnt lgkmcnt(0)
	v_add_f32_e32 v43, v29, v43
	ds_bpermute_b32 v55, v71, v43
	v_ashrrev_i32_e32 v29, 31, v28
	v_lshlrev_b64 v[28:29], 14, v[28:29]
	v_lshl_add_u64 v[28:29], s[62:63], 0, v[28:29]
	v_lshl_add_u64 v[28:29], v[28:29], 0, v[34:35]
	s_waitcnt lgkmcnt(0)
	v_add_f32_e32 v43, v43, v55
	v_fmamk_f32 v43, v43, 0x3a800000, v79
	v_mul_f32_e32 v51, 0x4b800000, v43
	v_cmp_gt_f32_e64 s[0:1], s18, v43
	v_lshl_add_u64 v[28:29], v[28:29], 0, v[64:65]
	v_mov_b32_e32 v98, v82
	v_cndmask_b32_e64 v43, v43, v51, s[0:1]
	v_rsq_f32_e32 v43, v43
	v_mov_b32_e32 v99, v84
	v_mov_b32_e32 v84, v83
	v_mul_f32_e32 v51, 0x45800000, v43
	v_cndmask_b32_e64 v96, v43, v51, s[0:1]
	v_pk_mul_f32 v[94:95], v[94:95], v[96:97] op_sel_hi:[1,0]
	v_pk_mul_f32 v[30:31], v[30:31], v[96:97] op_sel_hi:[1,0]
	v_pk_mul_f32 v[82:83], v[98:99], v[94:95]
	s_waitcnt vmcnt(1)
	v_mov_b32_e32 v95, v88
	v_mov_b32_e32 v88, v87
	v_mov_b32_e32 v94, v86
	s_waitcnt vmcnt(0)
	v_mov_b32_e32 v99, v92
	v_pk_mul_f32 v[30:31], v[84:85], v[30:31]
	v_pk_add_f32 v[84:85], v[88:89], 1.0 op_sel_hi:[1,0]
	v_mov_b32_e32 v92, v91
	v_mov_b32_e32 v98, v90
	v_pk_add_f32 v[94:95], v[94:95], 1.0 op_sel_hi:[1,0]
	v_pk_fma_f32 v[30:31], v[84:85], v[30:31], v[92:93]
	v_pk_fma_f32 v[82:83], v[94:95], v[82:83], v[98:99]
	v_and_b32_sdwa v55, v31, v80 dst_sel:DWORD dst_unused:UNUSED_PAD src0_sel:WORD_1 src1_sel:DWORD
	v_and_b32_sdwa v59, v30, v80 dst_sel:DWORD dst_unused:UNUSED_PAD src0_sel:WORD_1 src1_sel:DWORD
	v_and_b32_sdwa v43, v83, v80 dst_sel:DWORD dst_unused:UNUSED_PAD src0_sel:WORD_1 src1_sel:DWORD
	v_and_b32_sdwa v51, v82, v80 dst_sel:DWORD dst_unused:UNUSED_PAD src0_sel:WORD_1 src1_sel:DWORD
	v_add3_u32 v31, v31, v55, s19
	v_add3_u32 v30, v30, v59, s19
	v_add3_u32 v51, v82, v51, s19
	v_add3_u32 v43, v83, v43, s19
	v_and_b32_e32 v31, 0xffff0000, v31
	v_and_b32_e32 v30, 0xffff0000, v30
	v_or_b32_sdwa v31, v31, v43 dst_sel:DWORD dst_unused:UNUSED_PAD src0_sel:DWORD src1_sel:WORD_1
	v_or_b32_sdwa v30, v30, v51 dst_sel:DWORD dst_unused:UNUSED_PAD src0_sel:DWORD src1_sel:WORD_1
	v_mov_b32_e32 v250, v28
	v_mov_b32_e32 v251, v29
	v_mov_b32_e32 v252, v30
	v_mov_b32_e32 v253, v31
	v_lshl_add_u64 v[82:83], v[60:61], 0, v[48:49]
	global_load_dwordx4 v[28:31], v[38:39], off offset:1024
	v_lshl_add_u64 v[86:87], v[62:63], 0, v[48:49]
	global_load_dwordx4 v[82:85], v[82:83], off
	v_mov_b32_e32 v91, v26
	global_load_dwordx4 v[86:89], v[86:87], off
	global_store_dwordx2 v[250:251], v[252:253], off
	v_mov_b32_e32 v26, v25
	v_mov_b32_e32 v90, v24
	v_pk_mul_f32 v[26:27], v[26:27], v[96:97] op_sel_hi:[1,0]
	v_or_b32_e32 v24, v47, v74
	v_pk_mul_f32 v[90:91], v[90:91], v[96:97] op_sel_hi:[1,0]
	v_ashrrev_i32_e32 v25, 31, v24
	v_lshlrev_b64 v[24:25], 14, v[24:25]
	v_lshl_add_u64 v[24:25], s[62:63], 0, v[24:25]
	v_lshl_add_u64 v[24:25], v[24:25], 0, v[34:35]
	v_lshl_add_u64 v[24:25], v[24:25], 0, v[64:65]
	s_waitcnt vmcnt(3)
	v_mov_b32_e32 v93, v30
	v_mov_b32_e32 v30, v29
	s_waitcnt vmcnt(2)
	v_mov_b32_e32 v95, v84
	v_mov_b32_e32 v84, v83
	v_mov_b32_e32 v92, v28
	v_mov_b32_e32 v94, v82
	s_waitcnt vmcnt(1)
; __device__ __forceinline__ u16 f2bf(float x) { unsigned u = __float_as_uint(x); u += 0x7fffu + ((u >> 16) & 1u); return (u16)(u >> 16); }
; __device__ __forceinline__ size_t a_off(int row, int col, int nks) { return ((size_t)((row >> 8) * nks + (col >> 5)) << 13) + ((row & 255) << 5) + swzc(row, col & 31); }
; template <int MODE>
; __device__ __forceinline__ void norm_phase(const Params& p, const float* src, const float* w, const float* modl, int sh_off, int sc_off,
;                            char* smem, int bid, int nblk) {
;     ...
;     for (int i = 0; i < 4; ++i) {
;       const int c0 = i * 256 + lane * 4;
;       f32x4 ww = *(const f32x4*)(w + c0);
;       f32x4 y;
;       if (MODE == 2) {
; #pragma unroll
;         for (int e = 0; e < 4; ++e) y[e] = v[i][e] * rstd * ww[e];
;         *(f32x4*)(p.out + (size_t)row * 1024 + c0) = y;
;       } else {
;         f32x4 sc = *(const f32x4*)(modl + (size_t)b * 6144 + sc_off + c0);
;         f32x4 sh = *(const f32x4*)(modl + (size_t)b * 6144 + sh_off + c0);
; #pragma unroll
;         for (int e = 0; e < 4; ++e) y[e] = v[i][e] * rstd * ww[e] * (1.f + sc[e]) + sh[e];
;         uint2 pk; pk.x = (unsigned)f2bf(y[0]) | ((unsigned)f2bf(y[1]) << 16); pk.y = (unsigned)f2bf(y[2]) | ((unsigned)f2bf(y[3]) << 16);
;         *(uint2*)(hn + a_off(row, c0, 32)) = pk;
	v_mov_b32_e32 v99, v88
	v_mov_b32_e32 v88, v87
	v_pk_mul_f32 v[26:27], v[30:31], v[26:27]
	v_pk_add_f32 v[30:31], v[84:85], 1.0 op_sel_hi:[1,0]
	v_mov_b32_e32 v98, v86
	v_pk_mul_f32 v[28:29], v[92:93], v[90:91]
	v_pk_add_f32 v[82:83], v[94:95], 1.0 op_sel_hi:[1,0]
	v_pk_fma_f32 v[26:27], v[30:31], v[26:27], v[88:89]
	v_pk_fma_f32 v[28:29], v[82:83], v[28:29], v[98:99]
	v_and_b32_sdwa v43, v27, v80 dst_sel:DWORD dst_unused:UNUSED_PAD src0_sel:WORD_1 src1_sel:DWORD
	v_and_b32_sdwa v51, v26, v80 dst_sel:DWORD dst_unused:UNUSED_PAD src0_sel:WORD_1 src1_sel:DWORD
	v_and_b32_sdwa v30, v29, v80 dst_sel:DWORD dst_unused:UNUSED_PAD src0_sel:WORD_1 src1_sel:DWORD
	v_and_b32_sdwa v31, v28, v80 dst_sel:DWORD dst_unused:UNUSED_PAD src0_sel:WORD_1 src1_sel:DWORD
	v_add3_u32 v27, v27, v43, s19
	v_add3_u32 v26, v26, v51, s19
	v_add3_u32 v28, v28, v31, s19
	v_add3_u32 v29, v29, v30, s19
	v_and_b32_e32 v27, 0xffff0000, v27
	v_and_b32_e32 v26, 0xffff0000, v26
	v_or_b32_sdwa v27, v27, v29 dst_sel:DWORD dst_unused:UNUSED_PAD src0_sel:DWORD src1_sel:WORD_1
	v_or_b32_sdwa v26, v26, v28 dst_sel:DWORD dst_unused:UNUSED_PAD src0_sel:DWORD src1_sel:WORD_1
	v_mov_b32_e32 v250, v24
	v_mov_b32_e32 v251, v25
	v_mov_b32_e32 v252, v26
	v_mov_b32_e32 v253, v27
	v_lshl_add_u64 v[28:29], v[60:61], 0, v[52:53]
	global_load_dwordx4 v[24:27], v[38:39], off offset:2048
	v_lshl_add_u64 v[82:83], v[62:63], 0, v[52:53]
	global_load_dwordx4 v[28:31], v[28:29], off
	v_mov_b32_e32 v87, v22
	global_load_dwordx4 v[82:85], v[82:83], off
	global_store_dwordx2 v[250:251], v[252:253], off
	v_mov_b32_e32 v22, v21
	v_mov_b32_e32 v86, v20
	v_pk_mul_f32 v[22:23], v[22:23], v[96:97] op_sel_hi:[1,0]
	v_or_b32_e32 v20, v47, v75
	v_pk_mul_f32 v[86:87], v[86:87], v[96:97] op_sel_hi:[1,0]
	v_ashrrev_i32_e32 v21, 31, v20
	v_lshlrev_b64 v[20:21], 14, v[20:21]
	v_lshl_add_u64 v[20:21], s[62:63], 0, v[20:21]
	v_lshl_add_u64 v[20:21], v[20:21], 0, v[34:35]
	v_lshl_add_u64 v[20:21], v[20:21], 0, v[64:65]
	s_waitcnt vmcnt(3)
	v_mov_b32_e32 v89, v26
	v_mov_b32_e32 v26, v25
	s_waitcnt vmcnt(2)
	v_mov_b32_e32 v91, v30
	v_mov_b32_e32 v30, v29
	v_mov_b32_e32 v88, v24
	v_mov_b32_e32 v90, v28
	s_waitcnt vmcnt(1)
	v_mov_b32_e32 v93, v84
	v_mov_b32_e32 v84, v83
	v_pk_mul_f32 v[22:23], v[22:23], v[26:27]
	v_pk_add_f32 v[26:27], v[30:31], 1.0 op_sel_hi:[1,0]
	v_mov_b32_e32 v92, v82
	v_pk_mul_f32 v[24:25], v[86:87], v[88:89]
	v_pk_add_f32 v[28:29], v[90:91], 1.0 op_sel_hi:[1,0]
	v_pk_fma_f32 v[22:23], v[22:23], v[26:27], v[84:85]
	v_pk_fma_f32 v[24:25], v[24:25], v[28:29], v[92:93]
	v_and_b32_sdwa v28, v23, v80 dst_sel:DWORD dst_unused:UNUSED_PAD src0_sel:WORD_1 src1_sel:DWORD
	v_and_b32_sdwa v29, v22, v80 dst_sel:DWORD dst_unused:UNUSED_PAD src0_sel:WORD_1 src1_sel:DWORD
	v_and_b32_sdwa v26, v25, v80 dst_sel:DWORD dst_unused:UNUSED_PAD src0_sel:WORD_1 src1_sel:DWORD
	v_and_b32_sdwa v27, v24, v80 dst_sel:DWORD dst_unused:UNUSED_PAD src0_sel:WORD_1 src1_sel:DWORD
	v_add3_u32 v23, v23, v28, s19
	v_add3_u32 v22, v22, v29, s19
	v_add3_u32 v24, v24, v27, s19
	v_add3_u32 v25, v25, v26, s19
	v_and_b32_e32 v23, 0xffff0000, v23
	v_and_b32_e32 v22, 0xffff0000, v22
	v_or_b32_sdwa v23, v23, v25 dst_sel:DWORD dst_unused:UNUSED_PAD src0_sel:DWORD src1_sel:WORD_1
	v_or_b32_sdwa v22, v22, v24 dst_sel:DWORD dst_unused:UNUSED_PAD src0_sel:DWORD src1_sel:WORD_1
	v_mov_b32_e32 v250, v20
	v_mov_b32_e32 v251, v21
	v_mov_b32_e32 v252, v22
	v_mov_b32_e32 v253, v23
	v_lshl_add_u64 v[24:25], v[60:61], 0, v[56:57]
	global_load_dwordx4 v[20:23], v[38:39], off offset:3072
	v_lshl_add_u64 v[28:29], v[62:63], 0, v[56:57]
	global_load_dwordx4 v[24:27], v[24:25], off
	v_mov_b32_e32 v60, v16
	global_load_dwordx4 v[28:31], v[28:29], off
	global_store_dwordx2 v[250:251], v[252:253], off
	v_or_b32_e32 v16, v47, v76
	v_mov_b32_e32 v61, v18
	v_mov_b32_e32 v18, v17
	v_ashrrev_i32_e32 v17, 31, v16
	v_lshlrev_b64 v[16:17], 14, v[16:17]
	v_lshl_add_u64 v[16:17], s[62:63], 0, v[16:17]
	v_lshl_add_u64 v[16:17], v[16:17], 0, v[34:35]
	v_lshl_add_u64 v[16:17], v[16:17], 0, v[64:65]
	v_pk_mul_f32 v[18:19], v[18:19], v[96:97] op_sel_hi:[1,0]
	v_pk_mul_f32 v[60:61], v[60:61], v[96:97] op_sel_hi:[1,0]
	s_waitcnt vmcnt(3)
	v_mov_b32_e32 v63, v22
	v_mov_b32_e32 v22, v21
	s_waitcnt vmcnt(2)
	v_mov_b32_e32 v65, v26
	v_mov_b32_e32 v26, v25
	v_mov_b32_e32 v62, v20
	v_mov_b32_e32 v64, v24
	s_waitcnt vmcnt(1)
	v_mov_b32_e32 v83, v30
	v_mov_b32_e32 v30, v29
	v_pk_mul_f32 v[18:19], v[18:19], v[22:23]
	v_pk_add_f32 v[22:23], v[26:27], 1.0 op_sel_hi:[1,0]
	v_mov_b32_e32 v82, v28
	v_pk_mul_f32 v[20:21], v[60:61], v[62:63]
	v_pk_add_f32 v[24:25], v[64:65], 1.0 op_sel_hi:[1,0]
	v_pk_fma_f32 v[18:19], v[18:19], v[22:23], v[30:31]
	v_pk_fma_f32 v[20:21], v[20:21], v[24:25], v[82:83]
	v_and_b32_sdwa v24, v19, v80 dst_sel:DWORD dst_unused:UNUSED_PAD src0_sel:WORD_1 src1_sel:DWORD
	v_and_b32_sdwa v25, v18, v80 dst_sel:DWORD dst_unused:UNUSED_PAD src0_sel:WORD_1 src1_sel:DWORD
	v_and_b32_sdwa v22, v21, v80 dst_sel:DWORD dst_unused:UNUSED_PAD src0_sel:WORD_1 src1_sel:DWORD
	v_and_b32_sdwa v23, v20, v80 dst_sel:DWORD dst_unused:UNUSED_PAD src0_sel:WORD_1 src1_sel:DWORD
	v_add3_u32 v19, v19, v24, s19
	v_add3_u32 v18, v18, v25, s19
	v_add3_u32 v20, v20, v23, s19
	v_add3_u32 v21, v21, v22, s19
	v_and_b32_e32 v19, 0xffff0000, v19
	v_and_b32_e32 v18, 0xffff0000, v18
	v_or_b32_sdwa v19, v19, v21 dst_sel:DWORD dst_unused:UNUSED_PAD src0_sel:DWORD src1_sel:WORD_1
	v_or_b32_sdwa v18, v18, v20 dst_sel:DWORD dst_unused:UNUSED_PAD src0_sel:DWORD src1_sel:WORD_1
	global_store_dwordx2 v[16:17], v[18:19], off
	s_and_saveexec_b64 s[0:1], vcc
	s_cbranch_execz .LBB0_1419
; __device__ __forceinline__ u16 f2bf(float x) { unsigned u = __float_as_uint(x); u += 0x7fffu + ((u >> 16) & 1u); return (u16)(u >> 16); }
; __device__ __forceinline__ size_t a_off(int row, int col, int nks) { return ((size_t)((row >> 8) * nks + (col >> 5)) << 13) + ((row & 255) << 5) + swzc(row, col & 31); }
; template <int MODE>
; __device__ __forceinline__ void norm_phase(const Params& p, const float* src, const float* w, const float* modl, int sh_off, int sc_off,
;                            char* smem, int bid, int nblk) {
;     ...
;     float ss = 0.f;
; #pragma unroll
;     for (int i = 0; i < 4; ++i) ss += v[i][0] * v[i][0] + v[i][1] * v[i][1] + v[i][2] * v[i][2] + v[i][3] * v[i][3];
; #pragma unroll
;     for (int o = 32; o >= 1; o >>= 1) ss += __shfl_xor(ss, o);
;     const float rstd = rsqrtf(ss * (1.f / 1024.f) + 1e-6f);
;     const int b = row >> 13;
;     float dots[8];
;     if (MODE == 1) { for (int j = 0; j < 8; ++j) dots[j] = 0.f; }
; #pragma unroll
;     for (int i = 0; i < 4; ++i) {
;       const int c0 = i * 256 + lane * 4;
;       f32x4 ww = *(const f32x4*)(w + c0);
;       f32x4 y;
;       if (MODE == 2) {
; #pragma unroll
;         for (int e = 0; e < 4; ++e) y[e] = v[i][e] * rstd * ww[e];
;         *(f32x4*)(p.out + (size_t)row * 1024 + c0) = y;
;       } else {
;         f32x4 sc = *(const f32x4*)(modl + (size_t)b * 6144 + sc_off + c0);
;         f32x4 sh = *(const f32x4*)(modl + (size_t)b * 6144 + sh_off + c0);
; #pragma unroll
;         for (int e = 0; e < 4; ++e) y[e] = v[i][e] * rstd * ww[e] * (1.f + sc[e]) + sh[e];
;         uint2 pk; pk.x = (unsigned)f2bf(y[0]) | ((unsigned)f2bf(y[1]) << 16); pk.y = (unsigned)f2bf(y[2]) | ((unsigned)f2bf(y[3]) << 16);
;         *(uint2*)(hn + a_off(row, c0, 32)) = pk;
	v_ashrrev_i32_e32 v16, 13, v58
	v_mul_i32_i24_e32 v16, 0x1800, v16
	v_readlane_b32 s20, v244, 23
	v_ashrrev_i32_e32 v17, 31, v16
	v_readlane_b32 s21, v244, 24
	v_mov_b32_e32 v43, v35
	global_load_dwordx4 v[22:25], v[38:39], off
	v_lshl_add_u64 v[18:19], v[16:17], 2, s[20:21]
	v_lshl_add_u64 v[16:17], v[18:19], 0, s[12:13]
	v_lshl_add_u64 v[26:27], v[16:17], 0, v[42:43]
	v_lshl_add_u64 v[18:19], v[18:19], 0, s[14:15]
	global_load_dwordx4 v[26:29], v[26:27], off
	v_lshl_add_u64 v[30:31], v[18:19], 0, v[42:43]
	global_load_dwordx4 v[60:63], v[30:31], off
	v_pk_mul_f32 v[64:65], v[8:9], v[8:9]
	v_pk_mul_f32 v[82:83], v[12:13], v[12:13]
	v_pk_mul_f32 v[20:21], v[14:15], v[14:15]
	v_pk_mul_f32 v[30:31], v[10:11], v[10:11]
	v_mov_b32_e32 v84, v82
	v_mov_b32_e32 v85, v64
	v_mov_b32_e32 v64, v83
	v_pk_add_f32 v[64:65], v[84:85], v[64:65]
	v_mov_b32_e32 v82, v20
	v_mov_b32_e32 v83, v30
	v_pk_add_f32 v[64:65], v[82:83], v[64:65]
	v_mov_b32_e32 v30, v21
	v_pk_add_f32 v[20:21], v[30:31], v[64:65]
	v_mov_b32_e32 v64, v5
	v_mov_b32_e32 v65, v1
	v_mov_b32_e32 v30, v4
	v_mov_b32_e32 v31, v0
	v_pk_mul_f32 v[64:65], v[64:65], v[64:65]
	v_add_f32_e32 v20, v20, v21
	v_pk_fma_f32 v[30:31], v[30:31], v[30:31], v[64:65]
	v_mov_b32_e32 v64, v6
	v_mov_b32_e32 v65, v2
	v_pk_fma_f32 v[30:31], v[64:65], v[64:65], v[30:31]
	v_mov_b32_e32 v64, v7
	v_mov_b32_e32 v65, v3
	v_pk_fma_f32 v[30:31], v[64:65], v[64:65], v[30:31]
	v_ashrrev_i32_e32 v34, 3, v58
	v_add_f32_e32 v20, v30, v20
	v_add_f32_e32 v20, v20, v31
	ds_bpermute_b32 v21, v66, v20
	v_mov_b32_e32 v30, v12
	v_add_u32_e32 v43, s7, v78
	v_add_u32_e32 v47, s6, v77
	v_and_b32_e32 v81, 0xffffffe0, v34
	s_waitcnt lgkmcnt(0)
	v_add_f32_e32 v20, v20, v21
	ds_bpermute_b32 v21, v67, v20
	v_and_b32_e32 v34, 24, v47
	v_or_b32_e32 v58, v81, v72
	v_ashrrev_i32_e32 v59, 31, v58
	v_lshlrev_b64 v[58:59], 14, v[58:59]
	s_waitcnt lgkmcnt(0)
	v_add_f32_e32 v20, v20, v21
	ds_bpermute_b32 v31, v68, v20
	v_lshl_add_u64 v[58:59], s[62:63], 0, v[58:59]
	v_mov_b32_e32 v21, v35
	v_mov_b32_e32 v47, v35
	v_mov_b32_e32 v51, v35
	s_waitcnt lgkmcnt(0)
	v_add_f32_e32 v12, v20, v31
	ds_bpermute_b32 v20, v69, v12
	v_mov_b32_e32 v31, v14
	v_and_b32_e32 v14, 0x1fe0, v43
	v_sub_u32_e32 v43, 0, v34
	v_lshlrev_b32_e32 v34, 1, v14
	s_waitcnt lgkmcnt(0)
	v_add_f32_e32 v12, v12, v20
	ds_bpermute_b32 v20, v70, v12
	v_lshl_add_u64 v[58:59], v[58:59], 0, v[34:35]
	v_mov_b32_e32 v55, v35
	s_waitcnt lgkmcnt(0)
	v_add_f32_e32 v12, v12, v20
	ds_bpermute_b32 v14, v71, v12
	v_xor_b32_e32 v20, v32, v43
	v_and_or_b32 v20, v20, 24, v73
	v_lshlrev_b32_e32 v20, 1, v20
	v_lshl_add_u64 v[58:59], v[58:59], 0, v[20:21]
	s_waitcnt lgkmcnt(0)
	v_add_f32_e32 v12, v12, v14
	v_fmamk_f32 v12, v12, 0x3a800000, v79
	v_mul_f32_e32 v14, 0x4b800000, v12
	v_cmp_gt_f32_e32 vcc, s18, v12
	s_waitcnt vmcnt(2)
	v_mov_b32_e32 v64, v22
	v_cndmask_b32_e32 v12, v12, v14, vcc
	v_rsq_f32_e32 v12, v12
	v_mov_b32_e32 v65, v24
	v_mov_b32_e32 v24, v23
	v_mul_f32_e32 v14, 0x45800000, v12
	v_cndmask_b32_e32 v12, v12, v14, vcc
	v_pk_mul_f32 v[30:31], v[30:31], v[12:13] op_sel_hi:[1,0]
	v_mov_b32_e32 v14, v13
	v_pk_mul_f32 v[30:31], v[64:65], v[30:31]
	s_waitcnt vmcnt(1)
	v_mov_b32_e32 v65, v28
	v_pk_mul_f32 v[14:15], v[14:15], v[12:13] op_sel_hi:[1,0]
	v_mov_b32_e32 v28, v27
	v_mov_b32_e32 v64, v26
	s_waitcnt vmcnt(0)
	v_mov_b32_e32 v83, v62
	v_pk_mul_f32 v[14:15], v[24:25], v[14:15]
	v_pk_add_f32 v[22:23], v[28:29], 1.0 op_sel_hi:[1,0]
	v_mov_b32_e32 v62, v61
	v_mov_b32_e32 v82, v60
	v_pk_add_f32 v[64:65], v[64:65], 1.0 op_sel_hi:[1,0]
	v_pk_fma_f32 v[14:15], v[22:23], v[14:15], v[62:63]
	v_pk_fma_f32 v[30:31], v[64:65], v[30:31], v[82:83]
	v_and_b32_sdwa v23, v15, v80 dst_sel:DWORD dst_unused:UNUSED_PAD src0_sel:WORD_1 src1_sel:DWORD
	v_and_b32_sdwa v24, v14, v80 dst_sel:DWORD dst_unused:UNUSED_PAD src0_sel:WORD_1 src1_sel:DWORD
	v_and_b32_sdwa v13, v31, v80 dst_sel:DWORD dst_unused:UNUSED_PAD src0_sel:WORD_1 src1_sel:DWORD
	v_and_b32_sdwa v22, v30, v80 dst_sel:DWORD dst_unused:UNUSED_PAD src0_sel:WORD_1 src1_sel:DWORD
	v_add3_u32 v15, v15, v23, s19
	v_add3_u32 v14, v14, v24, s19
	v_add3_u32 v22, v30, v22, s19
	v_add3_u32 v13, v31, v13, s19
	v_and_b32_e32 v15, 0xffff0000, v15
	v_and_b32_e32 v14, 0xffff0000, v14
	v_or_b32_sdwa v15, v15, v13 dst_sel:DWORD dst_unused:UNUSED_PAD src0_sel:DWORD src1_sel:WORD_1
	v_or_b32_sdwa v14, v14, v22 dst_sel:DWORD dst_unused:UNUSED_PAD src0_sel:DWORD src1_sel:WORD_1
	v_mov_b32_e32 v250, v58
	v_mov_b32_e32 v251, v59
	v_mov_b32_e32 v252, v14
	v_mov_b32_e32 v253, v15
	v_lshl_add_u64 v[14:15], v[16:17], 0, v[46:47]
	global_load_dwordx4 v[22:25], v[38:39], off offset:1024
	global_load_dwordx4 v[26:29], v[14:15], off
	v_lshl_add_u64 v[14:15], v[18:19], 0, v[46:47]
	global_load_dwordx4 v[58:61], v[14:15], off
	global_store_dwordx2 v[250:251], v[252:253], off
	v_mov_b32_e32 v15, v10
	v_mov_b32_e32 v10, v9
	v_mov_b32_e32 v14, v8
	v_pk_mul_f32 v[10:11], v[10:11], v[12:13] op_sel_hi:[1,0]
	v_or_b32_e32 v8, v81, v74
	v_pk_mul_f32 v[14:15], v[14:15], v[12:13] op_sel_hi:[1,0]
	v_ashrrev_i32_e32 v9, 31, v8
	v_lshlrev_b64 v[8:9], 14, v[8:9]
	v_lshl_add_u64 v[8:9], s[62:63], 0, v[8:9]
	v_lshl_add_u64 v[8:9], v[8:9], 0, v[34:35]
	v_lshl_add_u64 v[8:9], v[8:9], 0, v[20:21]
	s_waitcnt vmcnt(3)
	v_mov_b32_e32 v31, v24
	s_waitcnt vmcnt(2)
	v_mov_b32_e32 v63, v28
	v_mov_b32_e32 v24, v23
	v_mov_b32_e32 v28, v27
	v_mov_b32_e32 v30, v22
	v_mov_b32_e32 v62, v26
	s_waitcnt vmcnt(1)
; __device__ __forceinline__ u16 f2bf(float x) { unsigned u = __float_as_uint(x); u += 0x7fffu + ((u >> 16) & 1u); return (u16)(u >> 16); }
; __device__ __forceinline__ size_t a_off(int row, int col, int nks) { return ((size_t)((row >> 8) * nks + (col >> 5)) << 13) + ((row & 255) << 5) + swzc(row, col & 31); }
; template <int MODE>
; __device__ __forceinline__ void norm_phase(const Params& p, const float* src, const float* w, const float* modl, int sh_off, int sc_off,
;                            char* smem, int bid, int nblk) {
;     ...
;     for (int i = 0; i < 4; ++i) {
;       const int c0 = i * 256 + lane * 4;
;       f32x4 ww = *(const f32x4*)(w + c0);
;       f32x4 y;
;       if (MODE == 2) {
; #pragma unroll
;         for (int e = 0; e < 4; ++e) y[e] = v[i][e] * rstd * ww[e];
;         *(f32x4*)(p.out + (size_t)row * 1024 + c0) = y;
;       } else {
;         f32x4 sc = *(const f32x4*)(modl + (size_t)b * 6144 + sc_off + c0);
;         f32x4 sh = *(const f32x4*)(modl + (size_t)b * 6144 + sh_off + c0);
; #pragma unroll
;         for (int e = 0; e < 4; ++e) y[e] = v[i][e] * rstd * ww[e] * (1.f + sc[e]) + sh[e];
;         uint2 pk; pk.x = (unsigned)f2bf(y[0]) | ((unsigned)f2bf(y[1]) << 16); pk.y = (unsigned)f2bf(y[2]) | ((unsigned)f2bf(y[3]) << 16);
;         *(uint2*)(hn + a_off(row, c0, 32)) = pk;
	v_mov_b32_e32 v65, v60
	v_mov_b32_e32 v60, v59
	v_pk_mul_f32 v[10:11], v[24:25], v[10:11]
	v_pk_add_f32 v[24:25], v[28:29], 1.0 op_sel_hi:[1,0]
	v_mov_b32_e32 v64, v58
	v_pk_mul_f32 v[14:15], v[30:31], v[14:15]
	v_pk_add_f32 v[22:23], v[62:63], 1.0 op_sel_hi:[1,0]
	v_pk_fma_f32 v[10:11], v[24:25], v[10:11], v[60:61]
	v_pk_fma_f32 v[14:15], v[22:23], v[14:15], v[64:65]
	v_and_b32_sdwa v23, v11, v80 dst_sel:DWORD dst_unused:UNUSED_PAD src0_sel:WORD_1 src1_sel:DWORD
	v_and_b32_sdwa v24, v10, v80 dst_sel:DWORD dst_unused:UNUSED_PAD src0_sel:WORD_1 src1_sel:DWORD
	v_and_b32_sdwa v13, v15, v80 dst_sel:DWORD dst_unused:UNUSED_PAD src0_sel:WORD_1 src1_sel:DWORD
	v_and_b32_sdwa v22, v14, v80 dst_sel:DWORD dst_unused:UNUSED_PAD src0_sel:WORD_1 src1_sel:DWORD
	v_add3_u32 v11, v11, v23, s19
	v_add3_u32 v10, v10, v24, s19
	v_add3_u32 v14, v14, v22, s19
	v_add3_u32 v13, v15, v13, s19
	v_and_b32_e32 v11, 0xffff0000, v11
	v_and_b32_e32 v10, 0xffff0000, v10
	v_or_b32_sdwa v11, v11, v13 dst_sel:DWORD dst_unused:UNUSED_PAD src0_sel:DWORD src1_sel:WORD_1
	v_or_b32_sdwa v10, v10, v14 dst_sel:DWORD dst_unused:UNUSED_PAD src0_sel:DWORD src1_sel:WORD_1
	v_mov_b32_e32 v250, v8
	v_mov_b32_e32 v251, v9
	v_mov_b32_e32 v252, v10
	v_mov_b32_e32 v253, v11
	v_lshl_add_u64 v[14:15], v[16:17], 0, v[50:51]
	global_load_dwordx4 v[8:11], v[38:39], off offset:2048
	global_load_dwordx4 v[22:25], v[14:15], off
	v_lshl_add_u64 v[14:15], v[18:19], 0, v[50:51]
	global_load_dwordx4 v[26:29], v[14:15], off
	global_store_dwordx2 v[250:251], v[252:253], off
	v_mov_b32_e32 v15, v6
	v_mov_b32_e32 v6, v5
	v_mov_b32_e32 v14, v4
	v_pk_mul_f32 v[6:7], v[6:7], v[12:13] op_sel_hi:[1,0]
	v_or_b32_e32 v4, v81, v75
	v_pk_mul_f32 v[14:15], v[14:15], v[12:13] op_sel_hi:[1,0]
	v_ashrrev_i32_e32 v5, 31, v4
	v_lshlrev_b64 v[4:5], 14, v[4:5]
	v_lshl_add_u64 v[4:5], s[62:63], 0, v[4:5]
	v_lshl_add_u64 v[4:5], v[4:5], 0, v[34:35]
	v_lshl_add_u64 v[4:5], v[4:5], 0, v[20:21]
	s_waitcnt vmcnt(3)
	v_mov_b32_e32 v31, v10
	s_waitcnt vmcnt(2)
	v_mov_b32_e32 v59, v24
	v_mov_b32_e32 v10, v9
	v_mov_b32_e32 v24, v23
	v_mov_b32_e32 v30, v8
	v_mov_b32_e32 v58, v22
	s_waitcnt vmcnt(1)
	v_mov_b32_e32 v61, v28
	v_mov_b32_e32 v28, v27
	v_pk_mul_f32 v[6:7], v[6:7], v[10:11]
	v_pk_add_f32 v[10:11], v[24:25], 1.0 op_sel_hi:[1,0]
	v_mov_b32_e32 v60, v26
	v_pk_mul_f32 v[8:9], v[14:15], v[30:31]
	v_pk_add_f32 v[14:15], v[58:59], 1.0 op_sel_hi:[1,0]
	v_pk_fma_f32 v[6:7], v[6:7], v[10:11], v[28:29]
	v_pk_fma_f32 v[8:9], v[8:9], v[14:15], v[60:61]
	v_and_b32_sdwa v13, v7, v80 dst_sel:DWORD dst_unused:UNUSED_PAD src0_sel:WORD_1 src1_sel:DWORD
	v_and_b32_sdwa v14, v6, v80 dst_sel:DWORD dst_unused:UNUSED_PAD src0_sel:WORD_1 src1_sel:DWORD
	v_and_b32_sdwa v10, v9, v80 dst_sel:DWORD dst_unused:UNUSED_PAD src0_sel:WORD_1 src1_sel:DWORD
	v_and_b32_sdwa v11, v8, v80 dst_sel:DWORD dst_unused:UNUSED_PAD src0_sel:WORD_1 src1_sel:DWORD
	v_add3_u32 v7, v7, v13, s19
	v_add3_u32 v6, v6, v14, s19
	v_add3_u32 v8, v8, v11, s19
	v_add3_u32 v9, v9, v10, s19
	v_and_b32_e32 v7, 0xffff0000, v7
	v_and_b32_e32 v6, 0xffff0000, v6
	v_or_b32_sdwa v7, v7, v9 dst_sel:DWORD dst_unused:UNUSED_PAD src0_sel:DWORD src1_sel:WORD_1
	v_or_b32_sdwa v6, v6, v8 dst_sel:DWORD dst_unused:UNUSED_PAD src0_sel:DWORD src1_sel:WORD_1
	v_mov_b32_e32 v250, v4
	v_mov_b32_e32 v251, v5
	v_mov_b32_e32 v252, v6
	v_mov_b32_e32 v253, v7
	v_lshl_add_u64 v[8:9], v[16:17], 0, v[54:55]
	global_load_dwordx4 v[4:7], v[38:39], off offset:3072
	v_lshl_add_u64 v[14:15], v[18:19], 0, v[54:55]
	global_load_dwordx4 v[8:11], v[8:9], off
	v_mov_b32_e32 v18, v0
	global_load_dwordx4 v[14:17], v[14:15], off
	global_store_dwordx2 v[250:251], v[252:253], off
	v_or_b32_e32 v0, v81, v76
	v_mov_b32_e32 v19, v2
	v_mov_b32_e32 v2, v1
	v_ashrrev_i32_e32 v1, 31, v0
	v_lshlrev_b64 v[0:1], 14, v[0:1]
	v_lshl_add_u64 v[0:1], s[62:63], 0, v[0:1]
	v_lshl_add_u64 v[0:1], v[0:1], 0, v[34:35]
	v_lshl_add_u64 v[0:1], v[0:1], 0, v[20:21]
	v_pk_mul_f32 v[18:19], v[18:19], v[12:13] op_sel_hi:[1,0]
	v_pk_mul_f32 v[2:3], v[2:3], v[12:13] op_sel_hi:[1,0]
	s_waitcnt vmcnt(3)
	v_mov_b32_e32 v13, v6
	v_mov_b32_e32 v6, v5
	s_waitcnt vmcnt(2)
	v_mov_b32_e32 v21, v10
	v_mov_b32_e32 v10, v9
	v_mov_b32_e32 v12, v4
	v_mov_b32_e32 v20, v8
	s_waitcnt vmcnt(1)
	v_mov_b32_e32 v23, v16
	v_mov_b32_e32 v16, v15
	v_pk_mul_f32 v[2:3], v[2:3], v[6:7]
	v_pk_add_f32 v[6:7], v[10:11], 1.0 op_sel_hi:[1,0]
	v_mov_b32_e32 v22, v14
	v_pk_mul_f32 v[4:5], v[18:19], v[12:13]
	v_pk_add_f32 v[8:9], v[20:21], 1.0 op_sel_hi:[1,0]
	v_pk_fma_f32 v[2:3], v[2:3], v[6:7], v[16:17]
	v_pk_fma_f32 v[4:5], v[4:5], v[8:9], v[22:23]
	v_and_b32_sdwa v8, v3, v80 dst_sel:DWORD dst_unused:UNUSED_PAD src0_sel:WORD_1 src1_sel:DWORD
	v_and_b32_sdwa v9, v2, v80 dst_sel:DWORD dst_unused:UNUSED_PAD src0_sel:WORD_1 src1_sel:DWORD
	v_and_b32_sdwa v6, v5, v80 dst_sel:DWORD dst_unused:UNUSED_PAD src0_sel:WORD_1 src1_sel:DWORD
	v_and_b32_sdwa v7, v4, v80 dst_sel:DWORD dst_unused:UNUSED_PAD src0_sel:WORD_1 src1_sel:DWORD
	v_add3_u32 v3, v3, v8, s19
	v_add3_u32 v2, v2, v9, s19
	v_add3_u32 v4, v4, v7, s19
	v_add3_u32 v5, v5, v6, s19
	v_and_b32_e32 v3, 0xffff0000, v3
	v_and_b32_e32 v2, 0xffff0000, v2
	v_or_b32_sdwa v3, v3, v5 dst_sel:DWORD dst_unused:UNUSED_PAD src0_sel:DWORD src1_sel:WORD_1
	v_or_b32_sdwa v2, v2, v4 dst_sel:DWORD dst_unused:UNUSED_PAD src0_sel:DWORD src1_sel:WORD_1
	global_store_dwordx2 v[0:1], v[2:3], off
	s_branch .LBB0_1419

; __device__ __forceinline__ u16 f2bf(float x) { unsigned u = __float_as_uint(x); u += 0x7fffu + ((u >> 16) & 1u); return (u16)(u >> 16); }
; __device__ __forceinline__ size_t a_off(int row, int col, int nks) { return ((size_t)((row >> 8) * nks + (col >> 5)) << 13) + ((row & 255) << 5) + swzc(row, col & 31); }
; template <int MODE>
; __device__ __forceinline__ void norm_phase(const Params& p, const float* src, const float* w, const float* modl, int sh_off, int sc_off,
;                            char* smem, int bid, int nblk) {
;     ...
;     float ss = 0.f;
; #pragma unroll
;     for (int i = 0; i < 4; ++i) ss += v[i][0] * v[i][0] + v[i][1] * v[i][1] + v[i][2] * v[i][2] + v[i][3] * v[i][3];
; #pragma unroll
;     for (int o = 32; o >= 1; o >>= 1) ss += __shfl_xor(ss, o);
;     const float rstd = rsqrtf(ss * (1.f / 1024.f) + 1e-6f);
;     const int b = row >> 13;
;     float dots[8];
;     if (MODE == 1) { for (int j = 0; j < 8; ++j) dots[j] = 0.f; }
; #pragma unroll
;     for (int i = 0; i < 4; ++i) {
;       const int c0 = i * 256 + lane * 4;
;       f32x4 ww = *(const f32x4*)(w + c0);
;       f32x4 y;
;       if (MODE == 2) {
; #pragma unroll
;         for (int e = 0; e < 4; ++e) y[e] = v[i][e] * rstd * ww[e];
;         *(f32x4*)(p.out + (size_t)row * 1024 + c0) = y;
;       } else {
;         f32x4 sc = *(const f32x4*)(modl + (size_t)b * 6144 + sc_off + c0);
;         f32x4 sh = *(const f32x4*)(modl + (size_t)b * 6144 + sh_off + c0);
; #pragma unroll
;         for (int e = 0; e < 4; ++e) y[e] = v[i][e] * rstd * ww[e] * (1.f + sc[e]) + sh[e];
;         uint2 pk; pk.x = (unsigned)f2bf(y[0]) | ((unsigned)f2bf(y[1]) << 16); pk.y = (unsigned)f2bf(y[2]) | ((unsigned)f2bf(y[3]) << 16);
;         *(uint2*)(hn + a_off(row, c0, 32)) = pk;
.LBB0_1646:
	s_or_b64 exec, exec, s[0:1]
	v_ashrrev_i32_e32 v34, 13, v33
	v_mul_i32_i24_e32 v66, 0x1800, v34
	v_ashrrev_i32_e32 v67, 31, v66
	v_lshl_add_u64 v[68:69], v[66:67], 2, s[6:7]
	v_lshl_add_u64 v[66:67], v[68:69], 0, s[8:9]
	global_load_dwordx4 v[88:91], v[38:39], off
	v_lshl_add_u64 v[92:93], v[66:67], 0, v[50:51]
	global_load_dwordx4 v[92:95], v[92:93], off
	v_lshl_add_u64 v[68:69], v[68:69], 0, v[50:51]
	global_load_dwordx4 v[96:99], v[68:69], off
	s_waitcnt vmcnt(0)
	v_pk_mul_f32 v[102:103], v[28:29], v[28:29]
	v_pk_mul_f32 v[104:105], v[24:25], v[24:25]
	v_pk_mul_f32 v[70:71], v[30:31], v[30:31]
	v_pk_mul_f32 v[100:101], v[26:27], v[26:27]
	v_mov_b32_e32 v106, v102
	v_mov_b32_e32 v107, v104
	v_mov_b32_e32 v104, v103
	v_pk_add_f32 v[102:103], v[106:107], v[104:105]
	v_mov_b32_e32 v104, v70
	v_mov_b32_e32 v105, v100
	v_pk_add_f32 v[102:103], v[104:105], v[102:103]
	v_mov_b32_e32 v100, v71
	v_pk_add_f32 v[70:71], v[100:101], v[102:103]
	v_mov_b32_e32 v102, v17
	v_mov_b32_e32 v103, v21
	v_mov_b32_e32 v100, v16
	v_mov_b32_e32 v101, v20
	v_pk_mul_f32 v[102:103], v[102:103], v[102:103]
	v_add_f32_e32 v34, v70, v71
	v_pk_fma_f32 v[100:101], v[100:101], v[100:101], v[102:103]
	v_mov_b32_e32 v102, v18
	v_mov_b32_e32 v103, v22
	v_pk_fma_f32 v[100:101], v[102:103], v[102:103], v[100:101]
	v_mov_b32_e32 v102, v19
	v_mov_b32_e32 v103, v23
	v_pk_fma_f32 v[100:101], v[102:103], v[102:103], v[100:101]
	v_and_b32_e32 v61, 24, v83
	v_add_f32_e32 v34, v101, v34
	v_add_f32_e32 v34, v100, v34
	ds_bpermute_b32 v49, v72, v34
	v_mov_b32_e32 v101, v30
	v_mov_b32_e32 v30, v29
	v_and_b32_e32 v57, 0x1fe0, v84
	v_sub_u32_e32 v61, 0, v61
	s_waitcnt lgkmcnt(0)
	v_add_f32_e32 v34, v34, v49
	ds_bpermute_b32 v49, v73, v34
	v_mov_b32_e32 v100, v28
	v_ashrrev_i32_e32 v53, 3, v33
	v_and_b32_e32 v53, 0xffffffe0, v53
	v_or_b32_e32 v28, v53, v78
	s_waitcnt lgkmcnt(0)
	v_add_f32_e32 v34, v34, v49
	ds_bpermute_b32 v49, v74, v34
	v_mov_b32_e32 v71, v35
	s_waitcnt lgkmcnt(0)
	v_add_f32_e32 v34, v34, v49
	ds_bpermute_b32 v49, v75, v34
	s_waitcnt lgkmcnt(0)
	v_add_f32_e32 v29, v34, v49
	ds_bpermute_b32 v49, v76, v29
	v_lshlrev_b32_e32 v34, 1, v57
	v_xor_b32_e32 v57, v32, v61
	v_and_or_b32 v57, v57, 24, v79
	v_lshlrev_b32_e32 v70, 1, v57
	s_waitcnt lgkmcnt(0)
	v_add_f32_e32 v49, v29, v49
	ds_bpermute_b32 v61, v77, v49
	v_ashrrev_i32_e32 v29, 31, v28
	v_lshlrev_b64 v[28:29], 14, v[28:29]
	v_lshl_add_u64 v[28:29], s[62:63], 0, v[28:29]
	v_lshl_add_u64 v[28:29], v[28:29], 0, v[34:35]
	s_waitcnt lgkmcnt(0)
	v_add_f32_e32 v49, v49, v61
	v_fmamk_f32 v49, v49, 0x3a800000, v85
	v_mul_f32_e32 v57, 0x4b800000, v49
	v_cmp_gt_f32_e64 s[0:1], s18, v49
	v_lshl_add_u64 v[28:29], v[28:29], 0, v[70:71]
	v_mov_b32_e32 v105, v90
	v_cndmask_b32_e64 v49, v49, v57, s[0:1]
	v_rsq_f32_e32 v49, v49
	v_mov_b32_e32 v90, v89
	v_mov_b32_e32 v104, v88
	v_mul_f32_e32 v57, 0x45800000, v49
	v_cndmask_b32_e64 v102, v49, v57, s[0:1]
	v_pk_mul_f32 v[30:31], v[30:31], v[102:103] op_sel_hi:[1,0]
	v_pk_mul_f32 v[100:101], v[100:101], v[102:103] op_sel_hi:[1,0]
	v_pk_mul_f32 v[30:31], v[90:91], v[30:31]
	v_mov_b32_e32 v90, v92
	v_mov_b32_e32 v91, v94
	v_pk_mul_f32 v[88:89], v[104:105], v[100:101]
	v_mov_b32_e32 v100, v96
	v_mov_b32_e32 v101, v98
	v_pk_add_f32 v[90:91], v[90:91], 1.0 op_sel_hi:[1,0]
	v_mov_b32_e32 v94, v93
	v_pk_fma_f32 v[88:89], v[90:91], v[88:89], v[100:101]
	v_pk_add_f32 v[90:91], v[94:95], 1.0 op_sel_hi:[1,0]
	v_mov_b32_e32 v98, v97
	v_pk_fma_f32 v[30:31], v[90:91], v[30:31], v[98:99]
	v_and_b32_sdwa v49, v89, v86 dst_sel:DWORD dst_unused:UNUSED_PAD src0_sel:WORD_1 src1_sel:DWORD
	v_and_b32_sdwa v61, v31, v86 dst_sel:DWORD dst_unused:UNUSED_PAD src0_sel:WORD_1 src1_sel:DWORD
	v_and_b32_sdwa v65, v30, v86 dst_sel:DWORD dst_unused:UNUSED_PAD src0_sel:WORD_1 src1_sel:DWORD
	v_and_b32_sdwa v57, v88, v86 dst_sel:DWORD dst_unused:UNUSED_PAD src0_sel:WORD_1 src1_sel:DWORD
	v_add3_u32 v31, v31, v61, s19
	v_add3_u32 v30, v30, v65, s19
	v_add3_u32 v57, v88, v57, s19
	v_add3_u32 v49, v89, v49, s19
	v_and_b32_e32 v31, 0xffff0000, v31
	v_and_b32_e32 v30, 0xffff0000, v30
	v_or_b32_sdwa v31, v31, v49 dst_sel:DWORD dst_unused:UNUSED_PAD src0_sel:DWORD src1_sel:WORD_1
	v_or_b32_sdwa v30, v30, v57 dst_sel:DWORD dst_unused:UNUSED_PAD src0_sel:DWORD src1_sel:WORD_1
	v_mov_b32_e32 v250, v28
	v_mov_b32_e32 v251, v29
	v_mov_b32_e32 v252, v30
	v_mov_b32_e32 v253, v31
	global_load_dwordx4 v[28:31], v[40:41], off
	v_lshl_add_u64 v[96:97], v[66:67], 0, v[54:55]
	global_load_dwordx4 v[88:91], v[96:97], off
	global_load_dwordx4 v[92:95], v[68:69], off offset:1024
	global_store_dwordx2 v[250:251], v[252:253], off
	v_mov_b32_e32 v97, v26
	v_mov_b32_e32 v26, v25
	v_mov_b32_e32 v96, v24
	v_pk_mul_f32 v[26:27], v[26:27], v[102:103] op_sel_hi:[1,0]
	v_or_b32_e32 v24, v53, v80
	v_pk_mul_f32 v[96:97], v[96:97], v[102:103] op_sel_hi:[1,0]
	v_ashrrev_i32_e32 v25, 31, v24
	v_lshlrev_b64 v[24:25], 14, v[24:25]
	v_lshl_add_u64 v[24:25], s[62:63], 0, v[24:25]
	v_lshl_add_u64 v[24:25], v[24:25], 0, v[34:35]
	v_lshl_add_u64 v[24:25], v[24:25], 0, v[70:71]
	s_waitcnt vmcnt(3)
	v_mov_b32_e32 v99, v30
	s_waitcnt vmcnt(2)
	v_mov_b32_e32 v101, v90
	v_mov_b32_e32 v30, v29
	v_mov_b32_e32 v90, v89
	v_mov_b32_e32 v98, v28
	v_mov_b32_e32 v100, v88
	s_waitcnt vmcnt(1)
; __device__ __forceinline__ u16 f2bf(float x) { unsigned u = __float_as_uint(x); u += 0x7fffu + ((u >> 16) & 1u); return (u16)(u >> 16); }
; __device__ __forceinline__ size_t a_off(int row, int col, int nks) { return ((size_t)((row >> 8) * nks + (col >> 5)) << 13) + ((row & 255) << 5) + swzc(row, col & 31); }
; template <int MODE>
; __device__ __forceinline__ void norm_phase(const Params& p, const float* src, const float* w, const float* modl, int sh_off, int sc_off,
;                            char* smem, int bid, int nblk) {
;     ...
;     for (int i = 0; i < 4; ++i) {
;       const int c0 = i * 256 + lane * 4;
;       f32x4 ww = *(const f32x4*)(w + c0);
;       f32x4 y;
;       if (MODE == 2) {
; #pragma unroll
;         for (int e = 0; e < 4; ++e) y[e] = v[i][e] * rstd * ww[e];
;         *(f32x4*)(p.out + (size_t)row * 1024 + c0) = y;
;       } else {
;         f32x4 sc = *(const f32x4*)(modl + (size_t)b * 6144 + sc_off + c0);
;         f32x4 sh = *(const f32x4*)(modl + (size_t)b * 6144 + sh_off + c0);
; #pragma unroll
;         for (int e = 0; e < 4; ++e) y[e] = v[i][e] * rstd * ww[e] * (1.f + sc[e]) + sh[e];
;         uint2 pk; pk.x = (unsigned)f2bf(y[0]) | ((unsigned)f2bf(y[1]) << 16); pk.y = (unsigned)f2bf(y[2]) | ((unsigned)f2bf(y[3]) << 16);
;         *(uint2*)(hn + a_off(row, c0, 32)) = pk;
	v_mov_b32_e32 v105, v94
	v_mov_b32_e32 v94, v93
	v_pk_mul_f32 v[26:27], v[30:31], v[26:27]
	v_pk_add_f32 v[30:31], v[90:91], 1.0 op_sel_hi:[1,0]
	v_mov_b32_e32 v104, v92
	v_pk_mul_f32 v[28:29], v[98:99], v[96:97]
	v_pk_add_f32 v[88:89], v[100:101], 1.0 op_sel_hi:[1,0]
	v_pk_fma_f32 v[26:27], v[30:31], v[26:27], v[94:95]
	v_pk_fma_f32 v[28:29], v[88:89], v[28:29], v[104:105]
	v_and_b32_sdwa v49, v27, v86 dst_sel:DWORD dst_unused:UNUSED_PAD src0_sel:WORD_1 src1_sel:DWORD
	v_and_b32_sdwa v57, v26, v86 dst_sel:DWORD dst_unused:UNUSED_PAD src0_sel:WORD_1 src1_sel:DWORD
	v_and_b32_sdwa v30, v29, v86 dst_sel:DWORD dst_unused:UNUSED_PAD src0_sel:WORD_1 src1_sel:DWORD
	v_and_b32_sdwa v31, v28, v86 dst_sel:DWORD dst_unused:UNUSED_PAD src0_sel:WORD_1 src1_sel:DWORD
	v_add3_u32 v27, v27, v49, s19
	v_add3_u32 v26, v26, v57, s19
	v_add3_u32 v28, v28, v31, s19
	v_add3_u32 v29, v29, v30, s19
	v_and_b32_e32 v27, 0xffff0000, v27
	v_and_b32_e32 v26, 0xffff0000, v26
	v_or_b32_sdwa v27, v27, v29 dst_sel:DWORD dst_unused:UNUSED_PAD src0_sel:DWORD src1_sel:WORD_1
	v_or_b32_sdwa v26, v26, v28 dst_sel:DWORD dst_unused:UNUSED_PAD src0_sel:DWORD src1_sel:WORD_1
	v_mov_b32_e32 v250, v24
	v_mov_b32_e32 v251, v25
	v_mov_b32_e32 v252, v26
	v_mov_b32_e32 v253, v27
	global_load_dwordx4 v[24:27], v[42:43], off
	v_lshl_add_u64 v[92:93], v[66:67], 0, v[58:59]
	global_load_dwordx4 v[28:31], v[92:93], off
	global_load_dwordx4 v[88:91], v[68:69], off offset:2048
	global_store_dwordx2 v[250:251], v[252:253], off
	v_mov_b32_e32 v93, v22
	v_mov_b32_e32 v22, v21
	v_mov_b32_e32 v92, v20
	v_pk_mul_f32 v[22:23], v[22:23], v[102:103] op_sel_hi:[1,0]
	v_or_b32_e32 v20, v53, v81
	v_pk_mul_f32 v[92:93], v[92:93], v[102:103] op_sel_hi:[1,0]
	v_ashrrev_i32_e32 v21, 31, v20
	v_lshlrev_b64 v[20:21], 14, v[20:21]
	v_lshl_add_u64 v[20:21], s[62:63], 0, v[20:21]
	v_lshl_add_u64 v[20:21], v[20:21], 0, v[34:35]
	v_lshl_add_u64 v[20:21], v[20:21], 0, v[70:71]
	v_lshl_add_u64 v[66:67], v[66:67], 0, v[62:63]
	s_waitcnt vmcnt(3)
	v_mov_b32_e32 v95, v26
	s_waitcnt vmcnt(2)
	v_mov_b32_e32 v97, v30
	v_mov_b32_e32 v26, v25
	v_mov_b32_e32 v30, v29
	v_mov_b32_e32 v94, v24
	v_mov_b32_e32 v96, v28
	s_waitcnt vmcnt(1)
	v_mov_b32_e32 v99, v90
	v_mov_b32_e32 v90, v89
	v_pk_mul_f32 v[22:23], v[22:23], v[26:27]
	v_pk_add_f32 v[26:27], v[30:31], 1.0 op_sel_hi:[1,0]
	v_mov_b32_e32 v98, v88
	v_pk_mul_f32 v[24:25], v[92:93], v[94:95]
	v_pk_add_f32 v[28:29], v[96:97], 1.0 op_sel_hi:[1,0]
	v_pk_fma_f32 v[22:23], v[22:23], v[26:27], v[90:91]
	v_pk_fma_f32 v[24:25], v[24:25], v[28:29], v[98:99]
	v_and_b32_sdwa v28, v23, v86 dst_sel:DWORD dst_unused:UNUSED_PAD src0_sel:WORD_1 src1_sel:DWORD
	v_and_b32_sdwa v29, v22, v86 dst_sel:DWORD dst_unused:UNUSED_PAD src0_sel:WORD_1 src1_sel:DWORD
	v_and_b32_sdwa v26, v25, v86 dst_sel:DWORD dst_unused:UNUSED_PAD src0_sel:WORD_1 src1_sel:DWORD
	v_and_b32_sdwa v27, v24, v86 dst_sel:DWORD dst_unused:UNUSED_PAD src0_sel:WORD_1 src1_sel:DWORD
	v_add3_u32 v23, v23, v28, s19
	v_add3_u32 v22, v22, v29, s19
	v_add3_u32 v24, v24, v27, s19
	v_add3_u32 v25, v25, v26, s19
	v_and_b32_e32 v23, 0xffff0000, v23
	v_and_b32_e32 v22, 0xffff0000, v22
	v_or_b32_sdwa v23, v23, v25 dst_sel:DWORD dst_unused:UNUSED_PAD src0_sel:DWORD src1_sel:WORD_1
	v_or_b32_sdwa v22, v22, v24 dst_sel:DWORD dst_unused:UNUSED_PAD src0_sel:DWORD src1_sel:WORD_1
	global_store_dwordx2 v[20:21], v[22:23], off
	global_load_dwordx4 v[20:23], v[44:45], off
	s_nop 0
	global_load_dwordx4 v[24:27], v[66:67], off
	global_load_dwordx4 v[28:31], v[68:69], off offset:3072
	v_mov_b32_e32 v66, v16
	v_or_b32_e32 v16, v53, v82
	v_mov_b32_e32 v67, v18
	v_mov_b32_e32 v18, v17
	v_ashrrev_i32_e32 v17, 31, v16
	v_lshlrev_b64 v[16:17], 14, v[16:17]
	v_lshl_add_u64 v[16:17], s[62:63], 0, v[16:17]
	v_lshl_add_u64 v[16:17], v[16:17], 0, v[34:35]
	v_lshl_add_u64 v[16:17], v[16:17], 0, v[70:71]
	v_pk_mul_f32 v[18:19], v[18:19], v[102:103] op_sel_hi:[1,0]
	v_pk_mul_f32 v[66:67], v[66:67], v[102:103] op_sel_hi:[1,0]
	s_waitcnt vmcnt(1)
	v_mov_b32_e32 v71, v26
	v_mov_b32_e32 v69, v22
	v_mov_b32_e32 v22, v21
	v_mov_b32_e32 v26, v25
	v_mov_b32_e32 v68, v20
	v_mov_b32_e32 v70, v24
	s_waitcnt vmcnt(0)
	v_mov_b32_e32 v89, v30
	v_mov_b32_e32 v30, v29
	v_pk_mul_f32 v[18:19], v[18:19], v[22:23]
	v_pk_add_f32 v[22:23], v[26:27], 1.0 op_sel_hi:[1,0]
	v_mov_b32_e32 v88, v28
	v_pk_mul_f32 v[20:21], v[66:67], v[68:69]
	v_pk_add_f32 v[24:25], v[70:71], 1.0 op_sel_hi:[1,0]
	v_pk_fma_f32 v[18:19], v[18:19], v[22:23], v[30:31]
	v_pk_fma_f32 v[20:21], v[20:21], v[24:25], v[88:89]
	v_and_b32_sdwa v24, v19, v86 dst_sel:DWORD dst_unused:UNUSED_PAD src0_sel:WORD_1 src1_sel:DWORD
	v_and_b32_sdwa v25, v18, v86 dst_sel:DWORD dst_unused:UNUSED_PAD src0_sel:WORD_1 src1_sel:DWORD
	v_and_b32_sdwa v22, v21, v86 dst_sel:DWORD dst_unused:UNUSED_PAD src0_sel:WORD_1 src1_sel:DWORD
	v_and_b32_sdwa v23, v20, v86 dst_sel:DWORD dst_unused:UNUSED_PAD src0_sel:WORD_1 src1_sel:DWORD
	v_add3_u32 v19, v19, v24, s19
	v_add3_u32 v18, v18, v25, s19
	v_add3_u32 v20, v20, v23, s19
	v_add3_u32 v21, v21, v22, s19
	v_and_b32_e32 v19, 0xffff0000, v19
	v_and_b32_e32 v18, 0xffff0000, v18
	v_or_b32_sdwa v19, v19, v21 dst_sel:DWORD dst_unused:UNUSED_PAD src0_sel:DWORD src1_sel:WORD_1
	v_or_b32_sdwa v18, v18, v20 dst_sel:DWORD dst_unused:UNUSED_PAD src0_sel:DWORD src1_sel:WORD_1
	global_store_dwordx2 v[16:17], v[18:19], off
	s_and_saveexec_b64 s[0:1], vcc
	s_cbranch_execz .LBB0_1637
; __device__ __forceinline__ u16 f2bf(float x) { unsigned u = __float_as_uint(x); u += 0x7fffu + ((u >> 16) & 1u); return (u16)(u >> 16); }
; __device__ __forceinline__ size_t a_off(int row, int col, int nks) { return ((size_t)((row >> 8) * nks + (col >> 5)) << 13) + ((row & 255) << 5) + swzc(row, col & 31); }
; template <int MODE>
; __device__ __forceinline__ void norm_phase(const Params& p, const float* src, const float* w, const float* modl, int sh_off, int sc_off,
;                            char* smem, int bid, int nblk) {
;     ...
;     float ss = 0.f;
; #pragma unroll
;     for (int i = 0; i < 4; ++i) ss += v[i][0] * v[i][0] + v[i][1] * v[i][1] + v[i][2] * v[i][2] + v[i][3] * v[i][3];
; #pragma unroll
;     for (int o = 32; o >= 1; o >>= 1) ss += __shfl_xor(ss, o);
;     const float rstd = rsqrtf(ss * (1.f / 1024.f) + 1e-6f);
;     const int b = row >> 13;
;     float dots[8];
;     if (MODE == 1) { for (int j = 0; j < 8; ++j) dots[j] = 0.f; }
; #pragma unroll
;     for (int i = 0; i < 4; ++i) {
;       const int c0 = i * 256 + lane * 4;
;       f32x4 ww = *(const f32x4*)(w + c0);
;       f32x4 y;
;       if (MODE == 2) {
; #pragma unroll
;         for (int e = 0; e < 4; ++e) y[e] = v[i][e] * rstd * ww[e];
;         *(f32x4*)(p.out + (size_t)row * 1024 + c0) = y;
;       } else {
;         f32x4 sc = *(const f32x4*)(modl + (size_t)b * 6144 + sc_off + c0);
;         f32x4 sh = *(const f32x4*)(modl + (size_t)b * 6144 + sh_off + c0);
; #pragma unroll
;         for (int e = 0; e < 4; ++e) y[e] = v[i][e] * rstd * ww[e] * (1.f + sc[e]) + sh[e];
;         uint2 pk; pk.x = (unsigned)f2bf(y[0]) | ((unsigned)f2bf(y[1]) << 16); pk.y = (unsigned)f2bf(y[2]) | ((unsigned)f2bf(y[3]) << 16);
;         *(uint2*)(hn + a_off(row, c0, 32)) = pk;
	v_ashrrev_i32_e32 v16, 13, v64
	v_mul_i32_i24_e32 v16, 0x1800, v16
	v_ashrrev_i32_e32 v17, 31, v16
	v_lshl_add_u64 v[18:19], v[16:17], 2, s[6:7]
	v_lshl_add_u64 v[16:17], v[18:19], 0, s[8:9]
	v_mov_b32_e32 v49, v35
	global_load_dwordx4 v[22:25], v[38:39], off
	v_lshl_add_u64 v[26:27], v[16:17], 0, v[48:49]
	global_load_dwordx4 v[26:29], v[26:27], off
	v_lshl_add_u64 v[18:19], v[18:19], 0, v[48:49]
	global_load_dwordx4 v[66:69], v[18:19], off
	v_pk_mul_f32 v[70:71], v[8:9], v[8:9]
	v_pk_mul_f32 v[88:89], v[12:13], v[12:13]
	v_pk_mul_f32 v[20:21], v[14:15], v[14:15]
	v_pk_mul_f32 v[30:31], v[10:11], v[10:11]
	v_mov_b32_e32 v90, v88
	v_mov_b32_e32 v91, v70
	v_mov_b32_e32 v70, v89
	v_pk_add_f32 v[70:71], v[90:91], v[70:71]
	v_mov_b32_e32 v88, v20
	v_mov_b32_e32 v89, v30
	v_pk_add_f32 v[70:71], v[88:89], v[70:71]
	v_mov_b32_e32 v30, v21
	v_pk_add_f32 v[20:21], v[30:31], v[70:71]
	v_mov_b32_e32 v70, v5
	v_mov_b32_e32 v71, v1
	v_mov_b32_e32 v30, v4
	v_mov_b32_e32 v31, v0
	v_pk_mul_f32 v[70:71], v[70:71], v[70:71]
	v_add_f32_e32 v20, v20, v21
	v_pk_fma_f32 v[30:31], v[30:31], v[30:31], v[70:71]
	v_mov_b32_e32 v70, v6
	v_mov_b32_e32 v71, v2
	v_pk_fma_f32 v[30:31], v[70:71], v[70:71], v[30:31]
	v_mov_b32_e32 v70, v7
	v_mov_b32_e32 v71, v3
	v_pk_fma_f32 v[30:31], v[70:71], v[70:71], v[30:31]
	v_add_u32_e32 v49, s11, v84
	v_add_f32_e32 v20, v30, v20
	v_add_f32_e32 v20, v20, v31
	ds_bpermute_b32 v21, v72, v20
	v_mov_b32_e32 v30, v12
	v_mov_b32_e32 v31, v14
	v_mov_b32_e32 v14, v13
	v_and_b32_e32 v13, 0x1fe0, v49
	s_waitcnt lgkmcnt(0)
	v_add_f32_e32 v20, v20, v21
	ds_bpermute_b32 v21, v73, v20
	v_ashrrev_i32_e32 v34, 3, v64
	v_add_u32_e32 v57, s10, v83
	v_and_b32_e32 v87, 0xffffffe0, v34
	v_and_b32_e32 v34, 24, v57
	s_waitcnt lgkmcnt(0)
	v_add_f32_e32 v20, v20, v21
	ds_bpermute_b32 v53, v74, v20
	v_mov_b32_e32 v21, v35
	v_mov_b32_e32 v57, v35
	v_mov_b32_e32 v61, v35
	s_waitcnt lgkmcnt(0)
	v_add_f32_e32 v12, v20, v53
	ds_bpermute_b32 v20, v75, v12
	v_sub_u32_e32 v53, 0, v34
	v_lshlrev_b32_e32 v34, 1, v13
	v_xor_b32_e32 v53, v32, v53
	v_and_or_b32 v53, v53, 24, v79
	s_waitcnt lgkmcnt(0)
	v_add_f32_e32 v20, v12, v20
	ds_bpermute_b32 v49, v76, v20
	v_or_b32_e32 v12, v87, v78
	v_ashrrev_i32_e32 v13, 31, v12
	v_lshlrev_b64 v[12:13], 14, v[12:13]
	v_lshl_add_u64 v[12:13], s[62:63], 0, v[12:13]
	s_waitcnt lgkmcnt(0)
	v_add_f32_e32 v20, v20, v49
	ds_bpermute_b32 v49, v77, v20
	v_lshl_add_u64 v[12:13], v[12:13], 0, v[34:35]
	s_waitcnt lgkmcnt(0)
	v_add_f32_e32 v20, v20, v49
	v_fmamk_f32 v20, v20, 0x3a800000, v85
	v_mul_f32_e32 v49, 0x4b800000, v20
	v_cmp_gt_f32_e32 vcc, s18, v20
	s_waitcnt vmcnt(2)
	v_mov_b32_e32 v70, v22
	v_cndmask_b32_e32 v20, v20, v49, vcc
	v_rsq_f32_e32 v49, v20
	v_lshlrev_b32_e32 v20, 1, v53
	v_lshl_add_u64 v[64:65], v[12:13], 0, v[20:21]
	v_mov_b32_e32 v71, v24
	v_mul_f32_e32 v12, 0x45800000, v49
	v_cndmask_b32_e32 v12, v49, v12, vcc
	v_pk_mul_f32 v[30:31], v[30:31], v[12:13] op_sel_hi:[1,0]
	v_pk_mul_f32 v[14:15], v[14:15], v[12:13] op_sel_hi:[1,0]
	v_pk_mul_f32 v[30:31], v[70:71], v[30:31]
	s_waitcnt vmcnt(1)
	v_mov_b32_e32 v71, v28
	v_mov_b32_e32 v24, v23
	v_mov_b32_e32 v28, v27
	v_mov_b32_e32 v70, v26
	s_waitcnt vmcnt(0)
	v_mov_b32_e32 v89, v68
	v_pk_mul_f32 v[14:15], v[24:25], v[14:15]
	v_pk_add_f32 v[22:23], v[28:29], 1.0 op_sel_hi:[1,0]
	v_mov_b32_e32 v68, v67
	v_mov_b32_e32 v88, v66
	v_pk_add_f32 v[70:71], v[70:71], 1.0 op_sel_hi:[1,0]
	v_pk_fma_f32 v[14:15], v[22:23], v[14:15], v[68:69]
	v_pk_fma_f32 v[30:31], v[70:71], v[30:31], v[88:89]
	v_and_b32_sdwa v23, v15, v86 dst_sel:DWORD dst_unused:UNUSED_PAD src0_sel:WORD_1 src1_sel:DWORD
	v_and_b32_sdwa v24, v14, v86 dst_sel:DWORD dst_unused:UNUSED_PAD src0_sel:WORD_1 src1_sel:DWORD
	v_and_b32_sdwa v13, v31, v86 dst_sel:DWORD dst_unused:UNUSED_PAD src0_sel:WORD_1 src1_sel:DWORD
	v_and_b32_sdwa v22, v30, v86 dst_sel:DWORD dst_unused:UNUSED_PAD src0_sel:WORD_1 src1_sel:DWORD
	v_add3_u32 v15, v15, v23, s19
	v_add3_u32 v14, v14, v24, s19
	v_add3_u32 v22, v30, v22, s19
	v_add3_u32 v13, v31, v13, s19
	v_and_b32_e32 v15, 0xffff0000, v15
	v_and_b32_e32 v14, 0xffff0000, v14
	v_or_b32_sdwa v15, v15, v13 dst_sel:DWORD dst_unused:UNUSED_PAD src0_sel:DWORD src1_sel:WORD_1
	v_or_b32_sdwa v14, v14, v22 dst_sel:DWORD dst_unused:UNUSED_PAD src0_sel:DWORD src1_sel:WORD_1
	v_mov_b32_e32 v250, v64
	v_mov_b32_e32 v251, v65
	v_mov_b32_e32 v252, v14
	v_mov_b32_e32 v253, v15
	v_mov_b32_e32 v53, v35
	global_load_dwordx4 v[22:25], v[40:41], off
	v_lshl_add_u64 v[14:15], v[16:17], 0, v[52:53]
	global_load_dwordx4 v[26:29], v[14:15], off
	global_load_dwordx4 v[64:67], v[18:19], off offset:1024
	global_store_dwordx2 v[250:251], v[252:253], off
	v_mov_b32_e32 v15, v10
	v_mov_b32_e32 v10, v9
	v_mov_b32_e32 v14, v8
	v_pk_mul_f32 v[10:11], v[10:11], v[12:13] op_sel_hi:[1,0]
	v_or_b32_e32 v8, v87, v80
	v_pk_mul_f32 v[14:15], v[14:15], v[12:13] op_sel_hi:[1,0]
	v_ashrrev_i32_e32 v9, 31, v8
	v_lshlrev_b64 v[8:9], 14, v[8:9]
	v_lshl_add_u64 v[8:9], s[62:63], 0, v[8:9]
	v_lshl_add_u64 v[8:9], v[8:9], 0, v[34:35]
	v_lshl_add_u64 v[8:9], v[8:9], 0, v[20:21]
	s_waitcnt vmcnt(3)
	v_mov_b32_e32 v31, v24
	s_waitcnt vmcnt(2)
	v_mov_b32_e32 v69, v28
	v_mov_b32_e32 v24, v23
	v_mov_b32_e32 v28, v27
	v_mov_b32_e32 v30, v22
	v_mov_b32_e32 v68, v26
	s_waitcnt vmcnt(1)
; __device__ __forceinline__ u16 f2bf(float x) { unsigned u = __float_as_uint(x); u += 0x7fffu + ((u >> 16) & 1u); return (u16)(u >> 16); }
; __device__ __forceinline__ size_t a_off(int row, int col, int nks) { return ((size_t)((row >> 8) * nks + (col >> 5)) << 13) + ((row & 255) << 5) + swzc(row, col & 31); }
; template <int MODE>
; __device__ __forceinline__ void norm_phase(const Params& p, const float* src, const float* w, const float* modl, int sh_off, int sc_off,
;                            char* smem, int bid, int nblk) {
;     ...
;     for (int i = 0; i < 4; ++i) {
;       const int c0 = i * 256 + lane * 4;
;       f32x4 ww = *(const f32x4*)(w + c0);
;       f32x4 y;
;       if (MODE == 2) {
; #pragma unroll
;         for (int e = 0; e < 4; ++e) y[e] = v[i][e] * rstd * ww[e];
;         *(f32x4*)(p.out + (size_t)row * 1024 + c0) = y;
;       } else {
;         f32x4 sc = *(const f32x4*)(modl + (size_t)b * 6144 + sc_off + c0);
;         f32x4 sh = *(const f32x4*)(modl + (size_t)b * 6144 + sh_off + c0);
; #pragma unroll
;         for (int e = 0; e < 4; ++e) y[e] = v[i][e] * rstd * ww[e] * (1.f + sc[e]) + sh[e];
;         uint2 pk; pk.x = (unsigned)f2bf(y[0]) | ((unsigned)f2bf(y[1]) << 16); pk.y = (unsigned)f2bf(y[2]) | ((unsigned)f2bf(y[3]) << 16);
;         *(uint2*)(hn + a_off(row, c0, 32)) = pk;
	v_mov_b32_e32 v71, v66
	v_mov_b32_e32 v66, v65
	v_pk_mul_f32 v[10:11], v[24:25], v[10:11]
	v_pk_add_f32 v[24:25], v[28:29], 1.0 op_sel_hi:[1,0]
	v_mov_b32_e32 v70, v64
	v_pk_mul_f32 v[14:15], v[30:31], v[14:15]
	v_pk_add_f32 v[22:23], v[68:69], 1.0 op_sel_hi:[1,0]
	v_pk_fma_f32 v[10:11], v[24:25], v[10:11], v[66:67]
	v_pk_fma_f32 v[14:15], v[22:23], v[14:15], v[70:71]
	v_and_b32_sdwa v23, v11, v86 dst_sel:DWORD dst_unused:UNUSED_PAD src0_sel:WORD_1 src1_sel:DWORD
	v_and_b32_sdwa v24, v10, v86 dst_sel:DWORD dst_unused:UNUSED_PAD src0_sel:WORD_1 src1_sel:DWORD
	v_and_b32_sdwa v13, v15, v86 dst_sel:DWORD dst_unused:UNUSED_PAD src0_sel:WORD_1 src1_sel:DWORD
	v_and_b32_sdwa v22, v14, v86 dst_sel:DWORD dst_unused:UNUSED_PAD src0_sel:WORD_1 src1_sel:DWORD
	v_add3_u32 v11, v11, v23, s19
	v_add3_u32 v10, v10, v24, s19
	v_add3_u32 v14, v14, v22, s19
	v_add3_u32 v13, v15, v13, s19
	v_and_b32_e32 v11, 0xffff0000, v11
	v_and_b32_e32 v10, 0xffff0000, v10
	v_or_b32_sdwa v11, v11, v13 dst_sel:DWORD dst_unused:UNUSED_PAD src0_sel:DWORD src1_sel:WORD_1
	v_or_b32_sdwa v10, v10, v14 dst_sel:DWORD dst_unused:UNUSED_PAD src0_sel:DWORD src1_sel:WORD_1
	v_mov_b32_e32 v250, v8
	v_mov_b32_e32 v251, v9
	v_mov_b32_e32 v252, v10
	v_mov_b32_e32 v253, v11
	global_load_dwordx4 v[8:11], v[42:43], off
	v_lshl_add_u64 v[14:15], v[16:17], 0, v[56:57]
	global_load_dwordx4 v[22:25], v[14:15], off
	global_load_dwordx4 v[26:29], v[18:19], off offset:2048
	global_store_dwordx2 v[250:251], v[252:253], off
	v_mov_b32_e32 v15, v6
	v_mov_b32_e32 v6, v5
	v_mov_b32_e32 v14, v4
	v_pk_mul_f32 v[6:7], v[6:7], v[12:13] op_sel_hi:[1,0]
	v_or_b32_e32 v4, v87, v81
	v_pk_mul_f32 v[14:15], v[14:15], v[12:13] op_sel_hi:[1,0]
	v_ashrrev_i32_e32 v5, 31, v4
	v_lshlrev_b64 v[4:5], 14, v[4:5]
	v_lshl_add_u64 v[4:5], s[62:63], 0, v[4:5]
	v_lshl_add_u64 v[4:5], v[4:5], 0, v[34:35]
	v_lshl_add_u64 v[4:5], v[4:5], 0, v[20:21]
	s_waitcnt vmcnt(3)
	v_mov_b32_e32 v31, v10
	s_waitcnt vmcnt(2)
	v_mov_b32_e32 v65, v24
	v_mov_b32_e32 v10, v9
	v_mov_b32_e32 v24, v23
	v_mov_b32_e32 v30, v8
	v_mov_b32_e32 v64, v22
	s_waitcnt vmcnt(1)
	v_mov_b32_e32 v67, v28
	v_mov_b32_e32 v28, v27
	v_pk_mul_f32 v[6:7], v[6:7], v[10:11]
	v_pk_add_f32 v[10:11], v[24:25], 1.0 op_sel_hi:[1,0]
	v_mov_b32_e32 v66, v26
	v_pk_mul_f32 v[8:9], v[14:15], v[30:31]
	v_pk_add_f32 v[14:15], v[64:65], 1.0 op_sel_hi:[1,0]
	v_pk_fma_f32 v[6:7], v[6:7], v[10:11], v[28:29]
	v_pk_fma_f32 v[8:9], v[8:9], v[14:15], v[66:67]
	v_and_b32_sdwa v13, v7, v86 dst_sel:DWORD dst_unused:UNUSED_PAD src0_sel:WORD_1 src1_sel:DWORD
	v_and_b32_sdwa v14, v6, v86 dst_sel:DWORD dst_unused:UNUSED_PAD src0_sel:WORD_1 src1_sel:DWORD
	v_and_b32_sdwa v10, v9, v86 dst_sel:DWORD dst_unused:UNUSED_PAD src0_sel:WORD_1 src1_sel:DWORD
	v_and_b32_sdwa v11, v8, v86 dst_sel:DWORD dst_unused:UNUSED_PAD src0_sel:WORD_1 src1_sel:DWORD
	v_add3_u32 v7, v7, v13, s19
	v_add3_u32 v6, v6, v14, s19
	v_add3_u32 v8, v8, v11, s19
	v_add3_u32 v9, v9, v10, s19
	v_and_b32_e32 v7, 0xffff0000, v7
	v_and_b32_e32 v6, 0xffff0000, v6
	v_or_b32_sdwa v7, v7, v9 dst_sel:DWORD dst_unused:UNUSED_PAD src0_sel:DWORD src1_sel:WORD_1
	v_or_b32_sdwa v6, v6, v8 dst_sel:DWORD dst_unused:UNUSED_PAD src0_sel:DWORD src1_sel:WORD_1
	v_mov_b32_e32 v250, v4
	v_mov_b32_e32 v251, v5
	v_mov_b32_e32 v252, v6
	v_mov_b32_e32 v253, v7
	global_load_dwordx4 v[4:7], v[44:45], off
	v_lshl_add_u64 v[22:23], v[16:17], 0, v[60:61]
	global_load_dwordx4 v[8:11], v[22:23], off
	global_load_dwordx4 v[14:17], v[18:19], off offset:3072
	global_store_dwordx2 v[250:251], v[252:253], off
	v_mov_b32_e32 v18, v0
	v_or_b32_e32 v0, v87, v82
	v_mov_b32_e32 v19, v2
	v_mov_b32_e32 v2, v1
	v_ashrrev_i32_e32 v1, 31, v0
	v_lshlrev_b64 v[0:1], 14, v[0:1]
	v_lshl_add_u64 v[0:1], s[62:63], 0, v[0:1]
	v_lshl_add_u64 v[0:1], v[0:1], 0, v[34:35]
	v_lshl_add_u64 v[0:1], v[0:1], 0, v[20:21]
	v_pk_mul_f32 v[18:19], v[18:19], v[12:13] op_sel_hi:[1,0]
	v_pk_mul_f32 v[2:3], v[2:3], v[12:13] op_sel_hi:[1,0]
	s_waitcnt vmcnt(3)
	v_mov_b32_e32 v13, v6
	s_waitcnt vmcnt(2)
	v_mov_b32_e32 v21, v10
	v_mov_b32_e32 v6, v5
	v_mov_b32_e32 v10, v9
	v_mov_b32_e32 v12, v4
	v_mov_b32_e32 v20, v8
	s_waitcnt vmcnt(1)
	v_mov_b32_e32 v23, v16
	v_mov_b32_e32 v16, v15
	v_pk_mul_f32 v[2:3], v[2:3], v[6:7]
	v_pk_add_f32 v[6:7], v[10:11], 1.0 op_sel_hi:[1,0]
	v_mov_b32_e32 v22, v14
	v_pk_mul_f32 v[4:5], v[18:19], v[12:13]
	v_pk_add_f32 v[8:9], v[20:21], 1.0 op_sel_hi:[1,0]
	v_pk_fma_f32 v[2:3], v[2:3], v[6:7], v[16:17]
	v_pk_fma_f32 v[4:5], v[4:5], v[8:9], v[22:23]
	v_and_b32_sdwa v8, v3, v86 dst_sel:DWORD dst_unused:UNUSED_PAD src0_sel:WORD_1 src1_sel:DWORD
	v_and_b32_sdwa v9, v2, v86 dst_sel:DWORD dst_unused:UNUSED_PAD src0_sel:WORD_1 src1_sel:DWORD
	v_and_b32_sdwa v6, v5, v86 dst_sel:DWORD dst_unused:UNUSED_PAD src0_sel:WORD_1 src1_sel:DWORD
	v_and_b32_sdwa v7, v4, v86 dst_sel:DWORD dst_unused:UNUSED_PAD src0_sel:WORD_1 src1_sel:DWORD
	v_add3_u32 v3, v3, v8, s19
	v_add3_u32 v2, v2, v9, s19
	v_add3_u32 v4, v4, v7, s19
	v_add3_u32 v5, v5, v6, s19
	v_and_b32_e32 v3, 0xffff0000, v3
	v_and_b32_e32 v2, 0xffff0000, v2
	v_or_b32_sdwa v3, v3, v5 dst_sel:DWORD dst_unused:UNUSED_PAD src0_sel:DWORD src1_sel:WORD_1
	v_or_b32_sdwa v2, v2, v4 dst_sel:DWORD dst_unused:UNUSED_PAD src0_sel:DWORD src1_sel:WORD_1
	global_store_dwordx2 v[0:1], v[2:3], off
	s_branch .LBB0_1637

; __device__ __forceinline__ u16 f2bf(float x) { unsigned u = __float_as_uint(x); u += 0x7fffu + ((u >> 16) & 1u); return (u16)(u >> 16); }
; __device__ __forceinline__ size_t a_off(int row, int col, int nks) { return ((size_t)((row >> 8) * nks + (col >> 5)) << 13) + ((row & 255) << 5) + swzc(row, col & 31); }
; template <int MODE>
; __device__ __forceinline__ void norm_phase(const Params& p, const float* src, const float* w, const float* modl, int sh_off, int sc_off,
;                            char* smem, int bid, int nblk) {
;     ...
;     float ss = 0.f;
; #pragma unroll
;     for (int i = 0; i < 4; ++i) ss += v[i][0] * v[i][0] + v[i][1] * v[i][1] + v[i][2] * v[i][2] + v[i][3] * v[i][3];
; #pragma unroll
;     for (int o = 32; o >= 1; o >>= 1) ss += __shfl_xor(ss, o);
;     const float rstd = rsqrtf(ss * (1.f / 1024.f) + 1e-6f);
;     const int b = row >> 13;
;     float dots[8];
;     if (MODE == 1) { for (int j = 0; j < 8; ++j) dots[j] = 0.f; }
; #pragma unroll
;     for (int i = 0; i < 4; ++i) {
;       const int c0 = i * 256 + lane * 4;
;       f32x4 ww = *(const f32x4*)(w + c0);
;       f32x4 y;
;       if (MODE == 2) {
; #pragma unroll
;         for (int e = 0; e < 4; ++e) y[e] = v[i][e] * rstd * ww[e];
;         *(f32x4*)(p.out + (size_t)row * 1024 + c0) = y;
;       } else {
;         f32x4 sc = *(const f32x4*)(modl + (size_t)b * 6144 + sc_off + c0);
;         f32x4 sh = *(const f32x4*)(modl + (size_t)b * 6144 + sh_off + c0);
; #pragma unroll
;         for (int e = 0; e < 4; ++e) y[e] = v[i][e] * rstd * ww[e] * (1.f + sc[e]) + sh[e];
;         uint2 pk; pk.x = (unsigned)f2bf(y[0]) | ((unsigned)f2bf(y[1]) << 16); pk.y = (unsigned)f2bf(y[2]) | ((unsigned)f2bf(y[3]) << 16);
;         *(uint2*)(hn + a_off(row, c0, 32)) = pk;
.LBB0_1945:
	s_or_b64 exec, exec, s[0:1]
	v_ashrrev_i32_e32 v34, 13, v33
	v_mul_i32_i24_e32 v66, 0x1800, v34
	v_ashrrev_i32_e32 v67, 31, v66
	v_lshl_add_u64 v[68:69], v[66:67], 2, s[6:7]
	v_lshl_add_u64 v[66:67], v[68:69], 0, s[14:15]
	global_load_dwordx4 v[88:91], v[38:39], off
	v_lshl_add_u64 v[92:93], v[66:67], 0, v[50:51]
	v_lshl_add_u64 v[68:69], v[68:69], 0, s[16:17]
	global_load_dwordx4 v[92:95], v[92:93], off
	v_lshl_add_u64 v[96:97], v[68:69], 0, v[50:51]
	global_load_dwordx4 v[96:99], v[96:97], off
	s_waitcnt vmcnt(0)
	v_pk_mul_f32 v[102:103], v[28:29], v[28:29]
	v_pk_mul_f32 v[104:105], v[24:25], v[24:25]
	v_pk_mul_f32 v[70:71], v[30:31], v[30:31]
	v_pk_mul_f32 v[100:101], v[26:27], v[26:27]
	v_mov_b32_e32 v106, v102
	v_mov_b32_e32 v107, v104
	v_mov_b32_e32 v104, v103
	v_pk_add_f32 v[102:103], v[106:107], v[104:105]
	v_mov_b32_e32 v104, v70
	v_mov_b32_e32 v105, v100
	v_pk_add_f32 v[102:103], v[104:105], v[102:103]
	v_mov_b32_e32 v100, v71
	v_pk_add_f32 v[70:71], v[100:101], v[102:103]
	v_mov_b32_e32 v102, v17
	v_mov_b32_e32 v103, v21
	v_mov_b32_e32 v100, v16
	v_mov_b32_e32 v101, v20
	v_pk_mul_f32 v[102:103], v[102:103], v[102:103]
	v_add_f32_e32 v34, v70, v71
	v_pk_fma_f32 v[100:101], v[100:101], v[100:101], v[102:103]
	v_mov_b32_e32 v102, v18
	v_mov_b32_e32 v103, v22
	v_pk_fma_f32 v[100:101], v[102:103], v[102:103], v[100:101]
	v_mov_b32_e32 v102, v19
	v_mov_b32_e32 v103, v23
	v_pk_fma_f32 v[100:101], v[102:103], v[102:103], v[100:101]
	v_and_b32_e32 v61, 24, v83
	v_add_f32_e32 v34, v101, v34
	v_add_f32_e32 v34, v100, v34
	ds_bpermute_b32 v49, v72, v34
	v_mov_b32_e32 v101, v30
	v_mov_b32_e32 v30, v29
	v_and_b32_e32 v57, 0x1fe0, v84
	v_sub_u32_e32 v61, 0, v61
	s_waitcnt lgkmcnt(0)
	v_add_f32_e32 v34, v34, v49
	ds_bpermute_b32 v49, v73, v34
	v_mov_b32_e32 v100, v28
	v_ashrrev_i32_e32 v53, 3, v33
	v_and_b32_e32 v53, 0xffffffe0, v53
	v_or_b32_e32 v28, v53, v78
	s_waitcnt lgkmcnt(0)
	v_add_f32_e32 v34, v34, v49
	ds_bpermute_b32 v49, v74, v34
	v_mov_b32_e32 v71, v35
	s_waitcnt lgkmcnt(0)
	v_add_f32_e32 v34, v34, v49
	ds_bpermute_b32 v49, v75, v34
	s_waitcnt lgkmcnt(0)
	v_add_f32_e32 v29, v34, v49
	ds_bpermute_b32 v49, v76, v29
	v_lshlrev_b32_e32 v34, 1, v57
	v_xor_b32_e32 v57, v32, v61
	v_and_or_b32 v57, v57, 24, v79
	v_lshlrev_b32_e32 v70, 1, v57
	s_waitcnt lgkmcnt(0)
	v_add_f32_e32 v49, v29, v49
	ds_bpermute_b32 v61, v77, v49
	v_ashrrev_i32_e32 v29, 31, v28
	v_lshlrev_b64 v[28:29], 14, v[28:29]
	v_lshl_add_u64 v[28:29], s[62:63], 0, v[28:29]
	v_lshl_add_u64 v[28:29], v[28:29], 0, v[34:35]
	s_waitcnt lgkmcnt(0)
	v_add_f32_e32 v49, v49, v61
	v_fmamk_f32 v49, v49, 0x3a800000, v85
	v_mul_f32_e32 v57, 0x4b800000, v49
	v_cmp_gt_f32_e64 s[0:1], s20, v49
	v_lshl_add_u64 v[28:29], v[28:29], 0, v[70:71]
	v_mov_b32_e32 v104, v88
	v_cndmask_b32_e64 v49, v49, v57, s[0:1]
	v_rsq_f32_e32 v49, v49
	v_mov_b32_e32 v105, v90
	v_mov_b32_e32 v90, v89
	v_mul_f32_e32 v57, 0x45800000, v49
	v_cndmask_b32_e64 v102, v49, v57, s[0:1]
	v_pk_mul_f32 v[100:101], v[100:101], v[102:103] op_sel_hi:[1,0]
	v_pk_mul_f32 v[30:31], v[30:31], v[102:103] op_sel_hi:[1,0]
	v_pk_mul_f32 v[88:89], v[104:105], v[100:101]
	v_mov_b32_e32 v101, v94
	v_mov_b32_e32 v94, v93
	v_mov_b32_e32 v100, v92
	v_mov_b32_e32 v105, v98
	v_pk_mul_f32 v[30:31], v[90:91], v[30:31]
	v_pk_add_f32 v[90:91], v[94:95], 1.0 op_sel_hi:[1,0]
	v_mov_b32_e32 v98, v97
	v_mov_b32_e32 v104, v96
	v_pk_add_f32 v[100:101], v[100:101], 1.0 op_sel_hi:[1,0]
	v_pk_fma_f32 v[30:31], v[90:91], v[30:31], v[98:99]
	v_pk_fma_f32 v[88:89], v[100:101], v[88:89], v[104:105]
	v_and_b32_sdwa v61, v31, v86 dst_sel:DWORD dst_unused:UNUSED_PAD src0_sel:WORD_1 src1_sel:DWORD
	v_and_b32_sdwa v65, v30, v86 dst_sel:DWORD dst_unused:UNUSED_PAD src0_sel:WORD_1 src1_sel:DWORD
	v_and_b32_sdwa v49, v89, v86 dst_sel:DWORD dst_unused:UNUSED_PAD src0_sel:WORD_1 src1_sel:DWORD
	v_and_b32_sdwa v57, v88, v86 dst_sel:DWORD dst_unused:UNUSED_PAD src0_sel:WORD_1 src1_sel:DWORD
	v_add3_u32 v31, v31, v61, s21
	v_add3_u32 v30, v30, v65, s21
	v_add3_u32 v57, v88, v57, s21
	v_add3_u32 v49, v89, v49, s21
	v_and_b32_e32 v31, 0xffff0000, v31
	v_and_b32_e32 v30, 0xffff0000, v30
	v_or_b32_sdwa v31, v31, v49 dst_sel:DWORD dst_unused:UNUSED_PAD src0_sel:DWORD src1_sel:WORD_1
	v_or_b32_sdwa v30, v30, v57 dst_sel:DWORD dst_unused:UNUSED_PAD src0_sel:DWORD src1_sel:WORD_1
	v_mov_b32_e32 v250, v28
	v_mov_b32_e32 v251, v29
	v_mov_b32_e32 v252, v30
	v_mov_b32_e32 v253, v31
	v_lshl_add_u64 v[88:89], v[66:67], 0, v[54:55]
	global_load_dwordx4 v[28:31], v[40:41], off
	v_lshl_add_u64 v[92:93], v[68:69], 0, v[54:55]
	global_load_dwordx4 v[88:91], v[88:89], off
	v_mov_b32_e32 v97, v26
	global_load_dwordx4 v[92:95], v[92:93], off
	global_store_dwordx2 v[250:251], v[252:253], off
	v_mov_b32_e32 v26, v25
	v_mov_b32_e32 v96, v24
	v_pk_mul_f32 v[26:27], v[26:27], v[102:103] op_sel_hi:[1,0]
	v_or_b32_e32 v24, v53, v80
	v_pk_mul_f32 v[96:97], v[96:97], v[102:103] op_sel_hi:[1,0]
	v_ashrrev_i32_e32 v25, 31, v24
	v_lshlrev_b64 v[24:25], 14, v[24:25]
	v_lshl_add_u64 v[24:25], s[62:63], 0, v[24:25]
	v_lshl_add_u64 v[24:25], v[24:25], 0, v[34:35]
	v_lshl_add_u64 v[24:25], v[24:25], 0, v[70:71]
	s_waitcnt vmcnt(3)
	v_mov_b32_e32 v99, v30
	v_mov_b32_e32 v30, v29
	s_waitcnt vmcnt(2)
	v_mov_b32_e32 v101, v90
	v_mov_b32_e32 v90, v89
	v_mov_b32_e32 v98, v28
	v_mov_b32_e32 v100, v88
	s_waitcnt vmcnt(1)
; __device__ __forceinline__ u16 f2bf(float x) { unsigned u = __float_as_uint(x); u += 0x7fffu + ((u >> 16) & 1u); return (u16)(u >> 16); }
; __device__ __forceinline__ size_t a_off(int row, int col, int nks) { return ((size_t)((row >> 8) * nks + (col >> 5)) << 13) + ((row & 255) << 5) + swzc(row, col & 31); }
; template <int MODE>
; __device__ __forceinline__ void norm_phase(const Params& p, const float* src, const float* w, const float* modl, int sh_off, int sc_off,
;                            char* smem, int bid, int nblk) {
;     ...
;     for (int i = 0; i < 4; ++i) {
;       const int c0 = i * 256 + lane * 4;
;       f32x4 ww = *(const f32x4*)(w + c0);
;       f32x4 y;
;       if (MODE == 2) {
; #pragma unroll
;         for (int e = 0; e < 4; ++e) y[e] = v[i][e] * rstd * ww[e];
;         *(f32x4*)(p.out + (size_t)row * 1024 + c0) = y;
;       } else {
;         f32x4 sc = *(const f32x4*)(modl + (size_t)b * 6144 + sc_off + c0);
;         f32x4 sh = *(const f32x4*)(modl + (size_t)b * 6144 + sh_off + c0);
; #pragma unroll
;         for (int e = 0; e < 4; ++e) y[e] = v[i][e] * rstd * ww[e] * (1.f + sc[e]) + sh[e];
;         uint2 pk; pk.x = (unsigned)f2bf(y[0]) | ((unsigned)f2bf(y[1]) << 16); pk.y = (unsigned)f2bf(y[2]) | ((unsigned)f2bf(y[3]) << 16);
;         *(uint2*)(hn + a_off(row, c0, 32)) = pk;
	v_mov_b32_e32 v105, v94
	v_mov_b32_e32 v94, v93
	v_pk_mul_f32 v[26:27], v[30:31], v[26:27]
	v_pk_add_f32 v[30:31], v[90:91], 1.0 op_sel_hi:[1,0]
	v_mov_b32_e32 v104, v92
	v_pk_mul_f32 v[28:29], v[98:99], v[96:97]
	v_pk_add_f32 v[88:89], v[100:101], 1.0 op_sel_hi:[1,0]
	v_pk_fma_f32 v[26:27], v[30:31], v[26:27], v[94:95]
	v_pk_fma_f32 v[28:29], v[88:89], v[28:29], v[104:105]
	v_and_b32_sdwa v49, v27, v86 dst_sel:DWORD dst_unused:UNUSED_PAD src0_sel:WORD_1 src1_sel:DWORD
	v_and_b32_sdwa v57, v26, v86 dst_sel:DWORD dst_unused:UNUSED_PAD src0_sel:WORD_1 src1_sel:DWORD
	v_and_b32_sdwa v30, v29, v86 dst_sel:DWORD dst_unused:UNUSED_PAD src0_sel:WORD_1 src1_sel:DWORD
	v_and_b32_sdwa v31, v28, v86 dst_sel:DWORD dst_unused:UNUSED_PAD src0_sel:WORD_1 src1_sel:DWORD
	v_add3_u32 v27, v27, v49, s21
	v_add3_u32 v26, v26, v57, s21
	v_add3_u32 v28, v28, v31, s21
	v_add3_u32 v29, v29, v30, s21
	v_and_b32_e32 v27, 0xffff0000, v27
	v_and_b32_e32 v26, 0xffff0000, v26
	v_or_b32_sdwa v27, v27, v29 dst_sel:DWORD dst_unused:UNUSED_PAD src0_sel:DWORD src1_sel:WORD_1
	v_or_b32_sdwa v26, v26, v28 dst_sel:DWORD dst_unused:UNUSED_PAD src0_sel:DWORD src1_sel:WORD_1
	v_mov_b32_e32 v250, v24
	v_mov_b32_e32 v251, v25
	v_mov_b32_e32 v252, v26
	v_mov_b32_e32 v253, v27
	v_lshl_add_u64 v[28:29], v[66:67], 0, v[58:59]
	global_load_dwordx4 v[24:27], v[42:43], off
	v_lshl_add_u64 v[88:89], v[68:69], 0, v[58:59]
	global_load_dwordx4 v[28:31], v[28:29], off
	v_mov_b32_e32 v93, v22
	global_load_dwordx4 v[88:91], v[88:89], off
	global_store_dwordx2 v[250:251], v[252:253], off
	v_mov_b32_e32 v22, v21
	v_mov_b32_e32 v92, v20
	v_pk_mul_f32 v[22:23], v[22:23], v[102:103] op_sel_hi:[1,0]
	v_or_b32_e32 v20, v53, v81
	v_pk_mul_f32 v[92:93], v[92:93], v[102:103] op_sel_hi:[1,0]
	v_ashrrev_i32_e32 v21, 31, v20
	v_lshlrev_b64 v[20:21], 14, v[20:21]
	v_lshl_add_u64 v[20:21], s[62:63], 0, v[20:21]
	v_lshl_add_u64 v[20:21], v[20:21], 0, v[34:35]
	v_lshl_add_u64 v[20:21], v[20:21], 0, v[70:71]
	s_waitcnt vmcnt(3)
	v_mov_b32_e32 v95, v26
	v_mov_b32_e32 v26, v25
	s_waitcnt vmcnt(2)
	v_mov_b32_e32 v97, v30
	v_mov_b32_e32 v30, v29
	v_mov_b32_e32 v94, v24
	v_mov_b32_e32 v96, v28
	s_waitcnt vmcnt(1)
	v_mov_b32_e32 v99, v90
	v_mov_b32_e32 v90, v89
	v_pk_mul_f32 v[22:23], v[22:23], v[26:27]
	v_pk_add_f32 v[26:27], v[30:31], 1.0 op_sel_hi:[1,0]
	v_mov_b32_e32 v98, v88
	v_pk_mul_f32 v[24:25], v[92:93], v[94:95]
	v_pk_add_f32 v[28:29], v[96:97], 1.0 op_sel_hi:[1,0]
	v_pk_fma_f32 v[22:23], v[22:23], v[26:27], v[90:91]
	v_pk_fma_f32 v[24:25], v[24:25], v[28:29], v[98:99]
	v_and_b32_sdwa v28, v23, v86 dst_sel:DWORD dst_unused:UNUSED_PAD src0_sel:WORD_1 src1_sel:DWORD
	v_and_b32_sdwa v29, v22, v86 dst_sel:DWORD dst_unused:UNUSED_PAD src0_sel:WORD_1 src1_sel:DWORD
	v_and_b32_sdwa v26, v25, v86 dst_sel:DWORD dst_unused:UNUSED_PAD src0_sel:WORD_1 src1_sel:DWORD
	v_and_b32_sdwa v27, v24, v86 dst_sel:DWORD dst_unused:UNUSED_PAD src0_sel:WORD_1 src1_sel:DWORD
	v_add3_u32 v23, v23, v28, s21
	v_add3_u32 v22, v22, v29, s21
	v_add3_u32 v24, v24, v27, s21
	v_add3_u32 v25, v25, v26, s21
	v_and_b32_e32 v23, 0xffff0000, v23
	v_and_b32_e32 v22, 0xffff0000, v22
	v_or_b32_sdwa v23, v23, v25 dst_sel:DWORD dst_unused:UNUSED_PAD src0_sel:DWORD src1_sel:WORD_1
	v_or_b32_sdwa v22, v22, v24 dst_sel:DWORD dst_unused:UNUSED_PAD src0_sel:DWORD src1_sel:WORD_1
	v_mov_b32_e32 v250, v20
	v_mov_b32_e32 v251, v21
	v_mov_b32_e32 v252, v22
	v_mov_b32_e32 v253, v23
	v_lshl_add_u64 v[24:25], v[66:67], 0, v[62:63]
	global_load_dwordx4 v[20:23], v[44:45], off
	v_lshl_add_u64 v[28:29], v[68:69], 0, v[62:63]
	global_load_dwordx4 v[24:27], v[24:25], off
	v_mov_b32_e32 v66, v16
	global_load_dwordx4 v[28:31], v[28:29], off
	global_store_dwordx2 v[250:251], v[252:253], off
	v_or_b32_e32 v16, v53, v82
	v_mov_b32_e32 v67, v18
	v_mov_b32_e32 v18, v17
	v_ashrrev_i32_e32 v17, 31, v16
	v_lshlrev_b64 v[16:17], 14, v[16:17]
	v_lshl_add_u64 v[16:17], s[62:63], 0, v[16:17]
	v_lshl_add_u64 v[16:17], v[16:17], 0, v[34:35]
	v_lshl_add_u64 v[16:17], v[16:17], 0, v[70:71]
	v_pk_mul_f32 v[18:19], v[18:19], v[102:103] op_sel_hi:[1,0]
	v_pk_mul_f32 v[66:67], v[66:67], v[102:103] op_sel_hi:[1,0]
	s_waitcnt vmcnt(3)
	v_mov_b32_e32 v69, v22
	v_mov_b32_e32 v22, v21
	s_waitcnt vmcnt(2)
	v_mov_b32_e32 v71, v26
	v_mov_b32_e32 v26, v25
	v_mov_b32_e32 v68, v20
	v_mov_b32_e32 v70, v24
	s_waitcnt vmcnt(1)
	v_mov_b32_e32 v89, v30
	v_mov_b32_e32 v30, v29
	v_pk_mul_f32 v[18:19], v[18:19], v[22:23]
	v_pk_add_f32 v[22:23], v[26:27], 1.0 op_sel_hi:[1,0]
	v_mov_b32_e32 v88, v28
	v_pk_mul_f32 v[20:21], v[66:67], v[68:69]
	v_pk_add_f32 v[24:25], v[70:71], 1.0 op_sel_hi:[1,0]
	v_pk_fma_f32 v[18:19], v[18:19], v[22:23], v[30:31]
	v_pk_fma_f32 v[20:21], v[20:21], v[24:25], v[88:89]
	v_and_b32_sdwa v24, v19, v86 dst_sel:DWORD dst_unused:UNUSED_PAD src0_sel:WORD_1 src1_sel:DWORD
	v_and_b32_sdwa v25, v18, v86 dst_sel:DWORD dst_unused:UNUSED_PAD src0_sel:WORD_1 src1_sel:DWORD
	v_and_b32_sdwa v22, v21, v86 dst_sel:DWORD dst_unused:UNUSED_PAD src0_sel:WORD_1 src1_sel:DWORD
	v_and_b32_sdwa v23, v20, v86 dst_sel:DWORD dst_unused:UNUSED_PAD src0_sel:WORD_1 src1_sel:DWORD
	v_add3_u32 v19, v19, v24, s21
	v_add3_u32 v18, v18, v25, s21
	v_add3_u32 v20, v20, v23, s21
	v_add3_u32 v21, v21, v22, s21
	v_and_b32_e32 v19, 0xffff0000, v19
	v_and_b32_e32 v18, 0xffff0000, v18
	v_or_b32_sdwa v19, v19, v21 dst_sel:DWORD dst_unused:UNUSED_PAD src0_sel:DWORD src1_sel:WORD_1
	v_or_b32_sdwa v18, v18, v20 dst_sel:DWORD dst_unused:UNUSED_PAD src0_sel:DWORD src1_sel:WORD_1
	global_store_dwordx2 v[16:17], v[18:19], off
	s_and_saveexec_b64 s[0:1], vcc
	s_cbranch_execz .LBB0_1936
; __device__ __forceinline__ u16 f2bf(float x) { unsigned u = __float_as_uint(x); u += 0x7fffu + ((u >> 16) & 1u); return (u16)(u >> 16); }
; __device__ __forceinline__ size_t a_off(int row, int col, int nks) { return ((size_t)((row >> 8) * nks + (col >> 5)) << 13) + ((row & 255) << 5) + swzc(row, col & 31); }
; template <int MODE>
; __device__ __forceinline__ void norm_phase(const Params& p, const float* src, const float* w, const float* modl, int sh_off, int sc_off,
;                            char* smem, int bid, int nblk) {
;     ...
;     float ss = 0.f;
; #pragma unroll
;     for (int i = 0; i < 4; ++i) ss += v[i][0] * v[i][0] + v[i][1] * v[i][1] + v[i][2] * v[i][2] + v[i][3] * v[i][3];
; #pragma unroll
;     for (int o = 32; o >= 1; o >>= 1) ss += __shfl_xor(ss, o);
;     const float rstd = rsqrtf(ss * (1.f / 1024.f) + 1e-6f);
;     const int b = row >> 13;
;     float dots[8];
;     if (MODE == 1) { for (int j = 0; j < 8; ++j) dots[j] = 0.f; }
; #pragma unroll
;     for (int i = 0; i < 4; ++i) {
;       const int c0 = i * 256 + lane * 4;
;       f32x4 ww = *(const f32x4*)(w + c0);
;       f32x4 y;
;       if (MODE == 2) {
; #pragma unroll
;         for (int e = 0; e < 4; ++e) y[e] = v[i][e] * rstd * ww[e];
;         *(f32x4*)(p.out + (size_t)row * 1024 + c0) = y;
;       } else {
;         f32x4 sc = *(const f32x4*)(modl + (size_t)b * 6144 + sc_off + c0);
;         f32x4 sh = *(const f32x4*)(modl + (size_t)b * 6144 + sh_off + c0);
; #pragma unroll
;         for (int e = 0; e < 4; ++e) y[e] = v[i][e] * rstd * ww[e] * (1.f + sc[e]) + sh[e];
;         uint2 pk; pk.x = (unsigned)f2bf(y[0]) | ((unsigned)f2bf(y[1]) << 16); pk.y = (unsigned)f2bf(y[2]) | ((unsigned)f2bf(y[3]) << 16);
;         *(uint2*)(hn + a_off(row, c0, 32)) = pk;
	v_ashrrev_i32_e32 v16, 13, v64
	v_mul_i32_i24_e32 v16, 0x1800, v16
	v_ashrrev_i32_e32 v17, 31, v16
	v_lshl_add_u64 v[18:19], v[16:17], 2, s[6:7]
	v_lshl_add_u64 v[16:17], v[18:19], 0, s[14:15]
	v_mov_b32_e32 v49, v35
	global_load_dwordx4 v[22:25], v[38:39], off
	v_lshl_add_u64 v[26:27], v[16:17], 0, v[48:49]
	v_lshl_add_u64 v[18:19], v[18:19], 0, s[16:17]
	global_load_dwordx4 v[26:29], v[26:27], off
	v_lshl_add_u64 v[30:31], v[18:19], 0, v[48:49]
	global_load_dwordx4 v[66:69], v[30:31], off
	v_pk_mul_f32 v[70:71], v[8:9], v[8:9]
	v_pk_mul_f32 v[88:89], v[12:13], v[12:13]
	v_pk_mul_f32 v[20:21], v[14:15], v[14:15]
	v_pk_mul_f32 v[30:31], v[10:11], v[10:11]
	v_mov_b32_e32 v90, v88
	v_mov_b32_e32 v91, v70
	v_mov_b32_e32 v70, v89
	v_pk_add_f32 v[70:71], v[90:91], v[70:71]
	v_mov_b32_e32 v88, v20
	v_mov_b32_e32 v89, v30
	v_pk_add_f32 v[70:71], v[88:89], v[70:71]
	v_mov_b32_e32 v30, v21
	v_pk_add_f32 v[20:21], v[30:31], v[70:71]
	v_mov_b32_e32 v70, v5
	v_mov_b32_e32 v71, v1
	v_mov_b32_e32 v30, v4
	v_mov_b32_e32 v31, v0
	v_pk_mul_f32 v[70:71], v[70:71], v[70:71]
	v_add_f32_e32 v20, v20, v21
	v_pk_fma_f32 v[30:31], v[30:31], v[30:31], v[70:71]
	v_mov_b32_e32 v70, v6
	v_mov_b32_e32 v71, v2
	v_pk_fma_f32 v[30:31], v[70:71], v[70:71], v[30:31]
	v_mov_b32_e32 v70, v7
	v_mov_b32_e32 v71, v3
	v_pk_fma_f32 v[30:31], v[70:71], v[70:71], v[30:31]
	v_ashrrev_i32_e32 v34, 3, v64
	v_add_f32_e32 v20, v30, v20
	v_add_f32_e32 v20, v20, v31
	ds_bpermute_b32 v21, v72, v20
	v_mov_b32_e32 v30, v12
	v_add_u32_e32 v49, s9, v84
	v_add_u32_e32 v53, s8, v83
	v_and_b32_e32 v87, 0xffffffe0, v34
	s_waitcnt lgkmcnt(0)
	v_add_f32_e32 v20, v20, v21
	ds_bpermute_b32 v21, v73, v20
	v_and_b32_e32 v34, 24, v53
	v_or_b32_e32 v64, v87, v78
	v_ashrrev_i32_e32 v65, 31, v64
	v_lshlrev_b64 v[64:65], 14, v[64:65]
	s_waitcnt lgkmcnt(0)
	v_add_f32_e32 v20, v20, v21
	ds_bpermute_b32 v31, v74, v20
	v_lshl_add_u64 v[64:65], s[62:63], 0, v[64:65]
	v_mov_b32_e32 v21, v35
	v_mov_b32_e32 v53, v35
	v_mov_b32_e32 v57, v35
	s_waitcnt lgkmcnt(0)
	v_add_f32_e32 v12, v20, v31
	ds_bpermute_b32 v20, v75, v12
	v_mov_b32_e32 v31, v14
	v_and_b32_e32 v14, 0x1fe0, v49
	v_sub_u32_e32 v49, 0, v34
	v_lshlrev_b32_e32 v34, 1, v14
	s_waitcnt lgkmcnt(0)
	v_add_f32_e32 v12, v12, v20
	ds_bpermute_b32 v20, v76, v12
	v_lshl_add_u64 v[64:65], v[64:65], 0, v[34:35]
	v_mov_b32_e32 v61, v35
	s_waitcnt lgkmcnt(0)
	v_add_f32_e32 v12, v12, v20
	ds_bpermute_b32 v14, v77, v12
	v_xor_b32_e32 v20, v32, v49
	v_and_or_b32 v20, v20, 24, v79
	v_lshlrev_b32_e32 v20, 1, v20
	v_lshl_add_u64 v[64:65], v[64:65], 0, v[20:21]
	s_waitcnt lgkmcnt(0)
	v_add_f32_e32 v12, v12, v14
	v_fmamk_f32 v12, v12, 0x3a800000, v85
	v_mul_f32_e32 v14, 0x4b800000, v12
	v_cmp_gt_f32_e32 vcc, s20, v12
	s_waitcnt vmcnt(2)
	v_mov_b32_e32 v70, v22
	v_cndmask_b32_e32 v12, v12, v14, vcc
	v_rsq_f32_e32 v12, v12
	v_mov_b32_e32 v71, v24
	v_mov_b32_e32 v24, v23
	s_waitcnt vmcnt(0)
	v_mov_b32_e32 v89, v68
	v_mul_f32_e32 v14, 0x45800000, v12
	v_cndmask_b32_e32 v12, v12, v14, vcc
	v_pk_mul_f32 v[30:31], v[30:31], v[12:13] op_sel_hi:[1,0]
	v_mov_b32_e32 v14, v13
	v_pk_mul_f32 v[30:31], v[70:71], v[30:31]
	v_mov_b32_e32 v71, v28
	v_pk_mul_f32 v[14:15], v[14:15], v[12:13] op_sel_hi:[1,0]
	v_mov_b32_e32 v28, v27
	v_mov_b32_e32 v70, v26
	v_pk_mul_f32 v[14:15], v[24:25], v[14:15]
	v_pk_add_f32 v[22:23], v[28:29], 1.0 op_sel_hi:[1,0]
	v_mov_b32_e32 v68, v67
	v_mov_b32_e32 v88, v66
	v_pk_add_f32 v[70:71], v[70:71], 1.0 op_sel_hi:[1,0]
	v_pk_fma_f32 v[14:15], v[22:23], v[14:15], v[68:69]
	v_pk_fma_f32 v[30:31], v[70:71], v[30:31], v[88:89]
	v_and_b32_sdwa v23, v15, v86 dst_sel:DWORD dst_unused:UNUSED_PAD src0_sel:WORD_1 src1_sel:DWORD
	v_and_b32_sdwa v24, v14, v86 dst_sel:DWORD dst_unused:UNUSED_PAD src0_sel:WORD_1 src1_sel:DWORD
	v_and_b32_sdwa v13, v31, v86 dst_sel:DWORD dst_unused:UNUSED_PAD src0_sel:WORD_1 src1_sel:DWORD
	v_and_b32_sdwa v22, v30, v86 dst_sel:DWORD dst_unused:UNUSED_PAD src0_sel:WORD_1 src1_sel:DWORD
	v_add3_u32 v15, v15, v23, s21
	v_add3_u32 v14, v14, v24, s21
	v_add3_u32 v22, v30, v22, s21
	v_add3_u32 v13, v31, v13, s21
	v_and_b32_e32 v15, 0xffff0000, v15
	v_and_b32_e32 v14, 0xffff0000, v14
	v_or_b32_sdwa v15, v15, v13 dst_sel:DWORD dst_unused:UNUSED_PAD src0_sel:DWORD src1_sel:WORD_1
	v_or_b32_sdwa v14, v14, v22 dst_sel:DWORD dst_unused:UNUSED_PAD src0_sel:DWORD src1_sel:WORD_1
	v_mov_b32_e32 v250, v64
	v_mov_b32_e32 v251, v65
	v_mov_b32_e32 v252, v14
	v_mov_b32_e32 v253, v15
	v_lshl_add_u64 v[14:15], v[16:17], 0, v[52:53]
	global_load_dwordx4 v[22:25], v[40:41], off
	global_load_dwordx4 v[26:29], v[14:15], off
	v_lshl_add_u64 v[14:15], v[18:19], 0, v[52:53]
	global_load_dwordx4 v[64:67], v[14:15], off
	global_store_dwordx2 v[250:251], v[252:253], off
	v_mov_b32_e32 v15, v10
	v_mov_b32_e32 v10, v9
	v_mov_b32_e32 v14, v8
	v_pk_mul_f32 v[10:11], v[10:11], v[12:13] op_sel_hi:[1,0]
	v_or_b32_e32 v8, v87, v80
	v_pk_mul_f32 v[14:15], v[14:15], v[12:13] op_sel_hi:[1,0]
	v_ashrrev_i32_e32 v9, 31, v8
	v_lshlrev_b64 v[8:9], 14, v[8:9]
	v_lshl_add_u64 v[8:9], s[62:63], 0, v[8:9]
	v_lshl_add_u64 v[8:9], v[8:9], 0, v[34:35]
	v_lshl_add_u64 v[8:9], v[8:9], 0, v[20:21]
	s_waitcnt vmcnt(3)
	v_mov_b32_e32 v31, v24
	s_waitcnt vmcnt(2)
	v_mov_b32_e32 v69, v28
	v_mov_b32_e32 v24, v23
	v_mov_b32_e32 v28, v27
	v_mov_b32_e32 v30, v22
	v_mov_b32_e32 v68, v26
	s_waitcnt vmcnt(1)
; __device__ __forceinline__ u16 f2bf(float x) { unsigned u = __float_as_uint(x); u += 0x7fffu + ((u >> 16) & 1u); return (u16)(u >> 16); }
; __device__ __forceinline__ size_t a_off(int row, int col, int nks) { return ((size_t)((row >> 8) * nks + (col >> 5)) << 13) + ((row & 255) << 5) + swzc(row, col & 31); }
; template <int MODE>
; __device__ __forceinline__ void norm_phase(const Params& p, const float* src, const float* w, const float* modl, int sh_off, int sc_off,
;                            char* smem, int bid, int nblk) {
;     ...
;     for (int i = 0; i < 4; ++i) {
;       const int c0 = i * 256 + lane * 4;
;       f32x4 ww = *(const f32x4*)(w + c0);
;       f32x4 y;
;       if (MODE == 2) {
; #pragma unroll
;         for (int e = 0; e < 4; ++e) y[e] = v[i][e] * rstd * ww[e];
;         *(f32x4*)(p.out + (size_t)row * 1024 + c0) = y;
;       } else {
;         f32x4 sc = *(const f32x4*)(modl + (size_t)b * 6144 + sc_off + c0);
;         f32x4 sh = *(const f32x4*)(modl + (size_t)b * 6144 + sh_off + c0);
; #pragma unroll
;         for (int e = 0; e < 4; ++e) y[e] = v[i][e] * rstd * ww[e] * (1.f + sc[e]) + sh[e];
;         uint2 pk; pk.x = (unsigned)f2bf(y[0]) | ((unsigned)f2bf(y[1]) << 16); pk.y = (unsigned)f2bf(y[2]) | ((unsigned)f2bf(y[3]) << 16);
;         *(uint2*)(hn + a_off(row, c0, 32)) = pk;
	v_mov_b32_e32 v71, v66
	v_mov_b32_e32 v66, v65
	v_pk_mul_f32 v[10:11], v[24:25], v[10:11]
	v_pk_add_f32 v[24:25], v[28:29], 1.0 op_sel_hi:[1,0]
	v_mov_b32_e32 v70, v64
	v_pk_mul_f32 v[14:15], v[30:31], v[14:15]
	v_pk_add_f32 v[22:23], v[68:69], 1.0 op_sel_hi:[1,0]
	v_pk_fma_f32 v[10:11], v[24:25], v[10:11], v[66:67]
	v_pk_fma_f32 v[14:15], v[22:23], v[14:15], v[70:71]
	v_and_b32_sdwa v23, v11, v86 dst_sel:DWORD dst_unused:UNUSED_PAD src0_sel:WORD_1 src1_sel:DWORD
	v_and_b32_sdwa v24, v10, v86 dst_sel:DWORD dst_unused:UNUSED_PAD src0_sel:WORD_1 src1_sel:DWORD
	v_and_b32_sdwa v13, v15, v86 dst_sel:DWORD dst_unused:UNUSED_PAD src0_sel:WORD_1 src1_sel:DWORD
	v_and_b32_sdwa v22, v14, v86 dst_sel:DWORD dst_unused:UNUSED_PAD src0_sel:WORD_1 src1_sel:DWORD
	v_add3_u32 v11, v11, v23, s21
	v_add3_u32 v10, v10, v24, s21
	v_add3_u32 v14, v14, v22, s21
	v_add3_u32 v13, v15, v13, s21
	v_and_b32_e32 v11, 0xffff0000, v11
	v_and_b32_e32 v10, 0xffff0000, v10
	v_or_b32_sdwa v11, v11, v13 dst_sel:DWORD dst_unused:UNUSED_PAD src0_sel:DWORD src1_sel:WORD_1
	v_or_b32_sdwa v10, v10, v14 dst_sel:DWORD dst_unused:UNUSED_PAD src0_sel:DWORD src1_sel:WORD_1
	v_mov_b32_e32 v250, v8
	v_mov_b32_e32 v251, v9
	v_mov_b32_e32 v252, v10
	v_mov_b32_e32 v253, v11
	v_lshl_add_u64 v[14:15], v[16:17], 0, v[56:57]
	global_load_dwordx4 v[8:11], v[42:43], off
	global_load_dwordx4 v[22:25], v[14:15], off
	v_lshl_add_u64 v[14:15], v[18:19], 0, v[56:57]
	global_load_dwordx4 v[26:29], v[14:15], off
	global_store_dwordx2 v[250:251], v[252:253], off
	v_mov_b32_e32 v15, v6
	v_mov_b32_e32 v6, v5
	v_mov_b32_e32 v14, v4
	v_pk_mul_f32 v[6:7], v[6:7], v[12:13] op_sel_hi:[1,0]
	v_or_b32_e32 v4, v87, v81
	v_pk_mul_f32 v[14:15], v[14:15], v[12:13] op_sel_hi:[1,0]
	v_ashrrev_i32_e32 v5, 31, v4
	v_lshlrev_b64 v[4:5], 14, v[4:5]
	v_lshl_add_u64 v[4:5], s[62:63], 0, v[4:5]
	v_lshl_add_u64 v[4:5], v[4:5], 0, v[34:35]
	v_lshl_add_u64 v[4:5], v[4:5], 0, v[20:21]
	s_waitcnt vmcnt(3)
	v_mov_b32_e32 v31, v10
	s_waitcnt vmcnt(2)
	v_mov_b32_e32 v65, v24
	v_mov_b32_e32 v10, v9
	v_mov_b32_e32 v24, v23
	v_mov_b32_e32 v30, v8
	v_mov_b32_e32 v64, v22
	s_waitcnt vmcnt(1)
	v_mov_b32_e32 v67, v28
	v_mov_b32_e32 v28, v27
	v_pk_mul_f32 v[6:7], v[6:7], v[10:11]
	v_pk_add_f32 v[10:11], v[24:25], 1.0 op_sel_hi:[1,0]
	v_mov_b32_e32 v66, v26
	v_pk_mul_f32 v[8:9], v[14:15], v[30:31]
	v_pk_add_f32 v[14:15], v[64:65], 1.0 op_sel_hi:[1,0]
	v_pk_fma_f32 v[6:7], v[6:7], v[10:11], v[28:29]
	v_pk_fma_f32 v[8:9], v[8:9], v[14:15], v[66:67]
	v_and_b32_sdwa v13, v7, v86 dst_sel:DWORD dst_unused:UNUSED_PAD src0_sel:WORD_1 src1_sel:DWORD
	v_and_b32_sdwa v14, v6, v86 dst_sel:DWORD dst_unused:UNUSED_PAD src0_sel:WORD_1 src1_sel:DWORD
	v_and_b32_sdwa v10, v9, v86 dst_sel:DWORD dst_unused:UNUSED_PAD src0_sel:WORD_1 src1_sel:DWORD
	v_and_b32_sdwa v11, v8, v86 dst_sel:DWORD dst_unused:UNUSED_PAD src0_sel:WORD_1 src1_sel:DWORD
	v_add3_u32 v7, v7, v13, s21
	v_add3_u32 v6, v6, v14, s21
	v_add3_u32 v8, v8, v11, s21
	v_add3_u32 v9, v9, v10, s21
	v_and_b32_e32 v7, 0xffff0000, v7
	v_and_b32_e32 v6, 0xffff0000, v6
	v_or_b32_sdwa v7, v7, v9 dst_sel:DWORD dst_unused:UNUSED_PAD src0_sel:DWORD src1_sel:WORD_1
	v_or_b32_sdwa v6, v6, v8 dst_sel:DWORD dst_unused:UNUSED_PAD src0_sel:DWORD src1_sel:WORD_1
	v_mov_b32_e32 v250, v4
	v_mov_b32_e32 v251, v5
	v_mov_b32_e32 v252, v6
	v_mov_b32_e32 v253, v7
	v_lshl_add_u64 v[8:9], v[16:17], 0, v[60:61]
	global_load_dwordx4 v[4:7], v[44:45], off
	v_lshl_add_u64 v[14:15], v[18:19], 0, v[60:61]
	global_load_dwordx4 v[8:11], v[8:9], off
	v_mov_b32_e32 v18, v0
	global_load_dwordx4 v[14:17], v[14:15], off
	global_store_dwordx2 v[250:251], v[252:253], off
	v_or_b32_e32 v0, v87, v82
	v_mov_b32_e32 v19, v2
	v_mov_b32_e32 v2, v1
	v_ashrrev_i32_e32 v1, 31, v0
	v_lshlrev_b64 v[0:1], 14, v[0:1]
	v_lshl_add_u64 v[0:1], s[62:63], 0, v[0:1]
	v_lshl_add_u64 v[0:1], v[0:1], 0, v[34:35]
	v_lshl_add_u64 v[0:1], v[0:1], 0, v[20:21]
	v_pk_mul_f32 v[18:19], v[18:19], v[12:13] op_sel_hi:[1,0]
	v_pk_mul_f32 v[2:3], v[2:3], v[12:13] op_sel_hi:[1,0]
	s_waitcnt vmcnt(3)
	v_mov_b32_e32 v13, v6
	v_mov_b32_e32 v6, v5
	s_waitcnt vmcnt(2)
	v_mov_b32_e32 v21, v10
	v_mov_b32_e32 v10, v9
	v_mov_b32_e32 v12, v4
	v_mov_b32_e32 v20, v8
	s_waitcnt vmcnt(1)
	v_mov_b32_e32 v23, v16
	v_mov_b32_e32 v16, v15
	v_pk_mul_f32 v[2:3], v[2:3], v[6:7]
	v_pk_add_f32 v[6:7], v[10:11], 1.0 op_sel_hi:[1,0]
	v_mov_b32_e32 v22, v14
	v_pk_mul_f32 v[4:5], v[18:19], v[12:13]
	v_pk_add_f32 v[8:9], v[20:21], 1.0 op_sel_hi:[1,0]
	v_pk_fma_f32 v[2:3], v[2:3], v[6:7], v[16:17]
	v_pk_fma_f32 v[4:5], v[4:5], v[8:9], v[22:23]
	v_and_b32_sdwa v8, v3, v86 dst_sel:DWORD dst_unused:UNUSED_PAD src0_sel:WORD_1 src1_sel:DWORD
	v_and_b32_sdwa v9, v2, v86 dst_sel:DWORD dst_unused:UNUSED_PAD src0_sel:WORD_1 src1_sel:DWORD
	v_and_b32_sdwa v6, v5, v86 dst_sel:DWORD dst_unused:UNUSED_PAD src0_sel:WORD_1 src1_sel:DWORD
	v_and_b32_sdwa v7, v4, v86 dst_sel:DWORD dst_unused:UNUSED_PAD src0_sel:WORD_1 src1_sel:DWORD
	v_add3_u32 v3, v3, v8, s21
	v_add3_u32 v2, v2, v9, s21
	v_add3_u32 v4, v4, v7, s21
	v_add3_u32 v5, v5, v6, s21
	v_and_b32_e32 v3, 0xffff0000, v3
	v_and_b32_e32 v2, 0xffff0000, v2
	v_or_b32_sdwa v3, v3, v5 dst_sel:DWORD dst_unused:UNUSED_PAD src0_sel:DWORD src1_sel:WORD_1
	v_or_b32_sdwa v2, v2, v4 dst_sel:DWORD dst_unused:UNUSED_PAD src0_sel:DWORD src1_sel:WORD_1
	global_store_dwordx2 v[0:1], v[2:3], off
	s_branch .LBB0_1936
